# kpair variant: A-fragment-major pair order (same srcB for 4 consecutive pairs) + dropwaits + rotary
# speedup vs baseline: 1.0856x; 1.0033x over previous
.LBB0_642:
	ds_read_b128 v[148:151], v139
	ds_read_b128 v[152:155], v139 offset:1024
	ds_read_b128 v[156:159], v139 offset:2048
	ds_read_b128 v[160:163], v139 offset:3072
	ds_read_b128 v[164:167], v140
	ds_read_b128 v[168:171], v140 offset:1024
	ds_read_b128 v[172:175], v140 offset:2048
	ds_read_b128 v[176:179], v140 offset:3072
	s_add_i32 s18, s71, 0xffe80080
	s_cmp_eq_u32 s58, s73
	s_cselect_b32 s74, s69, s18
	s_cselect_b32 s76, s70, s72
	s_or_b32 s75, s74, 0x80
	s_add_i32 s18, s71, 0xfff80000
	s_mov_b32 m0, s59
	ds_read_b128 v[180:183], v141
	ds_read_b128 v[184:187], v141 offset:1024
	ds_read_b128 v[188:191], v141 offset:2048
	ds_read_b128 v[192:195], v141 offset:3072
	ds_read_b128 v[196:199], v141 offset:4096
	ds_read_b128 v[200:203], v141 offset:5120
	ds_read_b128 v[204:207], v141 offset:6144
	ds_read_b128 v[208:211], v141 offset:7168
	buffer_load_dwordx4 v137, s[12:15], s18 offen lds
	s_mov_b32 m0, s60
	s_nop 0
	buffer_load_dwordx4 v137, s[12:15], s71 offen lds
	s_waitcnt vmcnt(8)
	s_waitcnt lgkmcnt(0)
	s_setprio 1
	v_mfma_f32_16x16x32_bf16 v[118:121], v[148:151], v[180:183], v[118:121]
	s_barrier
	v_mfma_f32_16x16x32_bf16 v[118:121], v[152:155], v[184:187], v[118:121]
	v_mfma_f32_16x16x32_bf16 v[114:117], v[156:159], v[180:183], v[114:117]
	v_mfma_f32_16x16x32_bf16 v[114:117], v[160:163], v[184:187], v[114:117]
	v_mfma_f32_16x16x32_bf16 v[126:129], v[164:167], v[180:183], v[126:129]
	v_mfma_f32_16x16x32_bf16 v[126:129], v[168:171], v[184:187], v[126:129]
	v_mfma_f32_16x16x32_bf16 v[122:125], v[172:175], v[180:183], v[122:125]
	v_mfma_f32_16x16x32_bf16 v[122:125], v[176:179], v[184:187], v[122:125]
	v_mfma_f32_16x16x32_bf16 v[110:113], v[148:151], v[188:191], v[110:113]
	v_mfma_f32_16x16x32_bf16 v[110:113], v[152:155], v[192:195], v[110:113]
	v_mfma_f32_16x16x32_bf16 v[102:105], v[156:159], v[188:191], v[102:105]
	v_mfma_f32_16x16x32_bf16 v[102:105], v[160:163], v[192:195], v[102:105]
	v_mfma_f32_16x16x32_bf16 v[106:109], v[164:167], v[188:191], v[106:109]
	v_mfma_f32_16x16x32_bf16 v[106:109], v[168:171], v[192:195], v[106:109]
	v_mfma_f32_16x16x32_bf16 v[98:101], v[172:175], v[188:191], v[98:101]
	v_mfma_f32_16x16x32_bf16 v[98:101], v[176:179], v[192:195], v[98:101]
	v_mfma_f32_16x16x32_bf16 v[94:97], v[148:151], v[196:199], v[94:97]
	v_mfma_f32_16x16x32_bf16 v[94:97], v[152:155], v[200:203], v[94:97]
	v_mfma_f32_16x16x32_bf16 v[86:89], v[156:159], v[196:199], v[86:89]
	v_mfma_f32_16x16x32_bf16 v[86:89], v[160:163], v[200:203], v[86:89]
	v_mfma_f32_16x16x32_bf16 v[90:93], v[164:167], v[196:199], v[90:93]
	v_mfma_f32_16x16x32_bf16 v[90:93], v[168:171], v[200:203], v[90:93]
	v_mfma_f32_16x16x32_bf16 v[82:85], v[172:175], v[196:199], v[82:85]
	v_mfma_f32_16x16x32_bf16 v[82:85], v[176:179], v[200:203], v[82:85]
	v_mfma_f32_16x16x32_bf16 v[78:81], v[148:151], v[204:207], v[78:81]
	v_mfma_f32_16x16x32_bf16 v[78:81], v[152:155], v[208:211], v[78:81]
	v_mfma_f32_16x16x32_bf16 v[66:69], v[156:159], v[204:207], v[66:69]
	v_mfma_f32_16x16x32_bf16 v[66:69], v[160:163], v[208:211], v[66:69]
	v_mfma_f32_16x16x32_bf16 v[74:77], v[164:167], v[204:207], v[74:77]
	v_mfma_f32_16x16x32_bf16 v[74:77], v[168:171], v[208:211], v[74:77]
	v_mfma_f32_16x16x32_bf16 v[70:73], v[172:175], v[204:207], v[70:73]
	v_mfma_f32_16x16x32_bf16 v[70:73], v[176:179], v[208:211], v[70:73]
	s_setprio 0
	s_barrier
	s_mov_b32 m0, s30
	s_mov_b32 s18, s14
	s_mov_b32 s19, s15
	ds_read_b128 v[180:183], v141 offset:16384
	ds_read_b128 v[184:187], v141 offset:17408
	ds_read_b128 v[188:191], v141 offset:18432
	ds_read_b128 v[192:195], v141 offset:19456
	ds_read_b128 v[196:199], v141 offset:20480
	ds_read_b128 v[200:203], v141 offset:21504
	ds_read_b128 v[204:207], v141 offset:22528
	ds_read_b128 v[208:211], v141 offset:23552
	buffer_load_dwordx4 v138, s[16:19], s76 offen lds
	s_add_i32 s77, s76, 0x80000
	s_mov_b32 m0, s31
	s_nop 0
	buffer_load_dwordx4 v138, s[16:19], s77 offen lds
	s_add_i32 s77, s76, 0x100000
	s_mov_b32 m0, s44
	s_nop 0
	buffer_load_dwordx4 v138, s[16:19], s77 offen lds
	s_add_i32 s77, s76, 0x180000
	s_mov_b32 m0, s45
	s_nop 0
	buffer_load_dwordx4 v138, s[16:19], s77 offen lds
	s_mov_b32 m0, s27
	s_add_i32 s77, s74, 0x80000
	buffer_load_dwordx4 v137, s[12:15], s74 offen lds
	s_mov_b32 m0, s46
	s_nop 0
	buffer_load_dwordx4 v137, s[12:15], s77 offen lds
	s_waitcnt vmcnt(8)
	s_waitcnt lgkmcnt(0)
	s_setprio 1
	v_mfma_f32_16x16x32_bf16 v[62:65], v[148:151], v[180:183], v[62:65]
	s_barrier
	v_mfma_f32_16x16x32_bf16 v[62:65], v[152:155], v[184:187], v[62:65]
	v_mfma_f32_16x16x32_bf16 v[54:57], v[156:159], v[180:183], v[54:57]
	v_mfma_f32_16x16x32_bf16 v[54:57], v[160:163], v[184:187], v[54:57]
	v_mfma_f32_16x16x32_bf16 v[58:61], v[164:167], v[180:183], v[58:61]
	v_mfma_f32_16x16x32_bf16 v[58:61], v[168:171], v[184:187], v[58:61]
	v_mfma_f32_16x16x32_bf16 v[50:53], v[172:175], v[180:183], v[50:53]
	v_mfma_f32_16x16x32_bf16 v[50:53], v[176:179], v[184:187], v[50:53]
	v_mfma_f32_16x16x32_bf16 v[46:49], v[148:151], v[188:191], v[46:49]
	v_mfma_f32_16x16x32_bf16 v[46:49], v[152:155], v[192:195], v[46:49]
	v_mfma_f32_16x16x32_bf16 v[38:41], v[156:159], v[188:191], v[38:41]
	v_mfma_f32_16x16x32_bf16 v[38:41], v[160:163], v[192:195], v[38:41]
	v_mfma_f32_16x16x32_bf16 v[42:45], v[164:167], v[188:191], v[42:45]
	v_mfma_f32_16x16x32_bf16 v[42:45], v[168:171], v[192:195], v[42:45]
	v_mfma_f32_16x16x32_bf16 v[34:37], v[172:175], v[188:191], v[34:37]
	v_mfma_f32_16x16x32_bf16 v[34:37], v[176:179], v[192:195], v[34:37]
	v_mfma_f32_16x16x32_bf16 v[30:33], v[148:151], v[196:199], v[30:33]
	v_mfma_f32_16x16x32_bf16 v[30:33], v[152:155], v[200:203], v[30:33]
	v_mfma_f32_16x16x32_bf16 v[22:25], v[156:159], v[196:199], v[22:25]
	v_mfma_f32_16x16x32_bf16 v[22:25], v[160:163], v[200:203], v[22:25]
	v_mfma_f32_16x16x32_bf16 v[26:29], v[164:167], v[196:199], v[26:29]
	v_mfma_f32_16x16x32_bf16 v[26:29], v[168:171], v[200:203], v[26:29]
	v_mfma_f32_16x16x32_bf16 v[18:21], v[172:175], v[196:199], v[18:21]
	v_mfma_f32_16x16x32_bf16 v[18:21], v[176:179], v[200:203], v[18:21]
	v_mfma_f32_16x16x32_bf16 v[14:17], v[148:151], v[204:207], v[14:17]
	v_mfma_f32_16x16x32_bf16 v[14:17], v[152:155], v[208:211], v[14:17]
	v_mfma_f32_16x16x32_bf16 v[6:9], v[156:159], v[204:207], v[6:9]
	v_mfma_f32_16x16x32_bf16 v[6:9], v[160:163], v[208:211], v[6:9]
	v_mfma_f32_16x16x32_bf16 v[10:13], v[164:167], v[204:207], v[10:13]
	v_mfma_f32_16x16x32_bf16 v[10:13], v[168:171], v[208:211], v[10:13]
	v_mfma_f32_16x16x32_bf16 v[2:5], v[172:175], v[204:207], v[2:5]
	v_mfma_f32_16x16x32_bf16 v[2:5], v[176:179], v[208:211], v[2:5]
	s_setprio 0
	s_barrier
	ds_read_b128 v[148:151], v142
	ds_read_b128 v[152:155], v142 offset:1024
	ds_read_b128 v[156:159], v142 offset:2048
	ds_read_b128 v[160:163], v142 offset:3072
	ds_read_b128 v[164:167], v143
	ds_read_b128 v[168:171], v143 offset:1024
	ds_read_b128 v[172:175], v143 offset:2048
	ds_read_b128 v[176:179], v143 offset:3072
	s_mov_b32 m0, s47
	s_add_i32 s77, s74, 0x100000
	ds_read_b128 v[180:183], v141 offset:32768
	ds_read_b128 v[184:187], v141 offset:33792
	ds_read_b128 v[188:191], v141 offset:34816
	ds_read_b128 v[192:195], v141 offset:35840
	ds_read_b128 v[196:199], v141 offset:36864
	ds_read_b128 v[200:203], v141 offset:37888
	ds_read_b128 v[204:207], v141 offset:38912
	ds_read_b128 v[208:211], v141 offset:39936
	buffer_load_dwordx4 v137, s[12:15], s77 offen lds
	s_add_i32 s77, s74, 0x180000
	s_mov_b32 m0, s48
	s_nop 0
	buffer_load_dwordx4 v137, s[12:15], s77 offen lds
	s_waitcnt vmcnt(8)
	s_waitcnt lgkmcnt(0)
	s_setprio 1
	v_mfma_f32_16x16x32_bf16 v[118:121], v[148:151], v[180:183], v[118:121]
	s_barrier
	v_mfma_f32_16x16x32_bf16 v[118:121], v[152:155], v[184:187], v[118:121]
	v_mfma_f32_16x16x32_bf16 v[114:117], v[156:159], v[180:183], v[114:117]
	v_mfma_f32_16x16x32_bf16 v[114:117], v[160:163], v[184:187], v[114:117]
	v_mfma_f32_16x16x32_bf16 v[126:129], v[164:167], v[180:183], v[126:129]
	v_mfma_f32_16x16x32_bf16 v[126:129], v[168:171], v[184:187], v[126:129]
	v_mfma_f32_16x16x32_bf16 v[122:125], v[172:175], v[180:183], v[122:125]
	v_mfma_f32_16x16x32_bf16 v[122:125], v[176:179], v[184:187], v[122:125]
	v_mfma_f32_16x16x32_bf16 v[110:113], v[148:151], v[188:191], v[110:113]
	v_mfma_f32_16x16x32_bf16 v[110:113], v[152:155], v[192:195], v[110:113]
	v_mfma_f32_16x16x32_bf16 v[102:105], v[156:159], v[188:191], v[102:105]
	v_mfma_f32_16x16x32_bf16 v[102:105], v[160:163], v[192:195], v[102:105]
	v_mfma_f32_16x16x32_bf16 v[106:109], v[164:167], v[188:191], v[106:109]
	v_mfma_f32_16x16x32_bf16 v[106:109], v[168:171], v[192:195], v[106:109]
	v_mfma_f32_16x16x32_bf16 v[98:101], v[172:175], v[188:191], v[98:101]
	v_mfma_f32_16x16x32_bf16 v[98:101], v[176:179], v[192:195], v[98:101]
	v_mfma_f32_16x16x32_bf16 v[94:97], v[148:151], v[196:199], v[94:97]
	v_mfma_f32_16x16x32_bf16 v[94:97], v[152:155], v[200:203], v[94:97]
	v_mfma_f32_16x16x32_bf16 v[86:89], v[156:159], v[196:199], v[86:89]
	v_mfma_f32_16x16x32_bf16 v[86:89], v[160:163], v[200:203], v[86:89]
	v_mfma_f32_16x16x32_bf16 v[90:93], v[164:167], v[196:199], v[90:93]
	v_mfma_f32_16x16x32_bf16 v[90:93], v[168:171], v[200:203], v[90:93]
	v_mfma_f32_16x16x32_bf16 v[82:85], v[172:175], v[196:199], v[82:85]
	v_mfma_f32_16x16x32_bf16 v[82:85], v[176:179], v[200:203], v[82:85]
	v_mfma_f32_16x16x32_bf16 v[78:81], v[148:151], v[204:207], v[78:81]
	v_mfma_f32_16x16x32_bf16 v[78:81], v[152:155], v[208:211], v[78:81]
	v_mfma_f32_16x16x32_bf16 v[66:69], v[156:159], v[204:207], v[66:69]
	v_mfma_f32_16x16x32_bf16 v[66:69], v[160:163], v[208:211], v[66:69]
	v_mfma_f32_16x16x32_bf16 v[74:77], v[164:167], v[204:207], v[74:77]
	v_mfma_f32_16x16x32_bf16 v[74:77], v[168:171], v[208:211], v[74:77]
	v_mfma_f32_16x16x32_bf16 v[70:73], v[172:175], v[204:207], v[70:73]
	v_mfma_f32_16x16x32_bf16 v[70:73], v[176:179], v[208:211], v[70:73]
	s_setprio 0
	s_barrier
	s_mov_b32 m0, s50
	s_or_b32 s77, s76, 0x80
	ds_read_b128 v[180:183], v141 offset:49152
	ds_read_b128 v[184:187], v141 offset:50176
	ds_read_b128 v[188:191], v141 offset:51200
	ds_read_b128 v[192:195], v141 offset:52224
	ds_read_b128 v[196:199], v141 offset:53248
	ds_read_b128 v[200:203], v141 offset:54272
	ds_read_b128 v[204:207], v141 offset:55296
	ds_read_b128 v[208:211], v141 offset:56320
	buffer_load_dwordx4 v138, s[16:19], s77 offen lds
	s_add_i32 s77, s76, 0x80080
	s_mov_b32 m0, s51
	s_add_i32 s74, s74, 0x80080
	buffer_load_dwordx4 v138, s[16:19], s77 offen lds
	s_add_i32 s77, s76, 0x100080
	s_mov_b32 m0, s54
	s_add_i32 s76, s76, 0x180080
	buffer_load_dwordx4 v138, s[16:19], s77 offen lds
	s_mov_b32 m0, s55
	s_nop 0
	buffer_load_dwordx4 v138, s[16:19], s76 offen lds
	s_mov_b32 m0, s52
	s_nop 0
	buffer_load_dwordx4 v137, s[12:15], s75 offen lds
	s_mov_b32 m0, s53
	s_nop 0
	buffer_load_dwordx4 v137, s[12:15], s74 offen lds
	s_waitcnt vmcnt(8)
	s_waitcnt lgkmcnt(0)
	s_setprio 1
	v_mfma_f32_16x16x32_bf16 v[62:65], v[148:151], v[180:183], v[62:65]
	s_barrier
	v_mfma_f32_16x16x32_bf16 v[62:65], v[152:155], v[184:187], v[62:65]
	v_mfma_f32_16x16x32_bf16 v[54:57], v[156:159], v[180:183], v[54:57]
	v_mfma_f32_16x16x32_bf16 v[54:57], v[160:163], v[184:187], v[54:57]
	v_mfma_f32_16x16x32_bf16 v[58:61], v[164:167], v[180:183], v[58:61]
	v_mfma_f32_16x16x32_bf16 v[58:61], v[168:171], v[184:187], v[58:61]
	v_mfma_f32_16x16x32_bf16 v[50:53], v[172:175], v[180:183], v[50:53]
	v_mfma_f32_16x16x32_bf16 v[50:53], v[176:179], v[184:187], v[50:53]
	v_mfma_f32_16x16x32_bf16 v[46:49], v[148:151], v[188:191], v[46:49]
	v_mfma_f32_16x16x32_bf16 v[46:49], v[152:155], v[192:195], v[46:49]
	v_mfma_f32_16x16x32_bf16 v[38:41], v[156:159], v[188:191], v[38:41]
	v_mfma_f32_16x16x32_bf16 v[38:41], v[160:163], v[192:195], v[38:41]
	v_mfma_f32_16x16x32_bf16 v[42:45], v[164:167], v[188:191], v[42:45]
	v_mfma_f32_16x16x32_bf16 v[42:45], v[168:171], v[192:195], v[42:45]
	v_mfma_f32_16x16x32_bf16 v[34:37], v[172:175], v[188:191], v[34:37]
	v_mfma_f32_16x16x32_bf16 v[34:37], v[176:179], v[192:195], v[34:37]
	v_mfma_f32_16x16x32_bf16 v[30:33], v[148:151], v[196:199], v[30:33]
	v_mfma_f32_16x16x32_bf16 v[30:33], v[152:155], v[200:203], v[30:33]
	v_mfma_f32_16x16x32_bf16 v[22:25], v[156:159], v[196:199], v[22:25]
	v_mfma_f32_16x16x32_bf16 v[22:25], v[160:163], v[200:203], v[22:25]
	v_mfma_f32_16x16x32_bf16 v[26:29], v[164:167], v[196:199], v[26:29]
	v_mfma_f32_16x16x32_bf16 v[26:29], v[168:171], v[200:203], v[26:29]
	v_mfma_f32_16x16x32_bf16 v[18:21], v[172:175], v[196:199], v[18:21]
	v_mfma_f32_16x16x32_bf16 v[18:21], v[176:179], v[200:203], v[18:21]
	v_mfma_f32_16x16x32_bf16 v[14:17], v[148:151], v[204:207], v[14:17]
	v_mfma_f32_16x16x32_bf16 v[14:17], v[152:155], v[208:211], v[14:17]
	v_mfma_f32_16x16x32_bf16 v[6:9], v[156:159], v[204:207], v[6:9]
	v_mfma_f32_16x16x32_bf16 v[6:9], v[160:163], v[208:211], v[6:9]
	v_mfma_f32_16x16x32_bf16 v[10:13], v[164:167], v[204:207], v[10:13]
	v_mfma_f32_16x16x32_bf16 v[10:13], v[168:171], v[208:211], v[10:13]
	v_mfma_f32_16x16x32_bf16 v[2:5], v[172:175], v[204:207], v[2:5]
	v_mfma_f32_16x16x32_bf16 v[2:5], v[176:179], v[208:211], v[2:5]
	s_setprio 0
	s_barrier
	s_add_i32 s73, s73, 2
	s_addk_i32 s71, 0x100
	s_addk_i32 s72, 0x100
	s_cmp_ge_i32 s73, s3
	s_cbranch_scc0 .LBB0_642
	s_and_b64 vcc, exec, s[42:43]
	s_cbranch_vccz .LBB0_645

.LBB0_799:
	ds_read_b128 v[134:137], v210
	ds_read_b128 v[138:141], v210 offset:1024
	ds_read_b128 v[142:145], v210 offset:2048
	ds_read_b128 v[148:151], v210 offset:3072
	ds_read_b128 v[152:155], v211
	ds_read_b128 v[156:159], v211 offset:1024
	ds_read_b128 v[160:163], v211 offset:2048
	ds_read_b128 v[164:167], v211 offset:3072
	s_add_i32 s18, s77, 0xffbf8080
	s_cmp_eq_u32 s62, s79
	s_cselect_b32 s80, s6, s18
	s_cselect_b32 s82, s7, s78
	s_or_b32 s81, s80, 0x80
	s_add_i32 s18, s77, 0xffea8000
	s_mov_b32 m0, s63
	ds_read_b128 v[168:171], v212
	ds_read_b128 v[172:175], v212 offset:1024
	ds_read_b128 v[176:179], v212 offset:2048
	ds_read_b128 v[180:183], v212 offset:3072
	ds_read_b128 v[184:187], v212 offset:4096
	ds_read_b128 v[188:191], v212 offset:5120
	ds_read_b128 v[192:195], v212 offset:6144
	ds_read_b128 v[196:199], v212 offset:7168
	buffer_load_dwordx4 v208, s[12:15], s18 offen lds
	s_mov_b32 m0, s66
	s_nop 0
	buffer_load_dwordx4 v208, s[12:15], s77 offen lds
	s_waitcnt vmcnt(8)
	s_waitcnt lgkmcnt(0)
	s_setprio 1
	v_mfma_f32_16x16x32_bf16 v[126:129], v[134:137], v[168:171], v[126:129]
	s_barrier
	v_mfma_f32_16x16x32_bf16 v[126:129], v[138:141], v[172:175], v[126:129]
	v_mfma_f32_16x16x32_bf16 v[122:125], v[142:145], v[168:171], v[122:125]
	v_mfma_f32_16x16x32_bf16 v[122:125], v[148:151], v[172:175], v[122:125]
	v_mfma_f32_16x16x32_bf16 v[110:113], v[152:155], v[168:171], v[110:113]
	v_mfma_f32_16x16x32_bf16 v[110:113], v[156:159], v[172:175], v[110:113]
	v_mfma_f32_16x16x32_bf16 v[102:105], v[160:163], v[168:171], v[102:105]
	v_mfma_f32_16x16x32_bf16 v[102:105], v[164:167], v[172:175], v[102:105]
	v_mfma_f32_16x16x32_bf16 v[118:121], v[134:137], v[176:179], v[118:121]
	v_mfma_f32_16x16x32_bf16 v[118:121], v[138:141], v[180:183], v[118:121]
	v_mfma_f32_16x16x32_bf16 v[114:117], v[142:145], v[176:179], v[114:117]
	v_mfma_f32_16x16x32_bf16 v[114:117], v[148:151], v[180:183], v[114:117]
	v_mfma_f32_16x16x32_bf16 v[94:97], v[152:155], v[176:179], v[94:97]
	v_mfma_f32_16x16x32_bf16 v[94:97], v[156:159], v[180:183], v[94:97]
	v_mfma_f32_16x16x32_bf16 v[86:89], v[160:163], v[176:179], v[86:89]
	v_mfma_f32_16x16x32_bf16 v[86:89], v[164:167], v[180:183], v[86:89]
	v_mfma_f32_16x16x32_bf16 v[106:109], v[134:137], v[184:187], v[106:109]
	v_mfma_f32_16x16x32_bf16 v[106:109], v[138:141], v[188:191], v[106:109]
	v_mfma_f32_16x16x32_bf16 v[98:101], v[142:145], v[184:187], v[98:101]
	v_mfma_f32_16x16x32_bf16 v[98:101], v[148:151], v[188:191], v[98:101]
	v_mfma_f32_16x16x32_bf16 v[78:81], v[152:155], v[184:187], v[78:81]
	v_mfma_f32_16x16x32_bf16 v[78:81], v[156:159], v[188:191], v[78:81]
	v_mfma_f32_16x16x32_bf16 v[74:77], v[160:163], v[184:187], v[74:77]
	v_mfma_f32_16x16x32_bf16 v[74:77], v[164:167], v[188:191], v[74:77]
	v_mfma_f32_16x16x32_bf16 v[90:93], v[134:137], v[192:195], v[90:93]
	v_mfma_f32_16x16x32_bf16 v[90:93], v[138:141], v[196:199], v[90:93]
	v_mfma_f32_16x16x32_bf16 v[82:85], v[142:145], v[192:195], v[82:85]
	v_mfma_f32_16x16x32_bf16 v[82:85], v[148:151], v[196:199], v[82:85]
	v_mfma_f32_16x16x32_bf16 v[70:73], v[152:155], v[192:195], v[70:73]
	v_mfma_f32_16x16x32_bf16 v[70:73], v[156:159], v[196:199], v[70:73]
	v_mfma_f32_16x16x32_bf16 v[66:69], v[160:163], v[192:195], v[66:69]
	v_mfma_f32_16x16x32_bf16 v[66:69], v[164:167], v[196:199], v[66:69]
	s_setprio 0
	s_barrier
	s_mov_b32 m0, s25
	s_mov_b32 s18, s14
	s_mov_b32 s19, s15
	ds_read_b128 v[168:171], v212 offset:16384
	ds_read_b128 v[172:175], v212 offset:17408
	ds_read_b128 v[176:179], v212 offset:18432
	ds_read_b128 v[180:183], v212 offset:19456
	ds_read_b128 v[184:187], v212 offset:20480
	ds_read_b128 v[188:191], v212 offset:21504
	ds_read_b128 v[192:195], v212 offset:22528
	ds_read_b128 v[196:199], v212 offset:23552
	buffer_load_dwordx4 v209, s[16:19], s82 offen lds
	s_add_i32 s83, s82, 0x158000
	s_mov_b32 m0, s27
	s_nop 0
	buffer_load_dwordx4 v209, s[16:19], s83 offen lds
	s_add_i32 s83, s82, 0x2b0000
	s_mov_b32 m0, s30
	s_nop 0
	buffer_load_dwordx4 v209, s[16:19], s83 offen lds
	s_add_i32 s83, s82, 0x408000
	s_mov_b32 m0, s31
	s_nop 0
	buffer_load_dwordx4 v209, s[16:19], s83 offen lds
	s_mov_b32 m0, s21
	s_add_i32 s83, s80, 0x158000
	buffer_load_dwordx4 v208, s[12:15], s80 offen lds
	s_mov_b32 m0, s48
	s_nop 0
	buffer_load_dwordx4 v208, s[12:15], s83 offen lds
	s_waitcnt vmcnt(8)
	s_waitcnt lgkmcnt(0)
	s_setprio 1
	v_mfma_f32_16x16x32_bf16 v[62:65], v[134:137], v[168:171], v[62:65]
	s_barrier
	v_mfma_f32_16x16x32_bf16 v[62:65], v[138:141], v[172:175], v[62:65]
	v_mfma_f32_16x16x32_bf16 v[58:61], v[142:145], v[168:171], v[58:61]
	v_mfma_f32_16x16x32_bf16 v[58:61], v[148:151], v[172:175], v[58:61]
	v_mfma_f32_16x16x32_bf16 v[46:49], v[152:155], v[168:171], v[46:49]
	v_mfma_f32_16x16x32_bf16 v[46:49], v[156:159], v[172:175], v[46:49]
	v_mfma_f32_16x16x32_bf16 v[38:41], v[160:163], v[168:171], v[38:41]
	v_mfma_f32_16x16x32_bf16 v[38:41], v[164:167], v[172:175], v[38:41]
	v_mfma_f32_16x16x32_bf16 v[54:57], v[134:137], v[176:179], v[54:57]
	v_mfma_f32_16x16x32_bf16 v[54:57], v[138:141], v[180:183], v[54:57]
	v_mfma_f32_16x16x32_bf16 v[50:53], v[142:145], v[176:179], v[50:53]
	v_mfma_f32_16x16x32_bf16 v[50:53], v[148:151], v[180:183], v[50:53]
	v_mfma_f32_16x16x32_bf16 v[30:33], v[152:155], v[176:179], v[30:33]
	v_mfma_f32_16x16x32_bf16 v[30:33], v[156:159], v[180:183], v[30:33]
	v_mfma_f32_16x16x32_bf16 v[22:25], v[160:163], v[176:179], v[22:25]
	v_mfma_f32_16x16x32_bf16 v[22:25], v[164:167], v[180:183], v[22:25]
	v_mfma_f32_16x16x32_bf16 v[42:45], v[134:137], v[184:187], v[42:45]
	v_mfma_f32_16x16x32_bf16 v[42:45], v[138:141], v[188:191], v[42:45]
	v_mfma_f32_16x16x32_bf16 v[34:37], v[142:145], v[184:187], v[34:37]
	v_mfma_f32_16x16x32_bf16 v[34:37], v[148:151], v[188:191], v[34:37]
	v_mfma_f32_16x16x32_bf16 v[14:17], v[152:155], v[184:187], v[14:17]
	v_mfma_f32_16x16x32_bf16 v[14:17], v[156:159], v[188:191], v[14:17]
	v_mfma_f32_16x16x32_bf16 v[10:13], v[160:163], v[184:187], v[10:13]
	v_mfma_f32_16x16x32_bf16 v[10:13], v[164:167], v[188:191], v[10:13]
	v_mfma_f32_16x16x32_bf16 v[26:29], v[134:137], v[192:195], v[26:29]
	v_mfma_f32_16x16x32_bf16 v[26:29], v[138:141], v[196:199], v[26:29]
	v_mfma_f32_16x16x32_bf16 v[18:21], v[142:145], v[192:195], v[18:21]
	v_mfma_f32_16x16x32_bf16 v[18:21], v[148:151], v[196:199], v[18:21]
	v_mfma_f32_16x16x32_bf16 v[6:9], v[152:155], v[192:195], v[6:9]
	v_mfma_f32_16x16x32_bf16 v[6:9], v[156:159], v[196:199], v[6:9]
	v_mfma_f32_16x16x32_bf16 v[2:5], v[160:163], v[192:195], v[2:5]
	v_mfma_f32_16x16x32_bf16 v[2:5], v[164:167], v[196:199], v[2:5]
	s_setprio 0
	s_barrier
	ds_read_b128 v[134:137], v213
	ds_read_b128 v[138:141], v213 offset:1024
	ds_read_b128 v[142:145], v213 offset:2048
	ds_read_b128 v[148:151], v213 offset:3072
	ds_read_b128 v[152:155], v214
	ds_read_b128 v[156:159], v214 offset:1024
	ds_read_b128 v[160:163], v214 offset:2048
	ds_read_b128 v[164:167], v214 offset:3072
	s_mov_b32 m0, s49
	s_add_i32 s83, s80, 0x2b0000
	ds_read_b128 v[168:171], v212 offset:32768
	ds_read_b128 v[172:175], v212 offset:33792
	ds_read_b128 v[176:179], v212 offset:34816
	ds_read_b128 v[180:183], v212 offset:35840
	ds_read_b128 v[184:187], v212 offset:36864
	ds_read_b128 v[188:191], v212 offset:37888
	ds_read_b128 v[192:195], v212 offset:38912
	ds_read_b128 v[196:199], v212 offset:39936
	buffer_load_dwordx4 v208, s[12:15], s83 offen lds
	s_add_i32 s83, s80, 0x408000
	s_mov_b32 m0, s50
	s_nop 0
	buffer_load_dwordx4 v208, s[12:15], s83 offen lds
	s_waitcnt vmcnt(8)
	s_waitcnt lgkmcnt(0)
	s_setprio 1
	v_mfma_f32_16x16x32_bf16 v[126:129], v[134:137], v[168:171], v[126:129]
	s_barrier
	v_mfma_f32_16x16x32_bf16 v[126:129], v[138:141], v[172:175], v[126:129]
	v_mfma_f32_16x16x32_bf16 v[122:125], v[142:145], v[168:171], v[122:125]
	v_mfma_f32_16x16x32_bf16 v[122:125], v[148:151], v[172:175], v[122:125]
	v_mfma_f32_16x16x32_bf16 v[110:113], v[152:155], v[168:171], v[110:113]
	v_mfma_f32_16x16x32_bf16 v[110:113], v[156:159], v[172:175], v[110:113]
	v_mfma_f32_16x16x32_bf16 v[102:105], v[160:163], v[168:171], v[102:105]
	v_mfma_f32_16x16x32_bf16 v[102:105], v[164:167], v[172:175], v[102:105]
	v_mfma_f32_16x16x32_bf16 v[118:121], v[134:137], v[176:179], v[118:121]
	v_mfma_f32_16x16x32_bf16 v[118:121], v[138:141], v[180:183], v[118:121]
	v_mfma_f32_16x16x32_bf16 v[114:117], v[142:145], v[176:179], v[114:117]
	v_mfma_f32_16x16x32_bf16 v[114:117], v[148:151], v[180:183], v[114:117]
	v_mfma_f32_16x16x32_bf16 v[94:97], v[152:155], v[176:179], v[94:97]
	v_mfma_f32_16x16x32_bf16 v[94:97], v[156:159], v[180:183], v[94:97]
	v_mfma_f32_16x16x32_bf16 v[86:89], v[160:163], v[176:179], v[86:89]
	v_mfma_f32_16x16x32_bf16 v[86:89], v[164:167], v[180:183], v[86:89]
	v_mfma_f32_16x16x32_bf16 v[106:109], v[134:137], v[184:187], v[106:109]
	v_mfma_f32_16x16x32_bf16 v[106:109], v[138:141], v[188:191], v[106:109]
	v_mfma_f32_16x16x32_bf16 v[98:101], v[142:145], v[184:187], v[98:101]
	v_mfma_f32_16x16x32_bf16 v[98:101], v[148:151], v[188:191], v[98:101]
	v_mfma_f32_16x16x32_bf16 v[78:81], v[152:155], v[184:187], v[78:81]
	v_mfma_f32_16x16x32_bf16 v[78:81], v[156:159], v[188:191], v[78:81]
	v_mfma_f32_16x16x32_bf16 v[74:77], v[160:163], v[184:187], v[74:77]
	v_mfma_f32_16x16x32_bf16 v[74:77], v[164:167], v[188:191], v[74:77]
	v_mfma_f32_16x16x32_bf16 v[90:93], v[134:137], v[192:195], v[90:93]
	v_mfma_f32_16x16x32_bf16 v[90:93], v[138:141], v[196:199], v[90:93]
	v_mfma_f32_16x16x32_bf16 v[82:85], v[142:145], v[192:195], v[82:85]
	v_mfma_f32_16x16x32_bf16 v[82:85], v[148:151], v[196:199], v[82:85]
	v_mfma_f32_16x16x32_bf16 v[70:73], v[152:155], v[192:195], v[70:73]
	v_mfma_f32_16x16x32_bf16 v[70:73], v[156:159], v[196:199], v[70:73]
	v_mfma_f32_16x16x32_bf16 v[66:69], v[160:163], v[192:195], v[66:69]
	v_mfma_f32_16x16x32_bf16 v[66:69], v[164:167], v[196:199], v[66:69]
	s_setprio 0
	s_barrier
	s_mov_b32 m0, s54
	s_or_b32 s83, s82, 0x80
	ds_read_b128 v[168:171], v212 offset:49152
	ds_read_b128 v[172:175], v212 offset:50176
	ds_read_b128 v[176:179], v212 offset:51200
	ds_read_b128 v[180:183], v212 offset:52224
	ds_read_b128 v[184:187], v212 offset:53248
	ds_read_b128 v[188:191], v212 offset:54272
	ds_read_b128 v[192:195], v212 offset:55296
	ds_read_b128 v[196:199], v212 offset:56320
	buffer_load_dwordx4 v209, s[16:19], s83 offen lds
	s_add_i32 s83, s82, 0x158080
	s_mov_b32 m0, s55
	s_add_i32 s80, s80, 0x158080
	buffer_load_dwordx4 v209, s[16:19], s83 offen lds
	s_add_i32 s83, s82, 0x2b0080
	s_mov_b32 m0, s58
	s_add_i32 s82, s82, 0x408080
	buffer_load_dwordx4 v209, s[16:19], s83 offen lds
	s_mov_b32 m0, s59
	s_nop 0
	buffer_load_dwordx4 v209, s[16:19], s82 offen lds
	s_mov_b32 m0, s56
	s_nop 0
	buffer_load_dwordx4 v208, s[12:15], s81 offen lds
	s_mov_b32 m0, s57
	s_nop 0
	buffer_load_dwordx4 v208, s[12:15], s80 offen lds
	s_waitcnt vmcnt(8)
	s_waitcnt lgkmcnt(0)
	s_setprio 1
	v_mfma_f32_16x16x32_bf16 v[62:65], v[134:137], v[168:171], v[62:65]
	s_barrier
	v_mfma_f32_16x16x32_bf16 v[62:65], v[138:141], v[172:175], v[62:65]
	v_mfma_f32_16x16x32_bf16 v[58:61], v[142:145], v[168:171], v[58:61]
	v_mfma_f32_16x16x32_bf16 v[58:61], v[148:151], v[172:175], v[58:61]
	v_mfma_f32_16x16x32_bf16 v[46:49], v[152:155], v[168:171], v[46:49]
	v_mfma_f32_16x16x32_bf16 v[46:49], v[156:159], v[172:175], v[46:49]
	v_mfma_f32_16x16x32_bf16 v[38:41], v[160:163], v[168:171], v[38:41]
	v_mfma_f32_16x16x32_bf16 v[38:41], v[164:167], v[172:175], v[38:41]
	v_mfma_f32_16x16x32_bf16 v[54:57], v[134:137], v[176:179], v[54:57]
	v_mfma_f32_16x16x32_bf16 v[54:57], v[138:141], v[180:183], v[54:57]
	v_mfma_f32_16x16x32_bf16 v[50:53], v[142:145], v[176:179], v[50:53]
	v_mfma_f32_16x16x32_bf16 v[50:53], v[148:151], v[180:183], v[50:53]
	v_mfma_f32_16x16x32_bf16 v[30:33], v[152:155], v[176:179], v[30:33]
	v_mfma_f32_16x16x32_bf16 v[30:33], v[156:159], v[180:183], v[30:33]
	v_mfma_f32_16x16x32_bf16 v[22:25], v[160:163], v[176:179], v[22:25]
	v_mfma_f32_16x16x32_bf16 v[22:25], v[164:167], v[180:183], v[22:25]
	v_mfma_f32_16x16x32_bf16 v[42:45], v[134:137], v[184:187], v[42:45]
	v_mfma_f32_16x16x32_bf16 v[42:45], v[138:141], v[188:191], v[42:45]
	v_mfma_f32_16x16x32_bf16 v[34:37], v[142:145], v[184:187], v[34:37]
	v_mfma_f32_16x16x32_bf16 v[34:37], v[148:151], v[188:191], v[34:37]
	v_mfma_f32_16x16x32_bf16 v[14:17], v[152:155], v[184:187], v[14:17]
	v_mfma_f32_16x16x32_bf16 v[14:17], v[156:159], v[188:191], v[14:17]
	v_mfma_f32_16x16x32_bf16 v[10:13], v[160:163], v[184:187], v[10:13]
	v_mfma_f32_16x16x32_bf16 v[10:13], v[164:167], v[188:191], v[10:13]
	v_mfma_f32_16x16x32_bf16 v[26:29], v[134:137], v[192:195], v[26:29]
	v_mfma_f32_16x16x32_bf16 v[26:29], v[138:141], v[196:199], v[26:29]
	v_mfma_f32_16x16x32_bf16 v[18:21], v[142:145], v[192:195], v[18:21]
	v_mfma_f32_16x16x32_bf16 v[18:21], v[148:151], v[196:199], v[18:21]
	v_mfma_f32_16x16x32_bf16 v[6:9], v[152:155], v[192:195], v[6:9]
	v_mfma_f32_16x16x32_bf16 v[6:9], v[156:159], v[196:199], v[6:9]
	v_mfma_f32_16x16x32_bf16 v[2:5], v[160:163], v[192:195], v[2:5]
	v_mfma_f32_16x16x32_bf16 v[2:5], v[164:167], v[196:199], v[2:5]
	s_setprio 0
	s_barrier
	s_add_i32 s79, s79, 2
	s_addk_i32 s77, 0x100
	s_addk_i32 s78, 0x100
	s_cmp_ge_i32 s79, s3
	s_cbranch_scc0 .LBB0_799
	v_pk_mul_f32 v[184:185], v[128:129], 0.5 op_sel_hi:[1,0]
	v_pk_mul_f32 v[186:187], v[126:127], 0.5 op_sel_hi:[1,0]
	v_pk_mul_f32 v[188:189], v[124:125], 0.5 op_sel_hi:[1,0]
	v_pk_mul_f32 v[190:191], v[122:123], 0.5 op_sel_hi:[1,0]
	v_pk_mul_f32 v[198:199], v[112:113], 0.5 op_sel_hi:[1,0]
	v_pk_mul_f32 v[196:197], v[110:111], 0.5 op_sel_hi:[1,0]
	v_pk_mul_f32 v[194:195], v[104:105], 0.5 op_sel_hi:[1,0]
	v_pk_mul_f32 v[192:193], v[102:103], 0.5 op_sel_hi:[1,0]
	v_pk_mul_f32 v[182:183], v[120:121], 0.5 op_sel_hi:[1,0]
	v_pk_mul_f32 v[180:181], v[118:119], 0.5 op_sel_hi:[1,0]
	v_pk_mul_f32 v[178:179], v[116:117], 0.5 op_sel_hi:[1,0]
	v_pk_mul_f32 v[176:177], v[114:115], 0.5 op_sel_hi:[1,0]
	v_pk_mul_f32 v[172:173], v[96:97], 0.5 op_sel_hi:[1,0]
	v_pk_mul_f32 v[170:171], v[94:95], 0.5 op_sel_hi:[1,0]
	v_pk_mul_f32 v[168:169], v[88:89], 0.5 op_sel_hi:[1,0]
	v_pk_mul_f32 v[166:167], v[86:87], 0.5 op_sel_hi:[1,0]
	v_pk_mul_f32 v[164:165], v[108:109], 0.5 op_sel_hi:[1,0]
	v_pk_mul_f32 v[162:163], v[106:107], 0.5 op_sel_hi:[1,0]
	v_pk_mul_f32 v[160:161], v[100:101], 0.5 op_sel_hi:[1,0]
	v_pk_mul_f32 v[158:159], v[98:99], 0.5 op_sel_hi:[1,0]
	v_pk_mul_f32 v[156:157], v[80:81], 0.5 op_sel_hi:[1,0]
	v_pk_mul_f32 v[154:155], v[78:79], 0.5 op_sel_hi:[1,0]
	v_pk_mul_f32 v[152:153], v[76:77], 0.5 op_sel_hi:[1,0]
	v_pk_mul_f32 v[150:151], v[74:75], 0.5 op_sel_hi:[1,0]
	v_pk_mul_f32 v[144:145], v[92:93], 0.5 op_sel_hi:[1,0]
	v_pk_mul_f32 v[142:143], v[90:91], 0.5 op_sel_hi:[1,0]
	v_pk_mul_f32 v[140:141], v[84:85], 0.5 op_sel_hi:[1,0]
	v_pk_mul_f32 v[138:139], v[82:83], 0.5 op_sel_hi:[1,0]
	v_pk_mul_f32 v[136:137], v[72:73], 0.5 op_sel_hi:[1,0]
	v_pk_mul_f32 v[134:135], v[70:71], 0.5 op_sel_hi:[1,0]
	v_pk_mul_f32 v[128:129], v[68:69], 0.5 op_sel_hi:[1,0]
	v_pk_mul_f32 v[126:127], v[66:67], 0.5 op_sel_hi:[1,0]
	v_pk_mul_f32 v[122:123], v[64:65], 0.5 op_sel_hi:[1,0]
	v_pk_mul_f32 v[120:121], v[62:63], 0.5 op_sel_hi:[1,0]
	v_pk_mul_f32 v[118:119], v[60:61], 0.5 op_sel_hi:[1,0]
	v_pk_mul_f32 v[116:117], v[58:59], 0.5 op_sel_hi:[1,0]
	v_pk_mul_f32 v[112:113], v[48:49], 0.5 op_sel_hi:[1,0]
	v_pk_mul_f32 v[110:111], v[46:47], 0.5 op_sel_hi:[1,0]
	v_pk_mul_f32 v[108:109], v[40:41], 0.5 op_sel_hi:[1,0]
	v_pk_mul_f32 v[106:107], v[38:39], 0.5 op_sel_hi:[1,0]
	v_pk_mul_f32 v[104:105], v[56:57], 0.5 op_sel_hi:[1,0]
	v_pk_mul_f32 v[102:103], v[54:55], 0.5 op_sel_hi:[1,0]
	v_pk_mul_f32 v[100:101], v[52:53], 0.5 op_sel_hi:[1,0]
	v_pk_mul_f32 v[98:99], v[50:51], 0.5 op_sel_hi:[1,0]
	v_pk_mul_f32 v[96:97], v[32:33], 0.5 op_sel_hi:[1,0]
	v_pk_mul_f32 v[94:95], v[30:31], 0.5 op_sel_hi:[1,0]
	v_pk_mul_f32 v[92:93], v[24:25], 0.5 op_sel_hi:[1,0]
	v_pk_mul_f32 v[90:91], v[22:23], 0.5 op_sel_hi:[1,0]
	v_pk_mul_f32 v[88:89], v[44:45], 0.5 op_sel_hi:[1,0]
	v_pk_mul_f32 v[86:87], v[42:43], 0.5 op_sel_hi:[1,0]
	v_pk_mul_f32 v[84:85], v[36:37], 0.5 op_sel_hi:[1,0]
	v_pk_mul_f32 v[82:83], v[34:35], 0.5 op_sel_hi:[1,0]
	v_pk_mul_f32 v[80:81], v[16:17], 0.5 op_sel_hi:[1,0]
	v_pk_mul_f32 v[78:79], v[14:15], 0.5 op_sel_hi:[1,0]
	v_pk_mul_f32 v[76:77], v[12:13], 0.5 op_sel_hi:[1,0]
	v_pk_mul_f32 v[74:75], v[10:11], 0.5 op_sel_hi:[1,0]
	v_pk_mul_f32 v[72:73], v[28:29], 0.5 op_sel_hi:[1,0]
	v_pk_mul_f32 v[70:71], v[26:27], 0.5 op_sel_hi:[1,0]
	v_pk_mul_f32 v[68:69], v[20:21], 0.5 op_sel_hi:[1,0]
	v_pk_mul_f32 v[66:67], v[18:19], 0.5 op_sel_hi:[1,0]
	v_pk_mul_f32 v[64:65], v[8:9], 0.5 op_sel_hi:[1,0]
	v_pk_mul_f32 v[62:63], v[6:7], 0.5 op_sel_hi:[1,0]
	v_pk_mul_f32 v[60:61], v[4:5], 0.5 op_sel_hi:[1,0]
	v_pk_mul_f32 v[58:59], v[2:3], 0.5 op_sel_hi:[1,0]
	s_and_b64 vcc, exec, s[38:39]
	s_cbranch_vccz .LBB0_802

.LBB0_892:
	ds_read_b128 v[130:133], v172
	ds_read_b128 v[134:137], v172 offset:1024
	ds_read_b128 v[148:151], v172 offset:2048
	ds_read_b128 v[152:155], v172 offset:3072
	ds_read_b128 v[156:159], v173
	ds_read_b128 v[160:163], v173 offset:1024
	ds_read_b128 v[164:167], v173 offset:2048
	ds_read_b128 v[180:183], v173 offset:3072
	s_add_i32 s18, s8, 0xffe80080
	s_cmp_eq_u32 s77, s52
	s_cselect_b32 s53, s6, s18
	s_cselect_b32 s58, s7, s9
	s_or_b32 s57, s53, 0x80
	s_add_i32 s18, s8, 0xfff80000
	s_mov_b32 m0, s78
	ds_read_b128 v[184:187], v174
	ds_read_b128 v[188:191], v174 offset:1024
	ds_read_b128 v[192:195], v174 offset:2048
	ds_read_b128 v[196:199], v174 offset:3072
	ds_read_b128 v[200:203], v174 offset:4096
	ds_read_b128 v[204:207], v174 offset:5120
	ds_read_b128 v[208:211], v174 offset:6144
	ds_read_b128 v[212:215], v174 offset:7168
	buffer_load_dwordx4 v170, s[12:15], s18 offen lds
	s_mov_b32 m0, s79
	s_nop 0
	buffer_load_dwordx4 v170, s[12:15], s8 offen lds
	s_waitcnt vmcnt(8)
	s_waitcnt lgkmcnt(0)
	s_setprio 1
	v_mfma_f32_16x16x32_bf16 v[126:129], v[130:133], v[184:187], v[126:129]
	s_barrier
	v_mfma_f32_16x16x32_bf16 v[126:129], v[134:137], v[188:191], v[126:129]
	v_mfma_f32_16x16x32_bf16 v[118:121], v[148:151], v[184:187], v[118:121]
	v_mfma_f32_16x16x32_bf16 v[118:121], v[152:155], v[188:191], v[118:121]
	v_mfma_f32_16x16x32_bf16 v[122:125], v[156:159], v[184:187], v[122:125]
	v_mfma_f32_16x16x32_bf16 v[122:125], v[160:163], v[188:191], v[122:125]
	v_mfma_f32_16x16x32_bf16 v[114:117], v[164:167], v[184:187], v[114:117]
	v_mfma_f32_16x16x32_bf16 v[114:117], v[180:183], v[188:191], v[114:117]
	v_mfma_f32_16x16x32_bf16 v[110:113], v[130:133], v[192:195], v[110:113]
	v_mfma_f32_16x16x32_bf16 v[110:113], v[134:137], v[196:199], v[110:113]
	v_mfma_f32_16x16x32_bf16 v[102:105], v[148:151], v[192:195], v[102:105]
	v_mfma_f32_16x16x32_bf16 v[102:105], v[152:155], v[196:199], v[102:105]
	v_mfma_f32_16x16x32_bf16 v[106:109], v[156:159], v[192:195], v[106:109]
	v_mfma_f32_16x16x32_bf16 v[106:109], v[160:163], v[196:199], v[106:109]
	v_mfma_f32_16x16x32_bf16 v[98:101], v[164:167], v[192:195], v[98:101]
	v_mfma_f32_16x16x32_bf16 v[98:101], v[180:183], v[196:199], v[98:101]
	v_mfma_f32_16x16x32_bf16 v[94:97], v[130:133], v[200:203], v[94:97]
	v_mfma_f32_16x16x32_bf16 v[94:97], v[134:137], v[204:207], v[94:97]
	v_mfma_f32_16x16x32_bf16 v[90:93], v[148:151], v[200:203], v[90:93]
	v_mfma_f32_16x16x32_bf16 v[90:93], v[152:155], v[204:207], v[90:93]
	v_mfma_f32_16x16x32_bf16 v[86:89], v[156:159], v[200:203], v[86:89]
	v_mfma_f32_16x16x32_bf16 v[86:89], v[160:163], v[204:207], v[86:89]
	v_mfma_f32_16x16x32_bf16 v[82:85], v[164:167], v[200:203], v[82:85]
	v_mfma_f32_16x16x32_bf16 v[82:85], v[180:183], v[204:207], v[82:85]
	v_mfma_f32_16x16x32_bf16 v[78:81], v[130:133], v[208:211], v[78:81]
	v_mfma_f32_16x16x32_bf16 v[78:81], v[134:137], v[212:215], v[78:81]
	v_mfma_f32_16x16x32_bf16 v[70:73], v[148:151], v[208:211], v[70:73]
	v_mfma_f32_16x16x32_bf16 v[70:73], v[152:155], v[212:215], v[70:73]
	v_mfma_f32_16x16x32_bf16 v[74:77], v[156:159], v[208:211], v[74:77]
	v_mfma_f32_16x16x32_bf16 v[74:77], v[160:163], v[212:215], v[74:77]
	v_mfma_f32_16x16x32_bf16 v[66:69], v[164:167], v[208:211], v[66:69]
	v_mfma_f32_16x16x32_bf16 v[66:69], v[180:183], v[212:215], v[66:69]
	s_setprio 0
	s_barrier
	s_mov_b32 m0, s27
	s_mov_b32 s18, s14
	s_mov_b32 s19, s15
	ds_read_b128 v[184:187], v174 offset:16384
	ds_read_b128 v[188:191], v174 offset:17408
	ds_read_b128 v[192:195], v174 offset:18432
	ds_read_b128 v[196:199], v174 offset:19456
	ds_read_b128 v[200:203], v174 offset:20480
	ds_read_b128 v[204:207], v174 offset:21504
	ds_read_b128 v[208:211], v174 offset:22528
	ds_read_b128 v[212:215], v174 offset:23552
	buffer_load_dwordx4 v171, s[16:19], s58 offen lds
	s_add_i32 s59, s58, 0x80000
	s_mov_b32 m0, s60
	s_nop 0
	buffer_load_dwordx4 v171, s[16:19], s59 offen lds
	s_add_i32 s59, s58, 0x100000
	s_mov_b32 m0, s61
	s_nop 0
	buffer_load_dwordx4 v171, s[16:19], s59 offen lds
	s_add_i32 s59, s58, 0x180000
	s_mov_b32 m0, s62
	s_nop 0
	buffer_load_dwordx4 v171, s[16:19], s59 offen lds
	s_mov_b32 m0, s25
	s_add_i32 s59, s53, 0x80000
	buffer_load_dwordx4 v170, s[12:15], s53 offen lds
	s_mov_b32 m0, s63
	s_nop 0
	buffer_load_dwordx4 v170, s[12:15], s59 offen lds
	s_waitcnt vmcnt(8)
	s_waitcnt lgkmcnt(0)
	s_setprio 1
	v_mfma_f32_16x16x32_bf16 v[62:65], v[130:133], v[184:187], v[62:65]
	s_barrier
	v_mfma_f32_16x16x32_bf16 v[62:65], v[134:137], v[188:191], v[62:65]
	v_mfma_f32_16x16x32_bf16 v[54:57], v[148:151], v[184:187], v[54:57]
	v_mfma_f32_16x16x32_bf16 v[54:57], v[152:155], v[188:191], v[54:57]
	v_mfma_f32_16x16x32_bf16 v[58:61], v[156:159], v[184:187], v[58:61]
	v_mfma_f32_16x16x32_bf16 v[58:61], v[160:163], v[188:191], v[58:61]
	v_mfma_f32_16x16x32_bf16 v[50:53], v[164:167], v[184:187], v[50:53]
	v_mfma_f32_16x16x32_bf16 v[50:53], v[180:183], v[188:191], v[50:53]
	v_mfma_f32_16x16x32_bf16 v[46:49], v[130:133], v[192:195], v[46:49]
	v_mfma_f32_16x16x32_bf16 v[46:49], v[134:137], v[196:199], v[46:49]
	v_mfma_f32_16x16x32_bf16 v[38:41], v[148:151], v[192:195], v[38:41]
	v_mfma_f32_16x16x32_bf16 v[38:41], v[152:155], v[196:199], v[38:41]
	v_mfma_f32_16x16x32_bf16 v[42:45], v[156:159], v[192:195], v[42:45]
	v_mfma_f32_16x16x32_bf16 v[42:45], v[160:163], v[196:199], v[42:45]
	v_mfma_f32_16x16x32_bf16 v[34:37], v[164:167], v[192:195], v[34:37]
	v_mfma_f32_16x16x32_bf16 v[34:37], v[180:183], v[196:199], v[34:37]
	v_mfma_f32_16x16x32_bf16 v[30:33], v[130:133], v[200:203], v[30:33]
	v_mfma_f32_16x16x32_bf16 v[30:33], v[134:137], v[204:207], v[30:33]
	v_mfma_f32_16x16x32_bf16 v[22:25], v[148:151], v[200:203], v[22:25]
	v_mfma_f32_16x16x32_bf16 v[22:25], v[152:155], v[204:207], v[22:25]
	v_mfma_f32_16x16x32_bf16 v[26:29], v[156:159], v[200:203], v[26:29]
	v_mfma_f32_16x16x32_bf16 v[26:29], v[160:163], v[204:207], v[26:29]
	v_mfma_f32_16x16x32_bf16 v[18:21], v[164:167], v[200:203], v[18:21]
	v_mfma_f32_16x16x32_bf16 v[18:21], v[180:183], v[204:207], v[18:21]
	v_mfma_f32_16x16x32_bf16 v[14:17], v[130:133], v[208:211], v[14:17]
	v_mfma_f32_16x16x32_bf16 v[14:17], v[134:137], v[212:215], v[14:17]
	v_mfma_f32_16x16x32_bf16 v[6:9], v[148:151], v[208:211], v[6:9]
	v_mfma_f32_16x16x32_bf16 v[6:9], v[152:155], v[212:215], v[6:9]
	v_mfma_f32_16x16x32_bf16 v[10:13], v[156:159], v[208:211], v[10:13]
	v_mfma_f32_16x16x32_bf16 v[10:13], v[160:163], v[212:215], v[10:13]
	v_mfma_f32_16x16x32_bf16 v[2:5], v[164:167], v[208:211], v[2:5]
	v_mfma_f32_16x16x32_bf16 v[2:5], v[180:183], v[212:215], v[2:5]
	s_setprio 0
	s_barrier
	ds_read_b128 v[130:133], v175
	ds_read_b128 v[134:137], v175 offset:1024
	ds_read_b128 v[148:151], v175 offset:2048
	ds_read_b128 v[152:155], v175 offset:3072
	ds_read_b128 v[156:159], v176
	ds_read_b128 v[160:163], v176 offset:1024
	ds_read_b128 v[164:167], v176 offset:2048
	ds_read_b128 v[180:183], v176 offset:3072
	s_mov_b32 m0, s64
	s_add_i32 s59, s53, 0x100000
	ds_read_b128 v[184:187], v174 offset:32768
	ds_read_b128 v[188:191], v174 offset:33792
	ds_read_b128 v[192:195], v174 offset:34816
	ds_read_b128 v[196:199], v174 offset:35840
	ds_read_b128 v[200:203], v174 offset:36864
	ds_read_b128 v[204:207], v174 offset:37888
	ds_read_b128 v[208:211], v174 offset:38912
	ds_read_b128 v[212:215], v174 offset:39936
	buffer_load_dwordx4 v170, s[12:15], s59 offen lds
	s_add_i32 s59, s53, 0x180000
	s_mov_b32 m0, s65
	s_nop 0
	buffer_load_dwordx4 v170, s[12:15], s59 offen lds
	s_waitcnt vmcnt(8)
	s_waitcnt lgkmcnt(0)
	s_setprio 1
	v_mfma_f32_16x16x32_bf16 v[126:129], v[130:133], v[184:187], v[126:129]
	s_barrier
	v_mfma_f32_16x16x32_bf16 v[126:129], v[134:137], v[188:191], v[126:129]
	v_mfma_f32_16x16x32_bf16 v[118:121], v[148:151], v[184:187], v[118:121]
	v_mfma_f32_16x16x32_bf16 v[118:121], v[152:155], v[188:191], v[118:121]
	v_mfma_f32_16x16x32_bf16 v[122:125], v[156:159], v[184:187], v[122:125]
	v_mfma_f32_16x16x32_bf16 v[122:125], v[160:163], v[188:191], v[122:125]
	v_mfma_f32_16x16x32_bf16 v[114:117], v[164:167], v[184:187], v[114:117]
	v_mfma_f32_16x16x32_bf16 v[114:117], v[180:183], v[188:191], v[114:117]
	v_mfma_f32_16x16x32_bf16 v[110:113], v[130:133], v[192:195], v[110:113]
	v_mfma_f32_16x16x32_bf16 v[110:113], v[134:137], v[196:199], v[110:113]
	v_mfma_f32_16x16x32_bf16 v[102:105], v[148:151], v[192:195], v[102:105]
	v_mfma_f32_16x16x32_bf16 v[102:105], v[152:155], v[196:199], v[102:105]
	v_mfma_f32_16x16x32_bf16 v[106:109], v[156:159], v[192:195], v[106:109]
	v_mfma_f32_16x16x32_bf16 v[106:109], v[160:163], v[196:199], v[106:109]
	v_mfma_f32_16x16x32_bf16 v[98:101], v[164:167], v[192:195], v[98:101]
	v_mfma_f32_16x16x32_bf16 v[98:101], v[180:183], v[196:199], v[98:101]
	v_mfma_f32_16x16x32_bf16 v[94:97], v[130:133], v[200:203], v[94:97]
	v_mfma_f32_16x16x32_bf16 v[94:97], v[134:137], v[204:207], v[94:97]
	v_mfma_f32_16x16x32_bf16 v[90:93], v[148:151], v[200:203], v[90:93]
	v_mfma_f32_16x16x32_bf16 v[90:93], v[152:155], v[204:207], v[90:93]
	v_mfma_f32_16x16x32_bf16 v[86:89], v[156:159], v[200:203], v[86:89]
	v_mfma_f32_16x16x32_bf16 v[86:89], v[160:163], v[204:207], v[86:89]
	v_mfma_f32_16x16x32_bf16 v[82:85], v[164:167], v[200:203], v[82:85]
	v_mfma_f32_16x16x32_bf16 v[82:85], v[180:183], v[204:207], v[82:85]
	v_mfma_f32_16x16x32_bf16 v[78:81], v[130:133], v[208:211], v[78:81]
	v_mfma_f32_16x16x32_bf16 v[78:81], v[134:137], v[212:215], v[78:81]
	v_mfma_f32_16x16x32_bf16 v[70:73], v[148:151], v[208:211], v[70:73]
	v_mfma_f32_16x16x32_bf16 v[70:73], v[152:155], v[212:215], v[70:73]
	v_mfma_f32_16x16x32_bf16 v[74:77], v[156:159], v[208:211], v[74:77]
	v_mfma_f32_16x16x32_bf16 v[74:77], v[160:163], v[212:215], v[74:77]
	v_mfma_f32_16x16x32_bf16 v[66:69], v[164:167], v[208:211], v[66:69]
	v_mfma_f32_16x16x32_bf16 v[66:69], v[180:183], v[212:215], v[66:69]
	s_setprio 0
	s_barrier
	s_mov_b32 m0, s70
	s_or_b32 s59, s58, 0x80
	ds_read_b128 v[184:187], v174 offset:49152
	ds_read_b128 v[188:191], v174 offset:50176
	ds_read_b128 v[192:195], v174 offset:51200
	ds_read_b128 v[196:199], v174 offset:52224
	ds_read_b128 v[200:203], v174 offset:53248
	ds_read_b128 v[204:207], v174 offset:54272
	ds_read_b128 v[208:211], v174 offset:55296
	ds_read_b128 v[212:215], v174 offset:56320
	buffer_load_dwordx4 v171, s[16:19], s59 offen lds
	s_add_i32 s59, s58, 0x80080
	s_mov_b32 m0, s71
	s_add_i32 s53, s53, 0x80080
	buffer_load_dwordx4 v171, s[16:19], s59 offen lds
	s_add_i32 s59, s58, 0x100080
	s_mov_b32 m0, s74
	s_add_i32 s58, s58, 0x180080
	buffer_load_dwordx4 v171, s[16:19], s59 offen lds
	s_mov_b32 m0, s75
	s_nop 0
	buffer_load_dwordx4 v171, s[16:19], s58 offen lds
	s_mov_b32 m0, s72
	s_nop 0
	buffer_load_dwordx4 v170, s[12:15], s57 offen lds
	s_mov_b32 m0, s73
	s_nop 0
	buffer_load_dwordx4 v170, s[12:15], s53 offen lds
	s_waitcnt vmcnt(8)
	s_waitcnt lgkmcnt(0)
	s_setprio 1
	v_mfma_f32_16x16x32_bf16 v[62:65], v[130:133], v[184:187], v[62:65]
	s_barrier
	v_mfma_f32_16x16x32_bf16 v[62:65], v[134:137], v[188:191], v[62:65]
	v_mfma_f32_16x16x32_bf16 v[54:57], v[148:151], v[184:187], v[54:57]
	v_mfma_f32_16x16x32_bf16 v[54:57], v[152:155], v[188:191], v[54:57]
	v_mfma_f32_16x16x32_bf16 v[58:61], v[156:159], v[184:187], v[58:61]
	v_mfma_f32_16x16x32_bf16 v[58:61], v[160:163], v[188:191], v[58:61]
	v_mfma_f32_16x16x32_bf16 v[50:53], v[164:167], v[184:187], v[50:53]
	v_mfma_f32_16x16x32_bf16 v[50:53], v[180:183], v[188:191], v[50:53]
	v_mfma_f32_16x16x32_bf16 v[46:49], v[130:133], v[192:195], v[46:49]
	v_mfma_f32_16x16x32_bf16 v[46:49], v[134:137], v[196:199], v[46:49]
	v_mfma_f32_16x16x32_bf16 v[38:41], v[148:151], v[192:195], v[38:41]
	v_mfma_f32_16x16x32_bf16 v[38:41], v[152:155], v[196:199], v[38:41]
	v_mfma_f32_16x16x32_bf16 v[42:45], v[156:159], v[192:195], v[42:45]
	v_mfma_f32_16x16x32_bf16 v[42:45], v[160:163], v[196:199], v[42:45]
	v_mfma_f32_16x16x32_bf16 v[34:37], v[164:167], v[192:195], v[34:37]
	v_mfma_f32_16x16x32_bf16 v[34:37], v[180:183], v[196:199], v[34:37]
	v_mfma_f32_16x16x32_bf16 v[30:33], v[130:133], v[200:203], v[30:33]
	v_mfma_f32_16x16x32_bf16 v[30:33], v[134:137], v[204:207], v[30:33]
	v_mfma_f32_16x16x32_bf16 v[22:25], v[148:151], v[200:203], v[22:25]
	v_mfma_f32_16x16x32_bf16 v[22:25], v[152:155], v[204:207], v[22:25]
	v_mfma_f32_16x16x32_bf16 v[26:29], v[156:159], v[200:203], v[26:29]
	v_mfma_f32_16x16x32_bf16 v[26:29], v[160:163], v[204:207], v[26:29]
	v_mfma_f32_16x16x32_bf16 v[18:21], v[164:167], v[200:203], v[18:21]
	v_mfma_f32_16x16x32_bf16 v[18:21], v[180:183], v[204:207], v[18:21]
	v_mfma_f32_16x16x32_bf16 v[14:17], v[130:133], v[208:211], v[14:17]
	v_mfma_f32_16x16x32_bf16 v[14:17], v[134:137], v[212:215], v[14:17]
	v_mfma_f32_16x16x32_bf16 v[6:9], v[148:151], v[208:211], v[6:9]
	v_mfma_f32_16x16x32_bf16 v[6:9], v[152:155], v[212:215], v[6:9]
	v_mfma_f32_16x16x32_bf16 v[10:13], v[156:159], v[208:211], v[10:13]
	v_mfma_f32_16x16x32_bf16 v[10:13], v[160:163], v[212:215], v[10:13]
	v_mfma_f32_16x16x32_bf16 v[2:5], v[164:167], v[208:211], v[2:5]
	v_mfma_f32_16x16x32_bf16 v[2:5], v[180:183], v[212:215], v[2:5]
	s_setprio 0
	s_barrier
	s_add_i32 s52, s52, 2
	s_addk_i32 s8, 0x100
	s_addk_i32 s9, 0x100
	s_cmp_ge_i32 s52, s21
	s_cbranch_scc0 .LBB0_892
	s_and_b64 vcc, exec, s[48:49]
	s_cbranch_vccz .LBB0_895

.LBB0_1020:
	v_add_u32_e32 v142, 0x10000, v162
	v_add_u32_e32 v150, 0x14000, v162
	ds_read_b128 v[130:133], v142
	ds_read_b128 v[134:137], v142 offset:1024
	ds_read_b128 v[138:141], v142 offset:2048
	ds_read_b128 v[142:145], v142 offset:3072
	ds_read_b128 v[154:157], v150
	ds_read_b128 v[164:167], v150 offset:1024
	ds_read_b128 v[168:171], v150 offset:2048
	ds_read_b128 v[172:175], v150 offset:3072
	s_add_i32 s90, s6, 0x100
	s_add_i32 s7, s88, s6
	s_cmp_eq_u32 s81, s89
	s_cselect_b32 s91, 0, s90
	s_cselect_b32 s93, s87, s7
	s_add_i32 s91, s91, s70
	s_or_b32 s92, s91, 0x80
	s_add_i32 s6, s3, s6
	s_mov_b32 m0, s82
	s_add_i32 s7, s6, 0x20080
	ds_read_b128 v[176:179], v163
	ds_read_b128 v[180:183], v163 offset:1024
	ds_read_b128 v[184:187], v163 offset:2048
	ds_read_b128 v[188:191], v163 offset:3072
	ds_read_b128 v[192:195], v163 offset:4096
	ds_read_b128 v[196:199], v163 offset:5120
	ds_read_b128 v[200:203], v163 offset:6144
	ds_read_b128 v[204:207], v163 offset:7168
	buffer_load_dwordx4 v161, s[12:15], s7 offen lds
	s_add_i32 s6, s6, 0x30080
	s_mov_b32 m0, s83
	s_nop 0
	buffer_load_dwordx4 v161, s[12:15], s6 offen lds
	s_waitcnt vmcnt(8)
	s_waitcnt lgkmcnt(0)
	s_setprio 1
	v_mfma_f32_16x16x32_bf16 v[126:129], v[130:133], v[176:179], v[126:129]
	s_barrier
	v_mfma_f32_16x16x32_bf16 v[126:129], v[134:137], v[180:183], v[126:129]
	v_mfma_f32_16x16x32_bf16 v[122:125], v[138:141], v[176:179], v[122:125]
	v_mfma_f32_16x16x32_bf16 v[122:125], v[142:145], v[180:183], v[122:125]
	v_mfma_f32_16x16x32_bf16 v[118:121], v[154:157], v[176:179], v[118:121]
	v_mfma_f32_16x16x32_bf16 v[118:121], v[164:167], v[180:183], v[118:121]
	v_mfma_f32_16x16x32_bf16 v[114:117], v[168:171], v[176:179], v[114:117]
	v_mfma_f32_16x16x32_bf16 v[114:117], v[172:175], v[180:183], v[114:117]
	v_mfma_f32_16x16x32_bf16 v[110:113], v[130:133], v[184:187], v[110:113]
	v_mfma_f32_16x16x32_bf16 v[110:113], v[134:137], v[188:191], v[110:113]
	v_mfma_f32_16x16x32_bf16 v[106:109], v[138:141], v[184:187], v[106:109]
	v_mfma_f32_16x16x32_bf16 v[106:109], v[142:145], v[188:191], v[106:109]
	v_mfma_f32_16x16x32_bf16 v[102:105], v[154:157], v[184:187], v[102:105]
	v_mfma_f32_16x16x32_bf16 v[102:105], v[164:167], v[188:191], v[102:105]
	v_mfma_f32_16x16x32_bf16 v[98:101], v[168:171], v[184:187], v[98:101]
	v_mfma_f32_16x16x32_bf16 v[98:101], v[172:175], v[188:191], v[98:101]
	v_mfma_f32_16x16x32_bf16 v[94:97], v[130:133], v[192:195], v[94:97]
	v_mfma_f32_16x16x32_bf16 v[94:97], v[134:137], v[196:199], v[94:97]
	v_mfma_f32_16x16x32_bf16 v[90:93], v[138:141], v[192:195], v[90:93]
	v_mfma_f32_16x16x32_bf16 v[90:93], v[142:145], v[196:199], v[90:93]
	v_mfma_f32_16x16x32_bf16 v[86:89], v[154:157], v[192:195], v[86:89]
	v_mfma_f32_16x16x32_bf16 v[86:89], v[164:167], v[196:199], v[86:89]
	v_mfma_f32_16x16x32_bf16 v[82:85], v[168:171], v[192:195], v[82:85]
	v_mfma_f32_16x16x32_bf16 v[82:85], v[172:175], v[196:199], v[82:85]
	v_mfma_f32_16x16x32_bf16 v[78:81], v[130:133], v[200:203], v[78:81]
	v_mfma_f32_16x16x32_bf16 v[78:81], v[134:137], v[204:207], v[78:81]
	v_mfma_f32_16x16x32_bf16 v[74:77], v[138:141], v[200:203], v[74:77]
	v_mfma_f32_16x16x32_bf16 v[74:77], v[142:145], v[204:207], v[74:77]
	v_mfma_f32_16x16x32_bf16 v[70:73], v[154:157], v[200:203], v[70:73]
	v_mfma_f32_16x16x32_bf16 v[70:73], v[164:167], v[204:207], v[70:73]
	v_mfma_f32_16x16x32_bf16 v[66:69], v[168:171], v[200:203], v[66:69]
	v_mfma_f32_16x16x32_bf16 v[66:69], v[172:175], v[204:207], v[66:69]
	s_setprio 0
	s_barrier
	s_mov_b32 m0, s66
	s_mov_b32 s6, s14
	s_mov_b32 s7, s15
	ds_read_b128 v[176:179], v163 offset:16384
	ds_read_b128 v[180:183], v163 offset:17408
	ds_read_b128 v[184:187], v163 offset:18432
	ds_read_b128 v[188:191], v163 offset:19456
	ds_read_b128 v[192:195], v163 offset:20480
	ds_read_b128 v[196:199], v163 offset:21504
	ds_read_b128 v[200:203], v163 offset:22528
	ds_read_b128 v[204:207], v163 offset:23552
	buffer_load_dwordx4 v160, s[4:7], s93 offen lds
	s_add_i32 s94, s93, 0x10000
	s_mov_b32 m0, s67
	s_nop 0
	buffer_load_dwordx4 v160, s[4:7], s94 offen lds
	s_add_i32 s94, s93, 0x20000
	s_mov_b32 m0, s68
	s_nop 0
	buffer_load_dwordx4 v160, s[4:7], s94 offen lds
	s_add_i32 s94, s93, 0x30000
	s_mov_b32 m0, s69
	s_nop 0
	buffer_load_dwordx4 v160, s[4:7], s94 offen lds
	s_mov_b32 m0, s65
	s_add_i32 s94, s91, 0x10000
	buffer_load_dwordx4 v161, s[12:15], s91 offen lds
	s_mov_b32 m0, s71
	s_nop 0
	buffer_load_dwordx4 v161, s[12:15], s94 offen lds
	s_waitcnt vmcnt(8)
	s_waitcnt lgkmcnt(0)
	s_setprio 1
	v_mfma_f32_16x16x32_bf16 v[62:65], v[130:133], v[176:179], v[62:65]
	s_barrier
	v_mfma_f32_16x16x32_bf16 v[62:65], v[134:137], v[180:183], v[62:65]
	v_mfma_f32_16x16x32_bf16 v[58:61], v[138:141], v[176:179], v[58:61]
	v_mfma_f32_16x16x32_bf16 v[58:61], v[142:145], v[180:183], v[58:61]
	v_mfma_f32_16x16x32_bf16 v[54:57], v[154:157], v[176:179], v[54:57]
	v_mfma_f32_16x16x32_bf16 v[54:57], v[164:167], v[180:183], v[54:57]
	v_mfma_f32_16x16x32_bf16 v[50:53], v[168:171], v[176:179], v[50:53]
	v_mfma_f32_16x16x32_bf16 v[50:53], v[172:175], v[180:183], v[50:53]
	v_mfma_f32_16x16x32_bf16 v[46:49], v[130:133], v[184:187], v[46:49]
	v_mfma_f32_16x16x32_bf16 v[46:49], v[134:137], v[188:191], v[46:49]
	v_mfma_f32_16x16x32_bf16 v[42:45], v[138:141], v[184:187], v[42:45]
	v_mfma_f32_16x16x32_bf16 v[42:45], v[142:145], v[188:191], v[42:45]
	v_mfma_f32_16x16x32_bf16 v[38:41], v[154:157], v[184:187], v[38:41]
	v_mfma_f32_16x16x32_bf16 v[38:41], v[164:167], v[188:191], v[38:41]
	v_mfma_f32_16x16x32_bf16 v[34:37], v[168:171], v[184:187], v[34:37]
	v_mfma_f32_16x16x32_bf16 v[34:37], v[172:175], v[188:191], v[34:37]
	v_mfma_f32_16x16x32_bf16 v[30:33], v[130:133], v[192:195], v[30:33]
	v_mfma_f32_16x16x32_bf16 v[30:33], v[134:137], v[196:199], v[30:33]
	v_mfma_f32_16x16x32_bf16 v[26:29], v[138:141], v[192:195], v[26:29]
	v_mfma_f32_16x16x32_bf16 v[26:29], v[142:145], v[196:199], v[26:29]
	v_mfma_f32_16x16x32_bf16 v[22:25], v[154:157], v[192:195], v[22:25]
	v_mfma_f32_16x16x32_bf16 v[22:25], v[164:167], v[196:199], v[22:25]
	v_mfma_f32_16x16x32_bf16 v[18:21], v[168:171], v[192:195], v[18:21]
	v_mfma_f32_16x16x32_bf16 v[18:21], v[172:175], v[196:199], v[18:21]
	v_mfma_f32_16x16x32_bf16 v[14:17], v[130:133], v[200:203], v[14:17]
	v_mfma_f32_16x16x32_bf16 v[14:17], v[134:137], v[204:207], v[14:17]
	v_mfma_f32_16x16x32_bf16 v[10:13], v[138:141], v[200:203], v[10:13]
	v_mfma_f32_16x16x32_bf16 v[10:13], v[142:145], v[204:207], v[10:13]
	v_mfma_f32_16x16x32_bf16 v[6:9], v[154:157], v[200:203], v[6:9]
	v_mfma_f32_16x16x32_bf16 v[6:9], v[164:167], v[204:207], v[6:9]
	v_mfma_f32_16x16x32_bf16 v[2:5], v[168:171], v[200:203], v[2:5]
	v_mfma_f32_16x16x32_bf16 v[2:5], v[172:175], v[204:207], v[2:5]
	s_setprio 0
	s_barrier
	v_add_u32_e32 v142, 0x18000, v162
	v_add_u32_e32 v150, 0x1c000, v162
	ds_read_b128 v[130:133], v142
	ds_read_b128 v[134:137], v142 offset:1024
	ds_read_b128 v[138:141], v142 offset:2048
	ds_read_b128 v[142:145], v142 offset:3072
	ds_read_b128 v[154:157], v150
	ds_read_b128 v[164:167], v150 offset:1024
	ds_read_b128 v[168:171], v150 offset:2048
	ds_read_b128 v[172:175], v150 offset:3072
	s_mov_b32 m0, s72
	s_add_i32 s94, s91, 0x20000
	ds_read_b128 v[176:179], v163 offset:32768
	ds_read_b128 v[180:183], v163 offset:33792
	ds_read_b128 v[184:187], v163 offset:34816
	ds_read_b128 v[188:191], v163 offset:35840
	ds_read_b128 v[192:195], v163 offset:36864
	ds_read_b128 v[196:199], v163 offset:37888
	ds_read_b128 v[200:203], v163 offset:38912
	ds_read_b128 v[204:207], v163 offset:39936
	buffer_load_dwordx4 v161, s[12:15], s94 offen lds
	s_add_i32 s94, s91, 0x30000
	s_mov_b32 m0, s73
	s_nop 0
	buffer_load_dwordx4 v161, s[12:15], s94 offen lds
	s_waitcnt vmcnt(8)
	s_waitcnt lgkmcnt(0)
	s_setprio 1
	v_mfma_f32_16x16x32_bf16 v[126:129], v[130:133], v[176:179], v[126:129]
	s_barrier
	v_mfma_f32_16x16x32_bf16 v[126:129], v[134:137], v[180:183], v[126:129]
	v_mfma_f32_16x16x32_bf16 v[122:125], v[138:141], v[176:179], v[122:125]
	v_mfma_f32_16x16x32_bf16 v[122:125], v[142:145], v[180:183], v[122:125]
	v_mfma_f32_16x16x32_bf16 v[118:121], v[154:157], v[176:179], v[118:121]
	v_mfma_f32_16x16x32_bf16 v[118:121], v[164:167], v[180:183], v[118:121]
	v_mfma_f32_16x16x32_bf16 v[114:117], v[168:171], v[176:179], v[114:117]
	v_mfma_f32_16x16x32_bf16 v[114:117], v[172:175], v[180:183], v[114:117]
	v_mfma_f32_16x16x32_bf16 v[110:113], v[130:133], v[184:187], v[110:113]
	v_mfma_f32_16x16x32_bf16 v[110:113], v[134:137], v[188:191], v[110:113]
	v_mfma_f32_16x16x32_bf16 v[106:109], v[138:141], v[184:187], v[106:109]
	v_mfma_f32_16x16x32_bf16 v[106:109], v[142:145], v[188:191], v[106:109]
	v_mfma_f32_16x16x32_bf16 v[102:105], v[154:157], v[184:187], v[102:105]
	v_mfma_f32_16x16x32_bf16 v[102:105], v[164:167], v[188:191], v[102:105]
	v_mfma_f32_16x16x32_bf16 v[98:101], v[168:171], v[184:187], v[98:101]
	v_mfma_f32_16x16x32_bf16 v[98:101], v[172:175], v[188:191], v[98:101]
	v_mfma_f32_16x16x32_bf16 v[94:97], v[130:133], v[192:195], v[94:97]
	v_mfma_f32_16x16x32_bf16 v[94:97], v[134:137], v[196:199], v[94:97]
	v_mfma_f32_16x16x32_bf16 v[90:93], v[138:141], v[192:195], v[90:93]
	v_mfma_f32_16x16x32_bf16 v[90:93], v[142:145], v[196:199], v[90:93]
	v_mfma_f32_16x16x32_bf16 v[86:89], v[154:157], v[192:195], v[86:89]
	v_mfma_f32_16x16x32_bf16 v[86:89], v[164:167], v[196:199], v[86:89]
	v_mfma_f32_16x16x32_bf16 v[82:85], v[168:171], v[192:195], v[82:85]
	v_mfma_f32_16x16x32_bf16 v[82:85], v[172:175], v[196:199], v[82:85]
	v_mfma_f32_16x16x32_bf16 v[78:81], v[130:133], v[200:203], v[78:81]
	v_mfma_f32_16x16x32_bf16 v[78:81], v[134:137], v[204:207], v[78:81]
	v_mfma_f32_16x16x32_bf16 v[74:77], v[138:141], v[200:203], v[74:77]
	v_mfma_f32_16x16x32_bf16 v[74:77], v[142:145], v[204:207], v[74:77]
	v_mfma_f32_16x16x32_bf16 v[70:73], v[154:157], v[200:203], v[70:73]
	v_mfma_f32_16x16x32_bf16 v[70:73], v[164:167], v[204:207], v[70:73]
	v_mfma_f32_16x16x32_bf16 v[66:69], v[168:171], v[200:203], v[66:69]
	v_mfma_f32_16x16x32_bf16 v[66:69], v[172:175], v[204:207], v[66:69]
	s_setprio 0
	s_barrier
	s_mov_b32 m0, s74
	s_or_b32 s94, s93, 0x80
	ds_read_b128 v[176:179], v163 offset:49152
	ds_read_b128 v[180:183], v163 offset:50176
	ds_read_b128 v[184:187], v163 offset:51200
	ds_read_b128 v[188:191], v163 offset:52224
	ds_read_b128 v[192:195], v163 offset:53248
	ds_read_b128 v[196:199], v163 offset:54272
	ds_read_b128 v[200:203], v163 offset:55296
	ds_read_b128 v[204:207], v163 offset:56320
	buffer_load_dwordx4 v160, s[4:7], s94 offen lds
	s_add_i32 s94, s93, 0x10080
	s_mov_b32 m0, s75
	s_add_i32 s91, s91, 0x10080
	buffer_load_dwordx4 v160, s[4:7], s94 offen lds
	s_add_i32 s94, s93, 0x20080
	s_mov_b32 m0, s78
	s_add_i32 s93, s93, 0x30080
	buffer_load_dwordx4 v160, s[4:7], s94 offen lds
	s_mov_b32 m0, s79
	s_nop 0
	buffer_load_dwordx4 v160, s[4:7], s93 offen lds
	s_mov_b32 m0, s76
	s_nop 0
	buffer_load_dwordx4 v161, s[12:15], s92 offen lds
	s_mov_b32 m0, s77
	s_nop 0
	buffer_load_dwordx4 v161, s[12:15], s91 offen lds
	s_waitcnt vmcnt(8)
	s_waitcnt lgkmcnt(0)
	s_setprio 1
	v_mfma_f32_16x16x32_bf16 v[62:65], v[130:133], v[176:179], v[62:65]
	s_barrier
	v_mfma_f32_16x16x32_bf16 v[62:65], v[134:137], v[180:183], v[62:65]
	v_mfma_f32_16x16x32_bf16 v[58:61], v[138:141], v[176:179], v[58:61]
	v_mfma_f32_16x16x32_bf16 v[58:61], v[142:145], v[180:183], v[58:61]
	v_mfma_f32_16x16x32_bf16 v[54:57], v[154:157], v[176:179], v[54:57]
	v_mfma_f32_16x16x32_bf16 v[54:57], v[164:167], v[180:183], v[54:57]
	v_mfma_f32_16x16x32_bf16 v[50:53], v[168:171], v[176:179], v[50:53]
	v_mfma_f32_16x16x32_bf16 v[50:53], v[172:175], v[180:183], v[50:53]
	v_mfma_f32_16x16x32_bf16 v[46:49], v[130:133], v[184:187], v[46:49]
	v_mfma_f32_16x16x32_bf16 v[46:49], v[134:137], v[188:191], v[46:49]
	v_mfma_f32_16x16x32_bf16 v[42:45], v[138:141], v[184:187], v[42:45]
	v_mfma_f32_16x16x32_bf16 v[42:45], v[142:145], v[188:191], v[42:45]
	v_mfma_f32_16x16x32_bf16 v[38:41], v[154:157], v[184:187], v[38:41]
	v_mfma_f32_16x16x32_bf16 v[38:41], v[164:167], v[188:191], v[38:41]
	v_mfma_f32_16x16x32_bf16 v[34:37], v[168:171], v[184:187], v[34:37]
	v_mfma_f32_16x16x32_bf16 v[34:37], v[172:175], v[188:191], v[34:37]
	v_mfma_f32_16x16x32_bf16 v[30:33], v[130:133], v[192:195], v[30:33]
	v_mfma_f32_16x16x32_bf16 v[30:33], v[134:137], v[196:199], v[30:33]
	v_mfma_f32_16x16x32_bf16 v[26:29], v[138:141], v[192:195], v[26:29]
	v_mfma_f32_16x16x32_bf16 v[26:29], v[142:145], v[196:199], v[26:29]
	v_mfma_f32_16x16x32_bf16 v[22:25], v[154:157], v[192:195], v[22:25]
	v_mfma_f32_16x16x32_bf16 v[22:25], v[164:167], v[196:199], v[22:25]
	v_mfma_f32_16x16x32_bf16 v[18:21], v[168:171], v[192:195], v[18:21]
	v_mfma_f32_16x16x32_bf16 v[18:21], v[172:175], v[196:199], v[18:21]
	v_mfma_f32_16x16x32_bf16 v[14:17], v[130:133], v[200:203], v[14:17]
	v_mfma_f32_16x16x32_bf16 v[14:17], v[134:137], v[204:207], v[14:17]
	v_mfma_f32_16x16x32_bf16 v[10:13], v[138:141], v[200:203], v[10:13]
	v_mfma_f32_16x16x32_bf16 v[10:13], v[142:145], v[204:207], v[10:13]
	v_mfma_f32_16x16x32_bf16 v[6:9], v[154:157], v[200:203], v[6:9]
	v_mfma_f32_16x16x32_bf16 v[6:9], v[164:167], v[204:207], v[6:9]
	v_mfma_f32_16x16x32_bf16 v[2:5], v[168:171], v[200:203], v[2:5]
	v_mfma_f32_16x16x32_bf16 v[2:5], v[172:175], v[204:207], v[2:5]
	s_setprio 0
	s_barrier
	s_add_i32 s89, s89, 2
	s_cmp_ge_i32 s89, s63
	s_mov_b32 s6, s90
	s_cbranch_scc0 .LBB0_1020
	s_and_b64 vcc, exec, s[54:55]
	s_cbranch_vccz .LBB0_1023

.LBB0_1035:
	ds_read_b128 v[140:143], v134
	ds_read_b128 v[148:151], v134 offset:1024
	ds_read_b128 v[152:155], v134 offset:2048
	ds_read_b128 v[156:159], v134 offset:3072
	ds_read_b128 v[160:163], v135
	ds_read_b128 v[164:167], v135 offset:1024
	ds_read_b128 v[168:171], v135 offset:2048
	ds_read_b128 v[172:175], v135 offset:3072
	s_add_i32 s73, s70, 0xfffb8080
	s_cmp_eq_u32 s53, s72
	s_cselect_b32 s73, s68, s73
	s_cselect_b32 s75, s69, s71
	s_add_i32 s74, s73, 0x80
	s_add_i32 s76, s70, 0xfffe8000
	s_mov_b32 m0, s54
	ds_read_b128 v[176:179], v136
	ds_read_b128 v[180:183], v136 offset:1024
	ds_read_b128 v[184:187], v136 offset:2048
	ds_read_b128 v[188:191], v136 offset:3072
	ds_read_b128 v[192:195], v136 offset:4096
	ds_read_b128 v[196:199], v136 offset:5120
	ds_read_b128 v[200:203], v136 offset:6144
	ds_read_b128 v[204:207], v136 offset:7168
	buffer_load_dwordx4 v132, s[12:15], s76 offen lds
	s_mov_b32 m0, s55
	s_nop 0
	buffer_load_dwordx4 v132, s[12:15], s70 offen lds
	s_waitcnt vmcnt(8)
	s_waitcnt lgkmcnt(0)
	s_setprio 1
	v_mfma_f32_16x16x32_bf16 v[126:129], v[140:143], v[176:179], v[126:129]
	s_barrier
	v_mfma_f32_16x16x32_bf16 v[126:129], v[148:151], v[180:183], v[126:129]
	v_mfma_f32_16x16x32_bf16 v[122:125], v[152:155], v[176:179], v[122:125]
	v_mfma_f32_16x16x32_bf16 v[122:125], v[156:159], v[180:183], v[122:125]
	v_mfma_f32_16x16x32_bf16 v[118:121], v[160:163], v[176:179], v[118:121]
	v_mfma_f32_16x16x32_bf16 v[118:121], v[164:167], v[180:183], v[118:121]
	v_mfma_f32_16x16x32_bf16 v[114:117], v[168:171], v[176:179], v[114:117]
	v_mfma_f32_16x16x32_bf16 v[114:117], v[172:175], v[180:183], v[114:117]
	v_mfma_f32_16x16x32_bf16 v[110:113], v[140:143], v[184:187], v[110:113]
	v_mfma_f32_16x16x32_bf16 v[110:113], v[148:151], v[188:191], v[110:113]
	v_mfma_f32_16x16x32_bf16 v[106:109], v[152:155], v[184:187], v[106:109]
	v_mfma_f32_16x16x32_bf16 v[106:109], v[156:159], v[188:191], v[106:109]
	v_mfma_f32_16x16x32_bf16 v[102:105], v[160:163], v[184:187], v[102:105]
	v_mfma_f32_16x16x32_bf16 v[102:105], v[164:167], v[188:191], v[102:105]
	v_mfma_f32_16x16x32_bf16 v[98:101], v[168:171], v[184:187], v[98:101]
	v_mfma_f32_16x16x32_bf16 v[98:101], v[172:175], v[188:191], v[98:101]
	v_mfma_f32_16x16x32_bf16 v[94:97], v[140:143], v[192:195], v[94:97]
	v_mfma_f32_16x16x32_bf16 v[94:97], v[148:151], v[196:199], v[94:97]
	v_mfma_f32_16x16x32_bf16 v[90:93], v[152:155], v[192:195], v[90:93]
	v_mfma_f32_16x16x32_bf16 v[90:93], v[156:159], v[196:199], v[90:93]
	v_mfma_f32_16x16x32_bf16 v[86:89], v[160:163], v[192:195], v[86:89]
	v_mfma_f32_16x16x32_bf16 v[86:89], v[164:167], v[196:199], v[86:89]
	v_mfma_f32_16x16x32_bf16 v[82:85], v[168:171], v[192:195], v[82:85]
	v_mfma_f32_16x16x32_bf16 v[82:85], v[172:175], v[196:199], v[82:85]
	v_mfma_f32_16x16x32_bf16 v[78:81], v[140:143], v[200:203], v[78:81]
	v_mfma_f32_16x16x32_bf16 v[78:81], v[148:151], v[204:207], v[78:81]
	v_mfma_f32_16x16x32_bf16 v[74:77], v[152:155], v[200:203], v[74:77]
	v_mfma_f32_16x16x32_bf16 v[74:77], v[156:159], v[204:207], v[74:77]
	v_mfma_f32_16x16x32_bf16 v[70:73], v[160:163], v[200:203], v[70:73]
	v_mfma_f32_16x16x32_bf16 v[70:73], v[164:167], v[204:207], v[70:73]
	v_mfma_f32_16x16x32_bf16 v[66:69], v[168:171], v[200:203], v[66:69]
	v_mfma_f32_16x16x32_bf16 v[66:69], v[172:175], v[204:207], v[66:69]
	s_setprio 0
	s_barrier
	s_mov_b32 m0, s30
	ds_read_b128 v[176:179], v136 offset:16384
	ds_read_b128 v[180:183], v136 offset:17408
	ds_read_b128 v[184:187], v136 offset:18432
	ds_read_b128 v[188:191], v136 offset:19456
	ds_read_b128 v[192:195], v136 offset:20480
	ds_read_b128 v[196:199], v136 offset:21504
	ds_read_b128 v[200:203], v136 offset:22528
	ds_read_b128 v[204:207], v136 offset:23552
	buffer_load_dwordx4 v133, s[16:19], s75 offen lds
	s_add_i32 s76, s75, 0x200000
	s_mov_b32 m0, s31
	s_nop 0
	buffer_load_dwordx4 v133, s[16:19], s76 offen lds
	s_add_i32 s76, s75, 0x400000
	s_mov_b32 m0, s35
	s_nop 0
	buffer_load_dwordx4 v133, s[16:19], s76 offen lds
	s_add_i32 s76, s75, 0x600000
	s_mov_b32 m0, s42
	s_nop 0
	buffer_load_dwordx4 v133, s[16:19], s76 offen lds
	s_mov_b32 m0, s27
	s_add_i32 s76, s73, 0x18000
	buffer_load_dwordx4 v132, s[12:15], s73 offen lds
	s_mov_b32 m0, s43
	s_nop 0
	buffer_load_dwordx4 v132, s[12:15], s76 offen lds
	s_waitcnt vmcnt(8)
	s_waitcnt lgkmcnt(0)
	s_setprio 1
	v_mfma_f32_16x16x32_bf16 v[62:65], v[140:143], v[176:179], v[62:65]
	s_barrier
	v_mfma_f32_16x16x32_bf16 v[62:65], v[148:151], v[180:183], v[62:65]
	v_mfma_f32_16x16x32_bf16 v[58:61], v[152:155], v[176:179], v[58:61]
	v_mfma_f32_16x16x32_bf16 v[58:61], v[156:159], v[180:183], v[58:61]
	v_mfma_f32_16x16x32_bf16 v[54:57], v[160:163], v[176:179], v[54:57]
	v_mfma_f32_16x16x32_bf16 v[54:57], v[164:167], v[180:183], v[54:57]
	v_mfma_f32_16x16x32_bf16 v[50:53], v[168:171], v[176:179], v[50:53]
	v_mfma_f32_16x16x32_bf16 v[50:53], v[172:175], v[180:183], v[50:53]
	v_mfma_f32_16x16x32_bf16 v[46:49], v[140:143], v[184:187], v[46:49]
	v_mfma_f32_16x16x32_bf16 v[46:49], v[148:151], v[188:191], v[46:49]
	v_mfma_f32_16x16x32_bf16 v[42:45], v[152:155], v[184:187], v[42:45]
	v_mfma_f32_16x16x32_bf16 v[42:45], v[156:159], v[188:191], v[42:45]
	v_mfma_f32_16x16x32_bf16 v[38:41], v[160:163], v[184:187], v[38:41]
	v_mfma_f32_16x16x32_bf16 v[38:41], v[164:167], v[188:191], v[38:41]
	v_mfma_f32_16x16x32_bf16 v[34:37], v[168:171], v[184:187], v[34:37]
	v_mfma_f32_16x16x32_bf16 v[34:37], v[172:175], v[188:191], v[34:37]
	v_mfma_f32_16x16x32_bf16 v[30:33], v[140:143], v[192:195], v[30:33]
	v_mfma_f32_16x16x32_bf16 v[30:33], v[148:151], v[196:199], v[30:33]
	v_mfma_f32_16x16x32_bf16 v[26:29], v[152:155], v[192:195], v[26:29]
	v_mfma_f32_16x16x32_bf16 v[26:29], v[156:159], v[196:199], v[26:29]
	v_mfma_f32_16x16x32_bf16 v[22:25], v[160:163], v[192:195], v[22:25]
	v_mfma_f32_16x16x32_bf16 v[22:25], v[164:167], v[196:199], v[22:25]
	v_mfma_f32_16x16x32_bf16 v[18:21], v[168:171], v[192:195], v[18:21]
	v_mfma_f32_16x16x32_bf16 v[18:21], v[172:175], v[196:199], v[18:21]
	v_mfma_f32_16x16x32_bf16 v[14:17], v[140:143], v[200:203], v[14:17]
	v_mfma_f32_16x16x32_bf16 v[14:17], v[148:151], v[204:207], v[14:17]
	v_mfma_f32_16x16x32_bf16 v[10:13], v[152:155], v[200:203], v[10:13]
	v_mfma_f32_16x16x32_bf16 v[10:13], v[156:159], v[204:207], v[10:13]
	v_mfma_f32_16x16x32_bf16 v[6:9], v[160:163], v[200:203], v[6:9]
	v_mfma_f32_16x16x32_bf16 v[6:9], v[164:167], v[204:207], v[6:9]
	v_mfma_f32_16x16x32_bf16 v[2:5], v[168:171], v[200:203], v[2:5]
	v_mfma_f32_16x16x32_bf16 v[2:5], v[172:175], v[204:207], v[2:5]
	s_setprio 0
	s_barrier
	ds_read_b128 v[140:143], v137
	ds_read_b128 v[148:151], v137 offset:1024
	ds_read_b128 v[152:155], v137 offset:2048
	ds_read_b128 v[156:159], v137 offset:3072
	ds_read_b128 v[160:163], v138
	ds_read_b128 v[164:167], v138 offset:1024
	ds_read_b128 v[168:171], v138 offset:2048
	ds_read_b128 v[172:175], v138 offset:3072
	s_mov_b32 m0, s44
	s_add_i32 s76, s73, 0x30000
	ds_read_b128 v[176:179], v136 offset:32768
	ds_read_b128 v[180:183], v136 offset:33792
	ds_read_b128 v[184:187], v136 offset:34816
	ds_read_b128 v[188:191], v136 offset:35840
	ds_read_b128 v[192:195], v136 offset:36864
	ds_read_b128 v[196:199], v136 offset:37888
	ds_read_b128 v[200:203], v136 offset:38912
	ds_read_b128 v[204:207], v136 offset:39936
	buffer_load_dwordx4 v132, s[12:15], s76 offen lds
	s_add_i32 s76, s73, 0x48000
	s_mov_b32 m0, s45
	s_nop 0
	buffer_load_dwordx4 v132, s[12:15], s76 offen lds
	s_waitcnt vmcnt(8)
	s_waitcnt lgkmcnt(0)
	s_setprio 1
	v_mfma_f32_16x16x32_bf16 v[126:129], v[140:143], v[176:179], v[126:129]
	s_barrier
	v_mfma_f32_16x16x32_bf16 v[126:129], v[148:151], v[180:183], v[126:129]
	v_mfma_f32_16x16x32_bf16 v[122:125], v[152:155], v[176:179], v[122:125]
	v_mfma_f32_16x16x32_bf16 v[122:125], v[156:159], v[180:183], v[122:125]
	v_mfma_f32_16x16x32_bf16 v[118:121], v[160:163], v[176:179], v[118:121]
	v_mfma_f32_16x16x32_bf16 v[118:121], v[164:167], v[180:183], v[118:121]
	v_mfma_f32_16x16x32_bf16 v[114:117], v[168:171], v[176:179], v[114:117]
	v_mfma_f32_16x16x32_bf16 v[114:117], v[172:175], v[180:183], v[114:117]
	v_mfma_f32_16x16x32_bf16 v[110:113], v[140:143], v[184:187], v[110:113]
	v_mfma_f32_16x16x32_bf16 v[110:113], v[148:151], v[188:191], v[110:113]
	v_mfma_f32_16x16x32_bf16 v[106:109], v[152:155], v[184:187], v[106:109]
	v_mfma_f32_16x16x32_bf16 v[106:109], v[156:159], v[188:191], v[106:109]
	v_mfma_f32_16x16x32_bf16 v[102:105], v[160:163], v[184:187], v[102:105]
	v_mfma_f32_16x16x32_bf16 v[102:105], v[164:167], v[188:191], v[102:105]
	v_mfma_f32_16x16x32_bf16 v[98:101], v[168:171], v[184:187], v[98:101]
	v_mfma_f32_16x16x32_bf16 v[98:101], v[172:175], v[188:191], v[98:101]
	v_mfma_f32_16x16x32_bf16 v[94:97], v[140:143], v[192:195], v[94:97]
	v_mfma_f32_16x16x32_bf16 v[94:97], v[148:151], v[196:199], v[94:97]
	v_mfma_f32_16x16x32_bf16 v[90:93], v[152:155], v[192:195], v[90:93]
	v_mfma_f32_16x16x32_bf16 v[90:93], v[156:159], v[196:199], v[90:93]
	v_mfma_f32_16x16x32_bf16 v[86:89], v[160:163], v[192:195], v[86:89]
	v_mfma_f32_16x16x32_bf16 v[86:89], v[164:167], v[196:199], v[86:89]
	v_mfma_f32_16x16x32_bf16 v[82:85], v[168:171], v[192:195], v[82:85]
	v_mfma_f32_16x16x32_bf16 v[82:85], v[172:175], v[196:199], v[82:85]
	v_mfma_f32_16x16x32_bf16 v[78:81], v[140:143], v[200:203], v[78:81]
	v_mfma_f32_16x16x32_bf16 v[78:81], v[148:151], v[204:207], v[78:81]
	v_mfma_f32_16x16x32_bf16 v[74:77], v[152:155], v[200:203], v[74:77]
	v_mfma_f32_16x16x32_bf16 v[74:77], v[156:159], v[204:207], v[74:77]
	v_mfma_f32_16x16x32_bf16 v[70:73], v[160:163], v[200:203], v[70:73]
	v_mfma_f32_16x16x32_bf16 v[70:73], v[164:167], v[204:207], v[70:73]
	v_mfma_f32_16x16x32_bf16 v[66:69], v[168:171], v[200:203], v[66:69]
	v_mfma_f32_16x16x32_bf16 v[66:69], v[172:175], v[204:207], v[66:69]
	s_setprio 0
	s_barrier
	s_mov_b32 m0, s46
	s_add_i32 s76, s75, 0x80
	ds_read_b128 v[176:179], v136 offset:49152
	ds_read_b128 v[180:183], v136 offset:50176
	ds_read_b128 v[184:187], v136 offset:51200
	ds_read_b128 v[188:191], v136 offset:52224
	ds_read_b128 v[192:195], v136 offset:53248
	ds_read_b128 v[196:199], v136 offset:54272
	ds_read_b128 v[200:203], v136 offset:55296
	ds_read_b128 v[204:207], v136 offset:56320
	buffer_load_dwordx4 v133, s[16:19], s76 offen lds
	s_add_i32 s76, s75, 0x200080
	s_mov_b32 m0, s47
	s_add_i32 s73, s73, 0x18080
	buffer_load_dwordx4 v133, s[16:19], s76 offen lds
	s_add_i32 s76, s75, 0x400080
	s_mov_b32 m0, s50
	s_add_i32 s75, s75, 0x600080
	buffer_load_dwordx4 v133, s[16:19], s76 offen lds
	s_mov_b32 m0, s51
	s_nop 0
	buffer_load_dwordx4 v133, s[16:19], s75 offen lds
	s_mov_b32 m0, s48
	s_nop 0
	buffer_load_dwordx4 v132, s[12:15], s74 offen lds
	s_mov_b32 m0, s49
	s_nop 0
	buffer_load_dwordx4 v132, s[12:15], s73 offen lds
	s_waitcnt vmcnt(8)
	s_waitcnt lgkmcnt(0)
	s_setprio 1
	v_mfma_f32_16x16x32_bf16 v[62:65], v[140:143], v[176:179], v[62:65]
	s_barrier
	v_mfma_f32_16x16x32_bf16 v[62:65], v[148:151], v[180:183], v[62:65]
	v_mfma_f32_16x16x32_bf16 v[58:61], v[152:155], v[176:179], v[58:61]
	v_mfma_f32_16x16x32_bf16 v[58:61], v[156:159], v[180:183], v[58:61]
	v_mfma_f32_16x16x32_bf16 v[54:57], v[160:163], v[176:179], v[54:57]
	v_mfma_f32_16x16x32_bf16 v[54:57], v[164:167], v[180:183], v[54:57]
	v_mfma_f32_16x16x32_bf16 v[50:53], v[168:171], v[176:179], v[50:53]
	v_mfma_f32_16x16x32_bf16 v[50:53], v[172:175], v[180:183], v[50:53]
	v_mfma_f32_16x16x32_bf16 v[46:49], v[140:143], v[184:187], v[46:49]
	v_mfma_f32_16x16x32_bf16 v[46:49], v[148:151], v[188:191], v[46:49]
	v_mfma_f32_16x16x32_bf16 v[42:45], v[152:155], v[184:187], v[42:45]
	v_mfma_f32_16x16x32_bf16 v[42:45], v[156:159], v[188:191], v[42:45]
	v_mfma_f32_16x16x32_bf16 v[38:41], v[160:163], v[184:187], v[38:41]
	v_mfma_f32_16x16x32_bf16 v[38:41], v[164:167], v[188:191], v[38:41]
	v_mfma_f32_16x16x32_bf16 v[34:37], v[168:171], v[184:187], v[34:37]
	v_mfma_f32_16x16x32_bf16 v[34:37], v[172:175], v[188:191], v[34:37]
	v_mfma_f32_16x16x32_bf16 v[30:33], v[140:143], v[192:195], v[30:33]
	v_mfma_f32_16x16x32_bf16 v[30:33], v[148:151], v[196:199], v[30:33]
	v_mfma_f32_16x16x32_bf16 v[26:29], v[152:155], v[192:195], v[26:29]
	v_mfma_f32_16x16x32_bf16 v[26:29], v[156:159], v[196:199], v[26:29]
	v_mfma_f32_16x16x32_bf16 v[22:25], v[160:163], v[192:195], v[22:25]
	v_mfma_f32_16x16x32_bf16 v[22:25], v[164:167], v[196:199], v[22:25]
	v_mfma_f32_16x16x32_bf16 v[18:21], v[168:171], v[192:195], v[18:21]
	v_mfma_f32_16x16x32_bf16 v[18:21], v[172:175], v[196:199], v[18:21]
	v_mfma_f32_16x16x32_bf16 v[14:17], v[140:143], v[200:203], v[14:17]
	v_mfma_f32_16x16x32_bf16 v[14:17], v[148:151], v[204:207], v[14:17]
	v_mfma_f32_16x16x32_bf16 v[10:13], v[152:155], v[200:203], v[10:13]
	v_mfma_f32_16x16x32_bf16 v[10:13], v[156:159], v[204:207], v[10:13]
	v_mfma_f32_16x16x32_bf16 v[6:9], v[160:163], v[200:203], v[6:9]
	v_mfma_f32_16x16x32_bf16 v[6:9], v[164:167], v[204:207], v[6:9]
	v_mfma_f32_16x16x32_bf16 v[2:5], v[168:171], v[200:203], v[2:5]
	v_mfma_f32_16x16x32_bf16 v[2:5], v[172:175], v[204:207], v[2:5]
	s_setprio 0
	s_barrier
	s_add_i32 s72, s72, 2
	s_addk_i32 s70, 0x100
	s_addk_i32 s71, 0x100
	s_cmp_ge_i32 s72, s21
	s_cbranch_scc0 .LBB0_1035

.LBB0_1050:
	ds_read_b128 v[132:135], v142
	ds_read_b128 v[136:139], v142 offset:1024
	ds_read_b128 v[148:151], v142 offset:2048
	ds_read_b128 v[152:155], v142 offset:3072
	ds_read_b128 v[156:159], v143
	ds_read_b128 v[160:163], v143 offset:1024
	ds_read_b128 v[164:167], v143 offset:2048
	ds_read_b128 v[168:171], v143 offset:3072
	s_add_i32 s18, s61, 0xfff40080
	s_cmp_eq_u32 s54, s62
	s_cselect_b32 s64, s35, s18
	s_add_i32 s63, s64, 0x80
	s_add_i32 s18, s61, 0xfffc0000
	s_mov_b32 m0, s55
	ds_read_b128 v[172:175], v144
	ds_read_b128 v[176:179], v144 offset:1024
	ds_read_b128 v[180:183], v144 offset:2048
	ds_read_b128 v[184:187], v144 offset:3072
	ds_read_b128 v[188:191], v144 offset:4096
	ds_read_b128 v[192:195], v144 offset:5120
	ds_read_b128 v[196:199], v144 offset:6144
	ds_read_b128 v[200:203], v144 offset:7168
	buffer_load_dwordx4 v140, s[12:15], s18 offen lds
	s_mov_b32 m0, s56
	s_nop 0
	buffer_load_dwordx4 v140, s[12:15], s61 offen lds
	s_waitcnt vmcnt(8)
	s_waitcnt lgkmcnt(0)
	s_setprio 1
	v_mfma_f32_16x16x32_bf16 v[126:129], v[132:135], v[172:175], v[126:129]
	s_barrier
	v_mfma_f32_16x16x32_bf16 v[126:129], v[136:139], v[176:179], v[126:129]
	v_mfma_f32_16x16x32_bf16 v[122:125], v[148:151], v[172:175], v[122:125]
	v_mfma_f32_16x16x32_bf16 v[122:125], v[152:155], v[176:179], v[122:125]
	v_mfma_f32_16x16x32_bf16 v[118:121], v[156:159], v[172:175], v[118:121]
	v_mfma_f32_16x16x32_bf16 v[118:121], v[160:163], v[176:179], v[118:121]
	v_mfma_f32_16x16x32_bf16 v[114:117], v[164:167], v[172:175], v[114:117]
	v_mfma_f32_16x16x32_bf16 v[114:117], v[168:171], v[176:179], v[114:117]
	v_mfma_f32_16x16x32_bf16 v[110:113], v[132:135], v[180:183], v[110:113]
	v_mfma_f32_16x16x32_bf16 v[110:113], v[136:139], v[184:187], v[110:113]
	v_mfma_f32_16x16x32_bf16 v[106:109], v[148:151], v[180:183], v[106:109]
	v_mfma_f32_16x16x32_bf16 v[106:109], v[152:155], v[184:187], v[106:109]
	v_mfma_f32_16x16x32_bf16 v[102:105], v[156:159], v[180:183], v[102:105]
	v_mfma_f32_16x16x32_bf16 v[102:105], v[160:163], v[184:187], v[102:105]
	v_mfma_f32_16x16x32_bf16 v[98:101], v[164:167], v[180:183], v[98:101]
	v_mfma_f32_16x16x32_bf16 v[98:101], v[168:171], v[184:187], v[98:101]
	v_mfma_f32_16x16x32_bf16 v[94:97], v[132:135], v[188:191], v[94:97]
	v_mfma_f32_16x16x32_bf16 v[94:97], v[136:139], v[192:195], v[94:97]
	v_mfma_f32_16x16x32_bf16 v[90:93], v[148:151], v[188:191], v[90:93]
	v_mfma_f32_16x16x32_bf16 v[90:93], v[152:155], v[192:195], v[90:93]
	v_mfma_f32_16x16x32_bf16 v[86:89], v[156:159], v[188:191], v[86:89]
	v_mfma_f32_16x16x32_bf16 v[86:89], v[160:163], v[192:195], v[86:89]
	v_mfma_f32_16x16x32_bf16 v[82:85], v[164:167], v[188:191], v[82:85]
	v_mfma_f32_16x16x32_bf16 v[82:85], v[168:171], v[192:195], v[82:85]
	v_mfma_f32_16x16x32_bf16 v[78:81], v[132:135], v[196:199], v[78:81]
	v_mfma_f32_16x16x32_bf16 v[78:81], v[136:139], v[200:203], v[78:81]
	v_mfma_f32_16x16x32_bf16 v[74:77], v[148:151], v[196:199], v[74:77]
	v_mfma_f32_16x16x32_bf16 v[74:77], v[152:155], v[200:203], v[74:77]
	v_mfma_f32_16x16x32_bf16 v[70:73], v[156:159], v[196:199], v[70:73]
	v_mfma_f32_16x16x32_bf16 v[70:73], v[160:163], v[200:203], v[70:73]
	v_mfma_f32_16x16x32_bf16 v[66:69], v[164:167], v[196:199], v[66:69]
	v_mfma_f32_16x16x32_bf16 v[66:69], v[168:171], v[200:203], v[66:69]
	s_setprio 0
	s_barrier
	s_mov_b32 m0, s25
	s_mov_b32 s18, s14
	s_mov_b32 s19, s15
	ds_read_b128 v[172:175], v144 offset:16384
	ds_read_b128 v[176:179], v144 offset:17408
	ds_read_b128 v[180:183], v144 offset:18432
	ds_read_b128 v[184:187], v144 offset:19456
	ds_read_b128 v[188:191], v144 offset:20480
	ds_read_b128 v[192:195], v144 offset:21504
	ds_read_b128 v[196:199], v144 offset:22528
	ds_read_b128 v[200:203], v144 offset:23552
	buffer_load_dwordx4 v141, s[16:19], s64 offen lds
	s_add_i32 s65, s64, 0x40000
	s_mov_b32 m0, s27
	s_add_i32 s66, s64, 0x80000
	buffer_load_dwordx4 v141, s[16:19], s65 offen lds
	s_mov_b32 m0, s30
	s_add_i32 s67, s64, 0xc0000
	buffer_load_dwordx4 v141, s[16:19], s66 offen lds
	s_mov_b32 m0, s31
	s_nop 0
	buffer_load_dwordx4 v141, s[16:19], s67 offen lds
	s_mov_b32 m0, s21
	s_nop 0
	buffer_load_dwordx4 v140, s[12:15], s64 offen lds
	s_mov_b32 m0, s38
	s_nop 0
	buffer_load_dwordx4 v140, s[12:15], s65 offen lds
	s_waitcnt vmcnt(8)
	s_waitcnt lgkmcnt(0)
	s_setprio 1
	v_mfma_f32_16x16x32_bf16 v[62:65], v[132:135], v[172:175], v[62:65]
	s_barrier
	v_mfma_f32_16x16x32_bf16 v[62:65], v[136:139], v[176:179], v[62:65]
	v_mfma_f32_16x16x32_bf16 v[58:61], v[148:151], v[172:175], v[58:61]
	v_mfma_f32_16x16x32_bf16 v[58:61], v[152:155], v[176:179], v[58:61]
	v_mfma_f32_16x16x32_bf16 v[54:57], v[156:159], v[172:175], v[54:57]
	v_mfma_f32_16x16x32_bf16 v[54:57], v[160:163], v[176:179], v[54:57]
	v_mfma_f32_16x16x32_bf16 v[50:53], v[164:167], v[172:175], v[50:53]
	v_mfma_f32_16x16x32_bf16 v[50:53], v[168:171], v[176:179], v[50:53]
	v_mfma_f32_16x16x32_bf16 v[46:49], v[132:135], v[180:183], v[46:49]
	v_mfma_f32_16x16x32_bf16 v[46:49], v[136:139], v[184:187], v[46:49]
	v_mfma_f32_16x16x32_bf16 v[42:45], v[148:151], v[180:183], v[42:45]
	v_mfma_f32_16x16x32_bf16 v[42:45], v[152:155], v[184:187], v[42:45]
	v_mfma_f32_16x16x32_bf16 v[38:41], v[156:159], v[180:183], v[38:41]
	v_mfma_f32_16x16x32_bf16 v[38:41], v[160:163], v[184:187], v[38:41]
	v_mfma_f32_16x16x32_bf16 v[34:37], v[164:167], v[180:183], v[34:37]
	v_mfma_f32_16x16x32_bf16 v[34:37], v[168:171], v[184:187], v[34:37]
	v_mfma_f32_16x16x32_bf16 v[30:33], v[132:135], v[188:191], v[30:33]
	v_mfma_f32_16x16x32_bf16 v[30:33], v[136:139], v[192:195], v[30:33]
	v_mfma_f32_16x16x32_bf16 v[26:29], v[148:151], v[188:191], v[26:29]
	v_mfma_f32_16x16x32_bf16 v[26:29], v[152:155], v[192:195], v[26:29]
	v_mfma_f32_16x16x32_bf16 v[22:25], v[156:159], v[188:191], v[22:25]
	v_mfma_f32_16x16x32_bf16 v[22:25], v[160:163], v[192:195], v[22:25]
	v_mfma_f32_16x16x32_bf16 v[18:21], v[164:167], v[188:191], v[18:21]
	v_mfma_f32_16x16x32_bf16 v[18:21], v[168:171], v[192:195], v[18:21]
	v_mfma_f32_16x16x32_bf16 v[14:17], v[132:135], v[196:199], v[14:17]
	v_mfma_f32_16x16x32_bf16 v[14:17], v[136:139], v[200:203], v[14:17]
	v_mfma_f32_16x16x32_bf16 v[10:13], v[148:151], v[196:199], v[10:13]
	v_mfma_f32_16x16x32_bf16 v[10:13], v[152:155], v[200:203], v[10:13]
	v_mfma_f32_16x16x32_bf16 v[6:9], v[156:159], v[196:199], v[6:9]
	v_mfma_f32_16x16x32_bf16 v[6:9], v[160:163], v[200:203], v[6:9]
	v_mfma_f32_16x16x32_bf16 v[2:5], v[164:167], v[196:199], v[2:5]
	v_mfma_f32_16x16x32_bf16 v[2:5], v[168:171], v[200:203], v[2:5]
	s_setprio 0
	s_barrier
	ds_read_b128 v[132:135], v145
	ds_read_b128 v[136:139], v145 offset:1024
	ds_read_b128 v[148:151], v145 offset:2048
	ds_read_b128 v[152:155], v145 offset:3072
	ds_read_b128 v[156:159], v147
	ds_read_b128 v[160:163], v147 offset:1024
	ds_read_b128 v[164:167], v147 offset:2048
	ds_read_b128 v[168:171], v147 offset:3072
	s_mov_b32 m0, s39
	ds_read_b128 v[172:175], v144 offset:32768
	ds_read_b128 v[176:179], v144 offset:33792
	ds_read_b128 v[180:183], v144 offset:34816
	ds_read_b128 v[184:187], v144 offset:35840
	ds_read_b128 v[188:191], v144 offset:36864
	ds_read_b128 v[192:195], v144 offset:37888
	ds_read_b128 v[196:199], v144 offset:38912
	ds_read_b128 v[200:203], v144 offset:39936
	buffer_load_dwordx4 v140, s[12:15], s66 offen lds
	s_mov_b32 m0, s40
	s_nop 0
	buffer_load_dwordx4 v140, s[12:15], s67 offen lds
	s_waitcnt vmcnt(8)
	s_waitcnt lgkmcnt(0)
	s_setprio 1
	v_mfma_f32_16x16x32_bf16 v[126:129], v[132:135], v[172:175], v[126:129]
	s_barrier
	v_mfma_f32_16x16x32_bf16 v[126:129], v[136:139], v[176:179], v[126:129]
	v_mfma_f32_16x16x32_bf16 v[122:125], v[148:151], v[172:175], v[122:125]
	v_mfma_f32_16x16x32_bf16 v[122:125], v[152:155], v[176:179], v[122:125]
	v_mfma_f32_16x16x32_bf16 v[118:121], v[156:159], v[172:175], v[118:121]
	v_mfma_f32_16x16x32_bf16 v[118:121], v[160:163], v[176:179], v[118:121]
	v_mfma_f32_16x16x32_bf16 v[114:117], v[164:167], v[172:175], v[114:117]
	v_mfma_f32_16x16x32_bf16 v[114:117], v[168:171], v[176:179], v[114:117]
	v_mfma_f32_16x16x32_bf16 v[110:113], v[132:135], v[180:183], v[110:113]
	v_mfma_f32_16x16x32_bf16 v[110:113], v[136:139], v[184:187], v[110:113]
	v_mfma_f32_16x16x32_bf16 v[106:109], v[148:151], v[180:183], v[106:109]
	v_mfma_f32_16x16x32_bf16 v[106:109], v[152:155], v[184:187], v[106:109]
	v_mfma_f32_16x16x32_bf16 v[102:105], v[156:159], v[180:183], v[102:105]
	v_mfma_f32_16x16x32_bf16 v[102:105], v[160:163], v[184:187], v[102:105]
	v_mfma_f32_16x16x32_bf16 v[98:101], v[164:167], v[180:183], v[98:101]
	v_mfma_f32_16x16x32_bf16 v[98:101], v[168:171], v[184:187], v[98:101]
	v_mfma_f32_16x16x32_bf16 v[94:97], v[132:135], v[188:191], v[94:97]
	v_mfma_f32_16x16x32_bf16 v[94:97], v[136:139], v[192:195], v[94:97]
	v_mfma_f32_16x16x32_bf16 v[90:93], v[148:151], v[188:191], v[90:93]
	v_mfma_f32_16x16x32_bf16 v[90:93], v[152:155], v[192:195], v[90:93]
	v_mfma_f32_16x16x32_bf16 v[86:89], v[156:159], v[188:191], v[86:89]
	v_mfma_f32_16x16x32_bf16 v[86:89], v[160:163], v[192:195], v[86:89]
	v_mfma_f32_16x16x32_bf16 v[82:85], v[164:167], v[188:191], v[82:85]
	v_mfma_f32_16x16x32_bf16 v[82:85], v[168:171], v[192:195], v[82:85]
	v_mfma_f32_16x16x32_bf16 v[78:81], v[132:135], v[196:199], v[78:81]
	v_mfma_f32_16x16x32_bf16 v[78:81], v[136:139], v[200:203], v[78:81]
	v_mfma_f32_16x16x32_bf16 v[74:77], v[148:151], v[196:199], v[74:77]
	v_mfma_f32_16x16x32_bf16 v[74:77], v[152:155], v[200:203], v[74:77]
	v_mfma_f32_16x16x32_bf16 v[70:73], v[156:159], v[196:199], v[70:73]
	v_mfma_f32_16x16x32_bf16 v[70:73], v[160:163], v[200:203], v[70:73]
	v_mfma_f32_16x16x32_bf16 v[66:69], v[164:167], v[196:199], v[66:69]
	v_mfma_f32_16x16x32_bf16 v[66:69], v[168:171], v[200:203], v[66:69]
	s_setprio 0
	s_barrier
	s_mov_b32 m0, s48
	ds_read_b128 v[172:175], v144 offset:49152
	ds_read_b128 v[176:179], v144 offset:50176
	ds_read_b128 v[180:183], v144 offset:51200
	ds_read_b128 v[184:187], v144 offset:52224
	ds_read_b128 v[188:191], v144 offset:53248
	ds_read_b128 v[192:195], v144 offset:54272
	ds_read_b128 v[196:199], v144 offset:55296
	ds_read_b128 v[200:203], v144 offset:56320
	buffer_load_dwordx4 v141, s[16:19], s63 offen lds
	s_add_i32 s65, s64, 0x40080
	s_mov_b32 m0, s49
	s_add_i32 s66, s64, 0x80080
	buffer_load_dwordx4 v141, s[16:19], s65 offen lds
	s_mov_b32 m0, s52
	s_add_i32 s64, s64, 0xc0080
	buffer_load_dwordx4 v141, s[16:19], s66 offen lds
	s_mov_b32 m0, s53
	s_nop 0
	buffer_load_dwordx4 v141, s[16:19], s64 offen lds
	s_mov_b32 m0, s50
	s_nop 0
	buffer_load_dwordx4 v140, s[12:15], s63 offen lds
	s_mov_b32 m0, s51
	s_nop 0
	buffer_load_dwordx4 v140, s[12:15], s65 offen lds
	s_waitcnt vmcnt(8)
	s_waitcnt lgkmcnt(0)
	s_setprio 1
	v_mfma_f32_16x16x32_bf16 v[62:65], v[132:135], v[172:175], v[62:65]
	s_barrier
	v_mfma_f32_16x16x32_bf16 v[62:65], v[136:139], v[176:179], v[62:65]
	v_mfma_f32_16x16x32_bf16 v[58:61], v[148:151], v[172:175], v[58:61]
	v_mfma_f32_16x16x32_bf16 v[58:61], v[152:155], v[176:179], v[58:61]
	v_mfma_f32_16x16x32_bf16 v[54:57], v[156:159], v[172:175], v[54:57]
	v_mfma_f32_16x16x32_bf16 v[54:57], v[160:163], v[176:179], v[54:57]
	v_mfma_f32_16x16x32_bf16 v[50:53], v[164:167], v[172:175], v[50:53]
	v_mfma_f32_16x16x32_bf16 v[50:53], v[168:171], v[176:179], v[50:53]
	v_mfma_f32_16x16x32_bf16 v[46:49], v[132:135], v[180:183], v[46:49]
	v_mfma_f32_16x16x32_bf16 v[46:49], v[136:139], v[184:187], v[46:49]
	v_mfma_f32_16x16x32_bf16 v[42:45], v[148:151], v[180:183], v[42:45]
	v_mfma_f32_16x16x32_bf16 v[42:45], v[152:155], v[184:187], v[42:45]
	v_mfma_f32_16x16x32_bf16 v[38:41], v[156:159], v[180:183], v[38:41]
	v_mfma_f32_16x16x32_bf16 v[38:41], v[160:163], v[184:187], v[38:41]
	v_mfma_f32_16x16x32_bf16 v[34:37], v[164:167], v[180:183], v[34:37]
	v_mfma_f32_16x16x32_bf16 v[34:37], v[168:171], v[184:187], v[34:37]
	v_mfma_f32_16x16x32_bf16 v[30:33], v[132:135], v[188:191], v[30:33]
	v_mfma_f32_16x16x32_bf16 v[30:33], v[136:139], v[192:195], v[30:33]
	v_mfma_f32_16x16x32_bf16 v[26:29], v[148:151], v[188:191], v[26:29]
	v_mfma_f32_16x16x32_bf16 v[26:29], v[152:155], v[192:195], v[26:29]
	v_mfma_f32_16x16x32_bf16 v[22:25], v[156:159], v[188:191], v[22:25]
	v_mfma_f32_16x16x32_bf16 v[22:25], v[160:163], v[192:195], v[22:25]
	v_mfma_f32_16x16x32_bf16 v[18:21], v[164:167], v[188:191], v[18:21]
	v_mfma_f32_16x16x32_bf16 v[18:21], v[168:171], v[192:195], v[18:21]
	v_mfma_f32_16x16x32_bf16 v[14:17], v[132:135], v[196:199], v[14:17]
	v_mfma_f32_16x16x32_bf16 v[14:17], v[136:139], v[200:203], v[14:17]
	v_mfma_f32_16x16x32_bf16 v[10:13], v[148:151], v[196:199], v[10:13]
	v_mfma_f32_16x16x32_bf16 v[10:13], v[152:155], v[200:203], v[10:13]
	v_mfma_f32_16x16x32_bf16 v[6:9], v[156:159], v[196:199], v[6:9]
	v_mfma_f32_16x16x32_bf16 v[6:9], v[160:163], v[200:203], v[6:9]
	v_mfma_f32_16x16x32_bf16 v[2:5], v[164:167], v[196:199], v[2:5]
	v_mfma_f32_16x16x32_bf16 v[2:5], v[168:171], v[200:203], v[2:5]
	s_setprio 0
	s_barrier
	s_add_i32 s62, s62, 2
	s_addk_i32 s61, 0x100
	s_cmp_ge_i32 s62, s3
	s_cbranch_scc0 .LBB0_1050

.LBB0_1181:
	v_add_u32_e32 v2, 0x10000, v232
	ds_read_b128 v[134:137], v2
	ds_read_b128 v[138:141], v2 offset:1024
	ds_read_b128 v[142:145], v2 offset:2048
	ds_read_b128 v[146:149], v2 offset:3072
	v_add_u32_e32 v2, 0x14000, v232
	ds_read_b128 v[150:153], v2
	ds_read_b128 v[154:157], v2 offset:1024
	ds_read_b128 v[158:161], v2 offset:2048
	ds_read_b128 v[162:165], v2 offset:3072
	s_add_i32 s50, s47, s90
	s_and_b64 s[18:19], exec, s[18:19]
	s_cselect_b32 s51, s88, s50
	s_add_i32 s50, s92, 0x80
	s_or_b32 s52, s51, 0x80
	s_add_i32 s18, s89, s93
	s_add_i32 s94, s94, 0x1bfffc80
	s_cmp_lt_u32 s91, 8
	s_cselect_b32 s18, s18, s94
	s_mov_b32 m0, s74
	s_add_i32 s19, s18, 0x80000
	ds_read_b128 v[166:169], v233
	ds_read_b128 v[170:173], v233 offset:1024
	ds_read_b128 v[174:177], v233 offset:2048
	ds_read_b128 v[178:181], v233 offset:3072
	ds_read_b128 v[182:185], v233 offset:4096
	ds_read_b128 v[186:189], v233 offset:5120
	ds_read_b128 v[190:193], v233 offset:6144
	ds_read_b128 v[194:197], v233 offset:7168
	buffer_load_dwordx4 v230, s[12:15], s19 offen lds
	s_add_i32 s18, s18, 0xc0000
	s_mov_b32 m0, s75
	s_nop 0
	buffer_load_dwordx4 v230, s[12:15], s18 offen lds
	s_waitcnt vmcnt(8)
	s_waitcnt lgkmcnt(0)
	s_setprio 1
	v_mfma_f32_16x16x32_bf16 v[130:133], v[134:137], v[166:169], v[130:133]
	s_barrier
	v_mfma_f32_16x16x32_bf16 v[130:133], v[138:141], v[170:173], v[130:133]
	v_mfma_f32_16x16x32_bf16 v[126:129], v[142:145], v[166:169], v[126:129]
	v_mfma_f32_16x16x32_bf16 v[126:129], v[146:149], v[170:173], v[126:129]
	v_mfma_f32_16x16x32_bf16 v[122:125], v[150:153], v[166:169], v[122:125]
	v_mfma_f32_16x16x32_bf16 v[122:125], v[154:157], v[170:173], v[122:125]
	v_mfma_f32_16x16x32_bf16 v[118:121], v[158:161], v[166:169], v[118:121]
	v_mfma_f32_16x16x32_bf16 v[118:121], v[162:165], v[170:173], v[118:121]
	v_mfma_f32_16x16x32_bf16 v[114:117], v[134:137], v[174:177], v[114:117]
	v_mfma_f32_16x16x32_bf16 v[114:117], v[138:141], v[178:181], v[114:117]
	v_mfma_f32_16x16x32_bf16 v[110:113], v[142:145], v[174:177], v[110:113]
	v_mfma_f32_16x16x32_bf16 v[110:113], v[146:149], v[178:181], v[110:113]
	v_mfma_f32_16x16x32_bf16 v[106:109], v[150:153], v[174:177], v[106:109]
	v_mfma_f32_16x16x32_bf16 v[106:109], v[154:157], v[178:181], v[106:109]
	v_mfma_f32_16x16x32_bf16 v[102:105], v[158:161], v[174:177], v[102:105]
	v_mfma_f32_16x16x32_bf16 v[102:105], v[162:165], v[178:181], v[102:105]
	v_mfma_f32_16x16x32_bf16 v[98:101], v[134:137], v[182:185], v[98:101]
	v_mfma_f32_16x16x32_bf16 v[98:101], v[138:141], v[186:189], v[98:101]
	v_mfma_f32_16x16x32_bf16 v[94:97], v[142:145], v[182:185], v[94:97]
	v_mfma_f32_16x16x32_bf16 v[94:97], v[146:149], v[186:189], v[94:97]
	v_mfma_f32_16x16x32_bf16 v[90:93], v[150:153], v[182:185], v[90:93]
	v_mfma_f32_16x16x32_bf16 v[90:93], v[154:157], v[186:189], v[90:93]
	v_mfma_f32_16x16x32_bf16 v[86:89], v[158:161], v[182:185], v[86:89]
	v_mfma_f32_16x16x32_bf16 v[86:89], v[162:165], v[186:189], v[86:89]
	v_mfma_f32_16x16x32_bf16 v[82:85], v[134:137], v[190:193], v[82:85]
	v_mfma_f32_16x16x32_bf16 v[82:85], v[138:141], v[194:197], v[82:85]
	v_mfma_f32_16x16x32_bf16 v[78:81], v[142:145], v[190:193], v[78:81]
	v_mfma_f32_16x16x32_bf16 v[78:81], v[146:149], v[194:197], v[78:81]
	v_mfma_f32_16x16x32_bf16 v[74:77], v[150:153], v[190:193], v[74:77]
	v_mfma_f32_16x16x32_bf16 v[74:77], v[154:157], v[194:197], v[74:77]
	v_mfma_f32_16x16x32_bf16 v[70:73], v[158:161], v[190:193], v[70:73]
	v_mfma_f32_16x16x32_bf16 v[70:73], v[162:165], v[194:197], v[70:73]
	s_setprio 0
	s_barrier
	s_mov_b32 m0, s27
	s_mov_b32 s18, s14
	s_mov_b32 s19, s15
	ds_read_b128 v[166:169], v233 offset:16384
	ds_read_b128 v[170:173], v233 offset:17408
	ds_read_b128 v[174:177], v233 offset:18432
	ds_read_b128 v[178:181], v233 offset:19456
	ds_read_b128 v[182:185], v233 offset:20480
	ds_read_b128 v[186:189], v233 offset:21504
	ds_read_b128 v[190:193], v233 offset:22528
	ds_read_b128 v[194:197], v233 offset:23552
	buffer_load_dwordx4 v231, s[16:19], s51 offen lds
	s_add_i32 s53, s51, 0x18000
	s_mov_b32 m0, s30
	s_nop 0
	buffer_load_dwordx4 v231, s[16:19], s53 offen lds
	s_add_i32 s53, s51, 0x30000
	s_mov_b32 m0, s31
	s_nop 0
	buffer_load_dwordx4 v231, s[16:19], s53 offen lds
	s_add_i32 s53, s51, 0x48000
	s_mov_b32 m0, s54
	s_nop 0
	buffer_load_dwordx4 v231, s[16:19], s53 offen lds
	s_mov_b32 m0, s25
	s_add_i32 s53, s92, 0x40000
	buffer_load_dwordx4 v230, s[12:15], s92 offen lds
	s_mov_b32 m0, s55
	s_nop 0
	buffer_load_dwordx4 v230, s[12:15], s53 offen lds
	s_waitcnt vmcnt(8)
	s_waitcnt lgkmcnt(0)
	s_setprio 1
	v_mfma_f32_16x16x32_bf16 v[66:69], v[134:137], v[166:169], v[66:69]
	s_barrier
	v_mfma_f32_16x16x32_bf16 v[62:65], v[142:145], v[166:169], v[62:65]
	v_mfma_f32_16x16x32_bf16 v[50:53], v[134:137], v[174:177], v[50:53]
	v_mfma_f32_16x16x32_bf16 v[46:49], v[142:145], v[174:177], v[46:49]
	v_mfma_f32_16x16x32_bf16 v[34:37], v[134:137], v[182:185], v[34:37]
	v_mfma_f32_16x16x32_bf16 v[30:33], v[142:145], v[182:185], v[30:33]
	v_mfma_f32_16x16x32_bf16 v[18:21], v[134:137], v[190:193], v[18:21]
	v_mfma_f32_16x16x32_bf16 v[14:17], v[142:145], v[190:193], v[14:17]
	v_mfma_f32_16x16x32_bf16 v[58:61], v[150:153], v[166:169], v[58:61]
	v_mfma_f32_16x16x32_bf16 v[54:57], v[158:161], v[166:169], v[54:57]
	v_mfma_f32_16x16x32_bf16 v[42:45], v[150:153], v[174:177], v[42:45]
	v_mfma_f32_16x16x32_bf16 v[38:41], v[158:161], v[174:177], v[38:41]
	v_mfma_f32_16x16x32_bf16 v[26:29], v[150:153], v[182:185], v[26:29]
	v_mfma_f32_16x16x32_bf16 v[22:25], v[158:161], v[182:185], v[22:25]
	v_mfma_f32_16x16x32_bf16 v[10:13], v[150:153], v[190:193], v[10:13]
	v_mfma_f32_16x16x32_bf16 v[4:7], v[158:161], v[190:193], v[6:9]
	v_mfma_f32_16x16x32_bf16 v[66:69], v[138:141], v[170:173], v[66:69]
	v_mfma_f32_16x16x32_bf16 v[62:65], v[146:149], v[170:173], v[62:65]
	v_mfma_f32_16x16x32_bf16 v[50:53], v[138:141], v[178:181], v[50:53]
	v_mfma_f32_16x16x32_bf16 v[46:49], v[146:149], v[178:181], v[46:49]
	v_mfma_f32_16x16x32_bf16 v[34:37], v[138:141], v[186:189], v[34:37]
	v_mfma_f32_16x16x32_bf16 v[30:33], v[146:149], v[186:189], v[30:33]
	v_mfma_f32_16x16x32_bf16 v[18:21], v[138:141], v[194:197], v[18:21]
	v_mfma_f32_16x16x32_bf16 v[14:17], v[146:149], v[194:197], v[14:17]
	v_mfma_f32_16x16x32_bf16 v[58:61], v[154:157], v[170:173], v[58:61]
	v_mfma_f32_16x16x32_bf16 v[54:57], v[162:165], v[170:173], v[54:57]
	v_mfma_f32_16x16x32_bf16 v[42:45], v[154:157], v[178:181], v[42:45]
	v_mfma_f32_16x16x32_bf16 v[38:41], v[162:165], v[178:181], v[38:41]
	v_mfma_f32_16x16x32_bf16 v[26:29], v[154:157], v[186:189], v[26:29]
	v_mfma_f32_16x16x32_bf16 v[22:25], v[162:165], v[186:189], v[22:25]
	v_mfma_f32_16x16x32_bf16 v[10:13], v[154:157], v[194:197], v[10:13]
	v_mfma_f32_16x16x32_bf16 v[4:7], v[162:165], v[194:197], v[4:7]
	s_setprio 0
	s_barrier
	v_add_u32_e32 v2, 0x18000, v232
	ds_read_b128 v[134:137], v2
	ds_read_b128 v[138:141], v2 offset:1024
	ds_read_b128 v[142:145], v2 offset:2048
	ds_read_b128 v[146:149], v2 offset:3072
	v_add_u32_e32 v2, 0x1c000, v232
	ds_read_b128 v[150:153], v2
	ds_read_b128 v[154:157], v2 offset:1024
	ds_read_b128 v[158:161], v2 offset:2048
	ds_read_b128 v[162:165], v2 offset:3072
	s_mov_b32 m0, s56
	s_add_i32 s53, s92, 0x80000
	ds_read_b128 v[166:169], v233 offset:32768
	ds_read_b128 v[170:173], v233 offset:33792
	ds_read_b128 v[174:177], v233 offset:34816
	ds_read_b128 v[178:181], v233 offset:35840
	ds_read_b128 v[182:185], v233 offset:36864
	ds_read_b128 v[186:189], v233 offset:37888
	ds_read_b128 v[190:193], v233 offset:38912
	ds_read_b128 v[194:197], v233 offset:39936
	buffer_load_dwordx4 v230, s[12:15], s53 offen lds
	s_add_i32 s53, s92, 0xc0000
	s_mov_b32 m0, s57
	s_nop 0
	buffer_load_dwordx4 v230, s[12:15], s53 offen lds
	s_waitcnt vmcnt(8)
	s_waitcnt lgkmcnt(0)
	s_setprio 1
	v_mfma_f32_16x16x32_bf16 v[130:133], v[134:137], v[166:169], v[130:133]
	s_barrier
	v_mfma_f32_16x16x32_bf16 v[130:133], v[138:141], v[170:173], v[130:133]
	v_mfma_f32_16x16x32_bf16 v[126:129], v[142:145], v[166:169], v[126:129]
	v_mfma_f32_16x16x32_bf16 v[126:129], v[146:149], v[170:173], v[126:129]
	v_mfma_f32_16x16x32_bf16 v[122:125], v[150:153], v[166:169], v[122:125]
	v_mfma_f32_16x16x32_bf16 v[122:125], v[154:157], v[170:173], v[122:125]
	v_mfma_f32_16x16x32_bf16 v[118:121], v[158:161], v[166:169], v[118:121]
	v_mfma_f32_16x16x32_bf16 v[118:121], v[162:165], v[170:173], v[118:121]
	v_mfma_f32_16x16x32_bf16 v[114:117], v[134:137], v[174:177], v[114:117]
	v_mfma_f32_16x16x32_bf16 v[114:117], v[138:141], v[178:181], v[114:117]
	v_mfma_f32_16x16x32_bf16 v[110:113], v[142:145], v[174:177], v[110:113]
	v_mfma_f32_16x16x32_bf16 v[110:113], v[146:149], v[178:181], v[110:113]
	v_mfma_f32_16x16x32_bf16 v[106:109], v[150:153], v[174:177], v[106:109]
	v_mfma_f32_16x16x32_bf16 v[106:109], v[154:157], v[178:181], v[106:109]
	v_mfma_f32_16x16x32_bf16 v[102:105], v[158:161], v[174:177], v[102:105]
	v_mfma_f32_16x16x32_bf16 v[102:105], v[162:165], v[178:181], v[102:105]
	v_mfma_f32_16x16x32_bf16 v[98:101], v[134:137], v[182:185], v[98:101]
	v_mfma_f32_16x16x32_bf16 v[98:101], v[138:141], v[186:189], v[98:101]
	v_mfma_f32_16x16x32_bf16 v[94:97], v[142:145], v[182:185], v[94:97]
	v_mfma_f32_16x16x32_bf16 v[94:97], v[146:149], v[186:189], v[94:97]
	v_mfma_f32_16x16x32_bf16 v[90:93], v[150:153], v[182:185], v[90:93]
	v_mfma_f32_16x16x32_bf16 v[90:93], v[154:157], v[186:189], v[90:93]
	v_mfma_f32_16x16x32_bf16 v[86:89], v[158:161], v[182:185], v[86:89]
	v_mfma_f32_16x16x32_bf16 v[86:89], v[162:165], v[186:189], v[86:89]
	v_mfma_f32_16x16x32_bf16 v[82:85], v[134:137], v[190:193], v[82:85]
	v_mfma_f32_16x16x32_bf16 v[82:85], v[138:141], v[194:197], v[82:85]
	v_mfma_f32_16x16x32_bf16 v[78:81], v[142:145], v[190:193], v[78:81]
	v_mfma_f32_16x16x32_bf16 v[78:81], v[146:149], v[194:197], v[78:81]
	v_mfma_f32_16x16x32_bf16 v[74:77], v[150:153], v[190:193], v[74:77]
	v_mfma_f32_16x16x32_bf16 v[74:77], v[154:157], v[194:197], v[74:77]
	v_mfma_f32_16x16x32_bf16 v[70:73], v[158:161], v[190:193], v[70:73]
	v_mfma_f32_16x16x32_bf16 v[70:73], v[162:165], v[194:197], v[70:73]
	s_setprio 0
	s_barrier
	s_mov_b32 m0, s64
	ds_read_b128 v[166:169], v233 offset:49152
	ds_read_b128 v[170:173], v233 offset:50176
	ds_read_b128 v[174:177], v233 offset:51200
	ds_read_b128 v[178:181], v233 offset:52224
	ds_read_b128 v[182:185], v233 offset:53248
	ds_read_b128 v[186:189], v233 offset:54272
	ds_read_b128 v[190:193], v233 offset:55296
	ds_read_b128 v[194:197], v233 offset:56320
	buffer_load_dwordx4 v231, s[16:19], s52 offen lds
	s_add_i32 s52, s51, 0x18080
	s_mov_b32 m0, s65
	s_nop 0
	buffer_load_dwordx4 v231, s[16:19], s52 offen lds
	s_add_i32 s52, s51, 0x30080
	s_mov_b32 m0, s68
	s_add_i32 s51, s51, 0x48080
	buffer_load_dwordx4 v231, s[16:19], s52 offen lds
	s_mov_b32 m0, s69
	s_nop 0
	buffer_load_dwordx4 v231, s[16:19], s51 offen lds
	s_mov_b32 m0, s66
	s_add_i32 s18, s92, 0x40080
	buffer_load_dwordx4 v230, s[12:15], s50 offen lds
	s_mov_b32 m0, s67
	s_nop 0
	buffer_load_dwordx4 v230, s[12:15], s18 offen lds
	s_waitcnt vmcnt(8)
	s_waitcnt lgkmcnt(0)
	s_setprio 1
	v_mfma_f32_16x16x32_bf16 v[66:69], v[134:137], v[166:169], v[66:69]
	s_barrier
	v_mfma_f32_16x16x32_bf16 v[62:65], v[142:145], v[166:169], v[62:65]
	v_mfma_f32_16x16x32_bf16 v[50:53], v[134:137], v[174:177], v[50:53]
	v_mfma_f32_16x16x32_bf16 v[46:49], v[142:145], v[174:177], v[46:49]
	v_mfma_f32_16x16x32_bf16 v[34:37], v[134:137], v[182:185], v[34:37]
	v_mfma_f32_16x16x32_bf16 v[30:33], v[142:145], v[182:185], v[30:33]
	v_mfma_f32_16x16x32_bf16 v[18:21], v[134:137], v[190:193], v[18:21]
	v_mfma_f32_16x16x32_bf16 v[14:17], v[142:145], v[190:193], v[14:17]
	v_mfma_f32_16x16x32_bf16 v[58:61], v[150:153], v[166:169], v[58:61]
	v_mfma_f32_16x16x32_bf16 v[54:57], v[158:161], v[166:169], v[54:57]
	v_mfma_f32_16x16x32_bf16 v[42:45], v[150:153], v[174:177], v[42:45]
	v_mfma_f32_16x16x32_bf16 v[38:41], v[158:161], v[174:177], v[38:41]
	v_mfma_f32_16x16x32_bf16 v[26:29], v[150:153], v[182:185], v[26:29]
	v_mfma_f32_16x16x32_bf16 v[22:25], v[158:161], v[182:185], v[22:25]
	v_mfma_f32_16x16x32_bf16 v[8:11], v[150:153], v[190:193], v[10:13]
	v_mfma_f32_16x16x32_bf16 v[4:7], v[158:161], v[190:193], v[4:7]
	v_mfma_f32_16x16x32_bf16 v[66:69], v[138:141], v[170:173], v[66:69]
	v_mfma_f32_16x16x32_bf16 v[62:65], v[146:149], v[170:173], v[62:65]
	v_mfma_f32_16x16x32_bf16 v[50:53], v[138:141], v[178:181], v[50:53]
	v_mfma_f32_16x16x32_bf16 v[46:49], v[146:149], v[178:181], v[46:49]
	v_mfma_f32_16x16x32_bf16 v[34:37], v[138:141], v[186:189], v[34:37]
	v_mfma_f32_16x16x32_bf16 v[30:33], v[146:149], v[186:189], v[30:33]
	v_mfma_f32_16x16x32_bf16 v[18:21], v[138:141], v[194:197], v[18:21]
	v_mfma_f32_16x16x32_bf16 v[14:17], v[146:149], v[194:197], v[14:17]
	v_mfma_f32_16x16x32_bf16 v[58:61], v[154:157], v[170:173], v[58:61]
	v_mfma_f32_16x16x32_bf16 v[54:57], v[162:165], v[170:173], v[54:57]
	v_mfma_f32_16x16x32_bf16 v[42:45], v[154:157], v[178:181], v[42:45]
	v_mfma_f32_16x16x32_bf16 v[38:41], v[162:165], v[178:181], v[38:41]
	v_mfma_f32_16x16x32_bf16 v[26:29], v[154:157], v[186:189], v[26:29]
	v_mfma_f32_16x16x32_bf16 v[22:25], v[162:165], v[186:189], v[22:25]
	v_mfma_f32_16x16x32_bf16 v[10:13], v[154:157], v[194:197], v[8:11]
	v_mfma_f32_16x16x32_bf16 v[6:9], v[162:165], v[194:197], v[4:7]
	s_setprio 0
	s_barrier
	s_add_i32 s91, s91, 2
	s_addk_i32 s90, 0x100
	s_cmp_ge_i32 s91, s3
	s_cbranch_scc1 .LBB0_1193

.LBB0_1290:
	ds_read_b128 v[106:109], v224
	ds_read_b128 v[118:121], v224 offset:1024
	ds_read_b128 v[130:133], v224 offset:2048
	ds_read_b128 v[138:141], v224 offset:3072
	ds_read_b128 v[146:149], v225
	ds_read_b128 v[150:153], v225 offset:1024
	ds_read_b128 v[154:157], v225 offset:2048
	ds_read_b128 v[158:161], v225 offset:3072
	s_add_i32 s18, s72, 0xffe80080
	s_cmp_eq_u32 s56, s74
	s_cselect_b32 s75, s6, s18
	s_cselect_b32 s77, s7, s73
	s_or_b32 s76, s75, 0x80
	s_add_i32 s18, s72, 0xfff80000
	s_mov_b32 m0, s57
	ds_read_b128 v[162:165], v226
	ds_read_b128 v[166:169], v226 offset:1024
	ds_read_b128 v[170:173], v226 offset:2048
	ds_read_b128 v[174:177], v226 offset:3072
	ds_read_b128 v[178:181], v226 offset:4096
	ds_read_b128 v[182:185], v226 offset:5120
	ds_read_b128 v[190:193], v226 offset:6144
	ds_read_b128 v[194:197], v226 offset:7168
	buffer_load_dwordx4 v222, s[12:15], s18 offen lds
	s_mov_b32 m0, s60
	s_nop 0
	buffer_load_dwordx4 v222, s[12:15], s72 offen lds
	s_waitcnt vmcnt(8)
	s_waitcnt lgkmcnt(0)
	s_setprio 1
	v_mfma_f32_16x16x32_bf16 v[142:145], v[106:109], v[162:165], v[142:145]
	s_barrier
	v_mfma_f32_16x16x32_bf16 v[142:145], v[118:121], v[166:169], v[142:145]
	v_mfma_f32_16x16x32_bf16 v[134:137], v[130:133], v[162:165], v[134:137]
	v_mfma_f32_16x16x32_bf16 v[134:137], v[138:141], v[166:169], v[134:137]
	v_mfma_f32_16x16x32_bf16 v[126:129], v[146:149], v[162:165], v[126:129]
	v_mfma_f32_16x16x32_bf16 v[126:129], v[150:153], v[166:169], v[126:129]
	v_mfma_f32_16x16x32_bf16 v[122:125], v[154:157], v[162:165], v[122:125]
	v_mfma_f32_16x16x32_bf16 v[122:125], v[158:161], v[166:169], v[122:125]
	v_mfma_f32_16x16x32_bf16 v[114:117], v[106:109], v[170:173], v[114:117]
	v_mfma_f32_16x16x32_bf16 v[114:117], v[118:121], v[174:177], v[114:117]
	v_mfma_f32_16x16x32_bf16 v[110:113], v[130:133], v[170:173], v[110:113]
	v_mfma_f32_16x16x32_bf16 v[110:113], v[138:141], v[174:177], v[110:113]
	v_mfma_f32_16x16x32_bf16 v[102:105], v[146:149], v[170:173], v[102:105]
	v_mfma_f32_16x16x32_bf16 v[102:105], v[150:153], v[174:177], v[102:105]
	v_mfma_f32_16x16x32_bf16 v[98:101], v[154:157], v[170:173], v[98:101]
	v_mfma_f32_16x16x32_bf16 v[98:101], v[158:161], v[174:177], v[98:101]
	v_mfma_f32_16x16x32_bf16 v[94:97], v[106:109], v[178:181], v[94:97]
	v_mfma_f32_16x16x32_bf16 v[94:97], v[118:121], v[182:185], v[94:97]
	v_mfma_f32_16x16x32_bf16 v[90:93], v[130:133], v[178:181], v[90:93]
	v_mfma_f32_16x16x32_bf16 v[90:93], v[138:141], v[182:185], v[90:93]
	v_mfma_f32_16x16x32_bf16 v[86:89], v[146:149], v[178:181], v[86:89]
	v_mfma_f32_16x16x32_bf16 v[86:89], v[150:153], v[182:185], v[86:89]
	v_mfma_f32_16x16x32_bf16 v[82:85], v[154:157], v[178:181], v[82:85]
	v_mfma_f32_16x16x32_bf16 v[82:85], v[158:161], v[182:185], v[82:85]
	v_mfma_f32_16x16x32_bf16 v[78:81], v[106:109], v[190:193], v[78:81]
	v_mfma_f32_16x16x32_bf16 v[78:81], v[118:121], v[194:197], v[78:81]
	v_mfma_f32_16x16x32_bf16 v[74:77], v[130:133], v[190:193], v[74:77]
	v_mfma_f32_16x16x32_bf16 v[74:77], v[138:141], v[194:197], v[74:77]
	v_mfma_f32_16x16x32_bf16 v[70:73], v[146:149], v[190:193], v[70:73]
	v_mfma_f32_16x16x32_bf16 v[70:73], v[150:153], v[194:197], v[70:73]
	v_mfma_f32_16x16x32_bf16 v[66:69], v[154:157], v[190:193], v[66:69]
	v_mfma_f32_16x16x32_bf16 v[66:69], v[158:161], v[194:197], v[66:69]
	s_setprio 0
	s_barrier
	s_mov_b32 m0, s27
	s_mov_b32 s18, s14
	s_mov_b32 s19, s15
	ds_read_b128 v[162:165], v226 offset:16384
	ds_read_b128 v[166:169], v226 offset:17408
	ds_read_b128 v[170:173], v226 offset:18432
	ds_read_b128 v[174:177], v226 offset:19456
	ds_read_b128 v[178:181], v226 offset:20480
	ds_read_b128 v[182:185], v226 offset:21504
	ds_read_b128 v[190:193], v226 offset:22528
	ds_read_b128 v[194:197], v226 offset:23552
	buffer_load_dwordx4 v223, s[16:19], s77 offen lds
	s_add_i32 s78, s77, 0x80000
	s_mov_b32 m0, s30
	s_nop 0
	buffer_load_dwordx4 v223, s[16:19], s78 offen lds
	s_add_i32 s78, s77, 0x100000
	s_mov_b32 m0, s31
	s_nop 0
	buffer_load_dwordx4 v223, s[16:19], s78 offen lds
	s_add_i32 s78, s77, 0x180000
	s_mov_b32 m0, s41
	s_nop 0
	buffer_load_dwordx4 v223, s[16:19], s78 offen lds
	s_mov_b32 m0, s25
	s_add_i32 s78, s75, 0x80000
	buffer_load_dwordx4 v222, s[12:15], s75 offen lds
	s_mov_b32 m0, s42
	s_nop 0
	buffer_load_dwordx4 v222, s[12:15], s78 offen lds
	s_waitcnt vmcnt(8)
	s_waitcnt lgkmcnt(0)
	s_setprio 1
	v_mfma_f32_16x16x32_bf16 v[62:65], v[106:109], v[162:165], v[62:65]
	s_barrier
	v_mfma_f32_16x16x32_bf16 v[62:65], v[118:121], v[166:169], v[62:65]
	v_mfma_f32_16x16x32_bf16 v[58:61], v[130:133], v[162:165], v[58:61]
	v_mfma_f32_16x16x32_bf16 v[58:61], v[138:141], v[166:169], v[58:61]
	v_mfma_f32_16x16x32_bf16 v[54:57], v[146:149], v[162:165], v[54:57]
	v_mfma_f32_16x16x32_bf16 v[54:57], v[150:153], v[166:169], v[54:57]
	v_mfma_f32_16x16x32_bf16 v[50:53], v[154:157], v[162:165], v[50:53]
	v_mfma_f32_16x16x32_bf16 v[50:53], v[158:161], v[166:169], v[50:53]
	v_mfma_f32_16x16x32_bf16 v[46:49], v[106:109], v[170:173], v[46:49]
	v_mfma_f32_16x16x32_bf16 v[46:49], v[118:121], v[174:177], v[46:49]
	v_mfma_f32_16x16x32_bf16 v[42:45], v[130:133], v[170:173], v[42:45]
	v_mfma_f32_16x16x32_bf16 v[42:45], v[138:141], v[174:177], v[42:45]
	v_mfma_f32_16x16x32_bf16 v[38:41], v[146:149], v[170:173], v[38:41]
	v_mfma_f32_16x16x32_bf16 v[38:41], v[150:153], v[174:177], v[38:41]
	v_mfma_f32_16x16x32_bf16 v[34:37], v[154:157], v[170:173], v[34:37]
	v_mfma_f32_16x16x32_bf16 v[34:37], v[158:161], v[174:177], v[34:37]
	v_mfma_f32_16x16x32_bf16 v[30:33], v[106:109], v[178:181], v[30:33]
	v_mfma_f32_16x16x32_bf16 v[30:33], v[118:121], v[182:185], v[30:33]
	v_mfma_f32_16x16x32_bf16 v[26:29], v[130:133], v[178:181], v[26:29]
	v_mfma_f32_16x16x32_bf16 v[26:29], v[138:141], v[182:185], v[26:29]
	v_mfma_f32_16x16x32_bf16 v[22:25], v[146:149], v[178:181], v[22:25]
	v_mfma_f32_16x16x32_bf16 v[22:25], v[150:153], v[182:185], v[22:25]
	v_mfma_f32_16x16x32_bf16 v[18:21], v[154:157], v[178:181], v[18:21]
	v_mfma_f32_16x16x32_bf16 v[18:21], v[158:161], v[182:185], v[18:21]
	v_mfma_f32_16x16x32_bf16 v[14:17], v[106:109], v[190:193], v[14:17]
	v_mfma_f32_16x16x32_bf16 v[14:17], v[118:121], v[194:197], v[14:17]
	v_mfma_f32_16x16x32_bf16 v[10:13], v[130:133], v[190:193], v[10:13]
	v_mfma_f32_16x16x32_bf16 v[10:13], v[138:141], v[194:197], v[10:13]
	v_mfma_f32_16x16x32_bf16 v[6:9], v[146:149], v[190:193], v[6:9]
	v_mfma_f32_16x16x32_bf16 v[6:9], v[150:153], v[194:197], v[6:9]
	v_mfma_f32_16x16x32_bf16 v[2:5], v[154:157], v[190:193], v[2:5]
	v_mfma_f32_16x16x32_bf16 v[2:5], v[158:161], v[194:197], v[2:5]
	s_setprio 0
	s_barrier
	ds_read_b128 v[106:109], v227
	ds_read_b128 v[118:121], v227 offset:1024
	ds_read_b128 v[130:133], v227 offset:2048
	ds_read_b128 v[138:141], v227 offset:3072
	ds_read_b128 v[146:149], v228
	ds_read_b128 v[150:153], v228 offset:1024
	ds_read_b128 v[154:157], v228 offset:2048
	ds_read_b128 v[158:161], v228 offset:3072
	s_mov_b32 m0, s43
	s_add_i32 s78, s75, 0x100000
	ds_read_b128 v[162:165], v226 offset:32768
	ds_read_b128 v[166:169], v226 offset:33792
	ds_read_b128 v[170:173], v226 offset:34816
	ds_read_b128 v[174:177], v226 offset:35840
	ds_read_b128 v[178:181], v226 offset:36864
	ds_read_b128 v[182:185], v226 offset:37888
	ds_read_b128 v[190:193], v226 offset:38912
	ds_read_b128 v[194:197], v226 offset:39936
	buffer_load_dwordx4 v222, s[12:15], s78 offen lds
	s_add_i32 s78, s75, 0x180000
	s_mov_b32 m0, s44
	s_nop 0
	buffer_load_dwordx4 v222, s[12:15], s78 offen lds
	s_waitcnt vmcnt(8)
	s_waitcnt lgkmcnt(0)
	s_setprio 1
	v_mfma_f32_16x16x32_bf16 v[142:145], v[106:109], v[162:165], v[142:145]
	s_barrier
	v_mfma_f32_16x16x32_bf16 v[142:145], v[118:121], v[166:169], v[142:145]
	v_mfma_f32_16x16x32_bf16 v[134:137], v[130:133], v[162:165], v[134:137]
	v_mfma_f32_16x16x32_bf16 v[134:137], v[138:141], v[166:169], v[134:137]
	v_mfma_f32_16x16x32_bf16 v[126:129], v[146:149], v[162:165], v[126:129]
	v_mfma_f32_16x16x32_bf16 v[126:129], v[150:153], v[166:169], v[126:129]
	v_mfma_f32_16x16x32_bf16 v[122:125], v[154:157], v[162:165], v[122:125]
	v_mfma_f32_16x16x32_bf16 v[122:125], v[158:161], v[166:169], v[122:125]
	v_mfma_f32_16x16x32_bf16 v[114:117], v[106:109], v[170:173], v[114:117]
	v_mfma_f32_16x16x32_bf16 v[114:117], v[118:121], v[174:177], v[114:117]
	v_mfma_f32_16x16x32_bf16 v[110:113], v[130:133], v[170:173], v[110:113]
	v_mfma_f32_16x16x32_bf16 v[110:113], v[138:141], v[174:177], v[110:113]
	v_mfma_f32_16x16x32_bf16 v[102:105], v[146:149], v[170:173], v[102:105]
	v_mfma_f32_16x16x32_bf16 v[102:105], v[150:153], v[174:177], v[102:105]
	v_mfma_f32_16x16x32_bf16 v[98:101], v[154:157], v[170:173], v[98:101]
	v_mfma_f32_16x16x32_bf16 v[98:101], v[158:161], v[174:177], v[98:101]
	v_mfma_f32_16x16x32_bf16 v[94:97], v[106:109], v[178:181], v[94:97]
	v_mfma_f32_16x16x32_bf16 v[94:97], v[118:121], v[182:185], v[94:97]
	v_mfma_f32_16x16x32_bf16 v[90:93], v[130:133], v[178:181], v[90:93]
	v_mfma_f32_16x16x32_bf16 v[90:93], v[138:141], v[182:185], v[90:93]
	v_mfma_f32_16x16x32_bf16 v[86:89], v[146:149], v[178:181], v[86:89]
	v_mfma_f32_16x16x32_bf16 v[86:89], v[150:153], v[182:185], v[86:89]
	v_mfma_f32_16x16x32_bf16 v[82:85], v[154:157], v[178:181], v[82:85]
	v_mfma_f32_16x16x32_bf16 v[82:85], v[158:161], v[182:185], v[82:85]
	v_mfma_f32_16x16x32_bf16 v[78:81], v[106:109], v[190:193], v[78:81]
	v_mfma_f32_16x16x32_bf16 v[78:81], v[118:121], v[194:197], v[78:81]
	v_mfma_f32_16x16x32_bf16 v[74:77], v[130:133], v[190:193], v[74:77]
	v_mfma_f32_16x16x32_bf16 v[74:77], v[138:141], v[194:197], v[74:77]
	v_mfma_f32_16x16x32_bf16 v[70:73], v[146:149], v[190:193], v[70:73]
	v_mfma_f32_16x16x32_bf16 v[70:73], v[150:153], v[194:197], v[70:73]
	v_mfma_f32_16x16x32_bf16 v[66:69], v[154:157], v[190:193], v[66:69]
	v_mfma_f32_16x16x32_bf16 v[66:69], v[158:161], v[194:197], v[66:69]
	s_setprio 0
	s_barrier
	s_mov_b32 m0, s48
	s_or_b32 s78, s77, 0x80
	ds_read_b128 v[162:165], v226 offset:49152
	ds_read_b128 v[166:169], v226 offset:50176
	ds_read_b128 v[170:173], v226 offset:51200
	ds_read_b128 v[174:177], v226 offset:52224
	ds_read_b128 v[178:181], v226 offset:53248
	ds_read_b128 v[182:185], v226 offset:54272
	ds_read_b128 v[190:193], v226 offset:55296
	ds_read_b128 v[194:197], v226 offset:56320
	buffer_load_dwordx4 v223, s[16:19], s78 offen lds
	s_add_i32 s78, s77, 0x80080
	s_mov_b32 m0, s49
	s_add_i32 s75, s75, 0x80080
	buffer_load_dwordx4 v223, s[16:19], s78 offen lds
	s_add_i32 s78, s77, 0x100080
	s_mov_b32 m0, s52
	s_add_i32 s77, s77, 0x180080
	buffer_load_dwordx4 v223, s[16:19], s78 offen lds
	s_mov_b32 m0, s53
	s_nop 0
	buffer_load_dwordx4 v223, s[16:19], s77 offen lds
	s_mov_b32 m0, s50
	s_nop 0
	buffer_load_dwordx4 v222, s[12:15], s76 offen lds
	s_mov_b32 m0, s51
	s_nop 0
	buffer_load_dwordx4 v222, s[12:15], s75 offen lds
	s_waitcnt vmcnt(8)
	s_waitcnt lgkmcnt(0)
	s_setprio 1
	v_mfma_f32_16x16x32_bf16 v[62:65], v[106:109], v[162:165], v[62:65]
	s_barrier
	v_mfma_f32_16x16x32_bf16 v[62:65], v[118:121], v[166:169], v[62:65]
	v_mfma_f32_16x16x32_bf16 v[58:61], v[130:133], v[162:165], v[58:61]
	v_mfma_f32_16x16x32_bf16 v[58:61], v[138:141], v[166:169], v[58:61]
	v_mfma_f32_16x16x32_bf16 v[54:57], v[146:149], v[162:165], v[54:57]
	v_mfma_f32_16x16x32_bf16 v[54:57], v[150:153], v[166:169], v[54:57]
	v_mfma_f32_16x16x32_bf16 v[50:53], v[154:157], v[162:165], v[50:53]
	v_mfma_f32_16x16x32_bf16 v[50:53], v[158:161], v[166:169], v[50:53]
	v_mfma_f32_16x16x32_bf16 v[46:49], v[106:109], v[170:173], v[46:49]
	v_mfma_f32_16x16x32_bf16 v[46:49], v[118:121], v[174:177], v[46:49]
	v_mfma_f32_16x16x32_bf16 v[42:45], v[130:133], v[170:173], v[42:45]
	v_mfma_f32_16x16x32_bf16 v[42:45], v[138:141], v[174:177], v[42:45]
	v_mfma_f32_16x16x32_bf16 v[38:41], v[146:149], v[170:173], v[38:41]
	v_mfma_f32_16x16x32_bf16 v[38:41], v[150:153], v[174:177], v[38:41]
	v_mfma_f32_16x16x32_bf16 v[34:37], v[154:157], v[170:173], v[34:37]
	v_mfma_f32_16x16x32_bf16 v[34:37], v[158:161], v[174:177], v[34:37]
	v_mfma_f32_16x16x32_bf16 v[30:33], v[106:109], v[178:181], v[30:33]
	v_mfma_f32_16x16x32_bf16 v[30:33], v[118:121], v[182:185], v[30:33]
	v_mfma_f32_16x16x32_bf16 v[26:29], v[130:133], v[178:181], v[26:29]
	v_mfma_f32_16x16x32_bf16 v[26:29], v[138:141], v[182:185], v[26:29]
	v_mfma_f32_16x16x32_bf16 v[22:25], v[146:149], v[178:181], v[22:25]
	v_mfma_f32_16x16x32_bf16 v[22:25], v[150:153], v[182:185], v[22:25]
	v_mfma_f32_16x16x32_bf16 v[18:21], v[154:157], v[178:181], v[18:21]
	v_mfma_f32_16x16x32_bf16 v[18:21], v[158:161], v[182:185], v[18:21]
	v_mfma_f32_16x16x32_bf16 v[14:17], v[106:109], v[190:193], v[14:17]
	v_mfma_f32_16x16x32_bf16 v[14:17], v[118:121], v[194:197], v[14:17]
	v_mfma_f32_16x16x32_bf16 v[10:13], v[130:133], v[190:193], v[10:13]
	v_mfma_f32_16x16x32_bf16 v[10:13], v[138:141], v[194:197], v[10:13]
	v_mfma_f32_16x16x32_bf16 v[6:9], v[146:149], v[190:193], v[6:9]
	v_mfma_f32_16x16x32_bf16 v[6:9], v[150:153], v[194:197], v[6:9]
	v_mfma_f32_16x16x32_bf16 v[2:5], v[154:157], v[190:193], v[2:5]
	v_mfma_f32_16x16x32_bf16 v[2:5], v[158:161], v[194:197], v[2:5]
	s_setprio 0
	s_barrier
	s_add_i32 s74, s74, 2
	s_addk_i32 s72, 0x100
	s_addk_i32 s73, 0x100
	s_cmp_ge_i32 s74, s3
	s_cbranch_scc0 .LBB0_1290
	s_and_b64 vcc, exec, s[38:39]
	s_cbranch_vccz .LBB0_1293

.LBB0_1382:
	ds_read_b128 v[144:147], v138
	ds_read_b128 v[148:151], v138 offset:1024
	ds_read_b128 v[152:155], v138 offset:2048
	ds_read_b128 v[156:159], v138 offset:3072
	ds_read_b128 v[160:163], v139
	ds_read_b128 v[164:167], v139 offset:1024
	ds_read_b128 v[168:171], v139 offset:2048
	ds_read_b128 v[172:175], v139 offset:3072
	s_add_i32 s14, s74, 0xffe80080
	s_cmp_eq_u32 s61, s76
	s_cselect_b32 s77, s72, s14
	s_cselect_b32 s79, s73, s75
	s_or_b32 s78, s77, 0x80
	s_add_i32 s14, s74, 0xfff80000
	s_mov_b32 m0, s62
	ds_read_b128 v[176:179], v140
	ds_read_b128 v[180:183], v140 offset:1024
	ds_read_b128 v[184:187], v140 offset:2048
	ds_read_b128 v[188:191], v140 offset:3072
	ds_read_b128 v[192:195], v140 offset:4096
	ds_read_b128 v[196:199], v140 offset:5120
	ds_read_b128 v[200:203], v140 offset:6144
	ds_read_b128 v[204:207], v140 offset:7168
	buffer_load_dwordx4 v136, s[16:19], s14 offen lds
	s_mov_b32 m0, s63
	s_nop 0
	buffer_load_dwordx4 v136, s[16:19], s74 offen lds
	s_waitcnt vmcnt(8)
	s_waitcnt lgkmcnt(0)
	s_setprio 1
	v_mfma_f32_16x16x32_bf16 v[118:121], v[144:147], v[176:179], v[118:121]
	s_barrier
	v_mfma_f32_16x16x32_bf16 v[118:121], v[148:151], v[180:183], v[118:121]
	v_mfma_f32_16x16x32_bf16 v[114:117], v[152:155], v[176:179], v[114:117]
	v_mfma_f32_16x16x32_bf16 v[114:117], v[156:159], v[180:183], v[114:117]
	v_mfma_f32_16x16x32_bf16 v[126:129], v[160:163], v[176:179], v[126:129]
	v_mfma_f32_16x16x32_bf16 v[126:129], v[164:167], v[180:183], v[126:129]
	v_mfma_f32_16x16x32_bf16 v[122:125], v[168:171], v[176:179], v[122:125]
	v_mfma_f32_16x16x32_bf16 v[122:125], v[172:175], v[180:183], v[122:125]
	v_mfma_f32_16x16x32_bf16 v[110:113], v[144:147], v[184:187], v[110:113]
	v_mfma_f32_16x16x32_bf16 v[110:113], v[148:151], v[188:191], v[110:113]
	v_mfma_f32_16x16x32_bf16 v[102:105], v[152:155], v[184:187], v[102:105]
	v_mfma_f32_16x16x32_bf16 v[102:105], v[156:159], v[188:191], v[102:105]
	v_mfma_f32_16x16x32_bf16 v[106:109], v[160:163], v[184:187], v[106:109]
	v_mfma_f32_16x16x32_bf16 v[106:109], v[164:167], v[188:191], v[106:109]
	v_mfma_f32_16x16x32_bf16 v[98:101], v[168:171], v[184:187], v[98:101]
	v_mfma_f32_16x16x32_bf16 v[98:101], v[172:175], v[188:191], v[98:101]
	v_mfma_f32_16x16x32_bf16 v[94:97], v[144:147], v[192:195], v[94:97]
	v_mfma_f32_16x16x32_bf16 v[94:97], v[148:151], v[196:199], v[94:97]
	v_mfma_f32_16x16x32_bf16 v[86:89], v[152:155], v[192:195], v[86:89]
	v_mfma_f32_16x16x32_bf16 v[86:89], v[156:159], v[196:199], v[86:89]
	v_mfma_f32_16x16x32_bf16 v[90:93], v[160:163], v[192:195], v[90:93]
	v_mfma_f32_16x16x32_bf16 v[90:93], v[164:167], v[196:199], v[90:93]
	v_mfma_f32_16x16x32_bf16 v[82:85], v[168:171], v[192:195], v[82:85]
	v_mfma_f32_16x16x32_bf16 v[82:85], v[172:175], v[196:199], v[82:85]
	v_mfma_f32_16x16x32_bf16 v[78:81], v[144:147], v[200:203], v[78:81]
	v_mfma_f32_16x16x32_bf16 v[78:81], v[148:151], v[204:207], v[78:81]
	v_mfma_f32_16x16x32_bf16 v[66:69], v[152:155], v[200:203], v[66:69]
	v_mfma_f32_16x16x32_bf16 v[66:69], v[156:159], v[204:207], v[66:69]
	v_mfma_f32_16x16x32_bf16 v[74:77], v[160:163], v[200:203], v[74:77]
	v_mfma_f32_16x16x32_bf16 v[74:77], v[164:167], v[204:207], v[74:77]
	v_mfma_f32_16x16x32_bf16 v[70:73], v[168:171], v[200:203], v[70:73]
	v_mfma_f32_16x16x32_bf16 v[70:73], v[172:175], v[204:207], v[70:73]
	s_setprio 0
	s_barrier
	s_mov_b32 m0, s45
	s_mov_b32 s14, s18
	s_mov_b32 s15, s19
	ds_read_b128 v[176:179], v140 offset:16384
	ds_read_b128 v[180:183], v140 offset:17408
	ds_read_b128 v[184:187], v140 offset:18432
	ds_read_b128 v[188:191], v140 offset:19456
	ds_read_b128 v[192:195], v140 offset:20480
	ds_read_b128 v[196:199], v140 offset:21504
	ds_read_b128 v[200:203], v140 offset:22528
	ds_read_b128 v[204:207], v140 offset:23552
	buffer_load_dwordx4 v137, s[12:15], s79 offen lds
	s_add_i32 s80, s79, 0x80000
	s_mov_b32 m0, s46
	s_nop 0
	buffer_load_dwordx4 v137, s[12:15], s80 offen lds
	s_add_i32 s80, s79, 0x100000
	s_mov_b32 m0, s47
	s_nop 0
	buffer_load_dwordx4 v137, s[12:15], s80 offen lds
	s_add_i32 s80, s79, 0x180000
	s_mov_b32 m0, s48
	s_nop 0
	buffer_load_dwordx4 v137, s[12:15], s80 offen lds
	s_mov_b32 m0, s44
	s_add_i32 s80, s77, 0x80000
	buffer_load_dwordx4 v136, s[16:19], s77 offen lds
	s_mov_b32 m0, s49
	s_nop 0
	buffer_load_dwordx4 v136, s[16:19], s80 offen lds
	s_waitcnt vmcnt(8)
	s_waitcnt lgkmcnt(0)
	s_setprio 1
	v_mfma_f32_16x16x32_bf16 v[62:65], v[144:147], v[176:179], v[62:65]
	s_barrier
	v_mfma_f32_16x16x32_bf16 v[62:65], v[148:151], v[180:183], v[62:65]
	v_mfma_f32_16x16x32_bf16 v[54:57], v[152:155], v[176:179], v[54:57]
	v_mfma_f32_16x16x32_bf16 v[54:57], v[156:159], v[180:183], v[54:57]
	v_mfma_f32_16x16x32_bf16 v[58:61], v[160:163], v[176:179], v[58:61]
	v_mfma_f32_16x16x32_bf16 v[58:61], v[164:167], v[180:183], v[58:61]
	v_mfma_f32_16x16x32_bf16 v[50:53], v[168:171], v[176:179], v[50:53]
	v_mfma_f32_16x16x32_bf16 v[50:53], v[172:175], v[180:183], v[50:53]
	v_mfma_f32_16x16x32_bf16 v[46:49], v[144:147], v[184:187], v[46:49]
	v_mfma_f32_16x16x32_bf16 v[46:49], v[148:151], v[188:191], v[46:49]
	v_mfma_f32_16x16x32_bf16 v[38:41], v[152:155], v[184:187], v[38:41]
	v_mfma_f32_16x16x32_bf16 v[38:41], v[156:159], v[188:191], v[38:41]
	v_mfma_f32_16x16x32_bf16 v[42:45], v[160:163], v[184:187], v[42:45]
	v_mfma_f32_16x16x32_bf16 v[42:45], v[164:167], v[188:191], v[42:45]
	v_mfma_f32_16x16x32_bf16 v[34:37], v[168:171], v[184:187], v[34:37]
	v_mfma_f32_16x16x32_bf16 v[34:37], v[172:175], v[188:191], v[34:37]
	v_mfma_f32_16x16x32_bf16 v[30:33], v[144:147], v[192:195], v[30:33]
	v_mfma_f32_16x16x32_bf16 v[30:33], v[148:151], v[196:199], v[30:33]
	v_mfma_f32_16x16x32_bf16 v[22:25], v[152:155], v[192:195], v[22:25]
	v_mfma_f32_16x16x32_bf16 v[22:25], v[156:159], v[196:199], v[22:25]
	v_mfma_f32_16x16x32_bf16 v[26:29], v[160:163], v[192:195], v[26:29]
	v_mfma_f32_16x16x32_bf16 v[26:29], v[164:167], v[196:199], v[26:29]
	v_mfma_f32_16x16x32_bf16 v[18:21], v[168:171], v[192:195], v[18:21]
	v_mfma_f32_16x16x32_bf16 v[18:21], v[172:175], v[196:199], v[18:21]
	v_mfma_f32_16x16x32_bf16 v[14:17], v[144:147], v[200:203], v[14:17]
	v_mfma_f32_16x16x32_bf16 v[14:17], v[148:151], v[204:207], v[14:17]
	v_mfma_f32_16x16x32_bf16 v[6:9], v[152:155], v[200:203], v[6:9]
	v_mfma_f32_16x16x32_bf16 v[6:9], v[156:159], v[204:207], v[6:9]
	v_mfma_f32_16x16x32_bf16 v[10:13], v[160:163], v[200:203], v[10:13]
	v_mfma_f32_16x16x32_bf16 v[10:13], v[164:167], v[204:207], v[10:13]
	v_mfma_f32_16x16x32_bf16 v[2:5], v[168:171], v[200:203], v[2:5]
	v_mfma_f32_16x16x32_bf16 v[2:5], v[172:175], v[204:207], v[2:5]
	s_setprio 0
	s_barrier
	ds_read_b128 v[144:147], v141
	ds_read_b128 v[148:151], v141 offset:1024
	ds_read_b128 v[152:155], v141 offset:2048
	ds_read_b128 v[156:159], v141 offset:3072
	ds_read_b128 v[160:163], v142
	ds_read_b128 v[164:167], v142 offset:1024
	ds_read_b128 v[168:171], v142 offset:2048
	ds_read_b128 v[172:175], v142 offset:3072
	s_mov_b32 m0, s50
	s_add_i32 s80, s77, 0x100000
	ds_read_b128 v[176:179], v140 offset:32768
	ds_read_b128 v[180:183], v140 offset:33792
	ds_read_b128 v[184:187], v140 offset:34816
	ds_read_b128 v[188:191], v140 offset:35840
	ds_read_b128 v[192:195], v140 offset:36864
	ds_read_b128 v[196:199], v140 offset:37888
	ds_read_b128 v[200:203], v140 offset:38912
	ds_read_b128 v[204:207], v140 offset:39936
	buffer_load_dwordx4 v136, s[16:19], s80 offen lds
	s_add_i32 s80, s77, 0x180000
	s_mov_b32 m0, s51
	s_nop 0
	buffer_load_dwordx4 v136, s[16:19], s80 offen lds
	s_waitcnt vmcnt(8)
	s_waitcnt lgkmcnt(0)
	s_setprio 1
	v_mfma_f32_16x16x32_bf16 v[118:121], v[144:147], v[176:179], v[118:121]
	s_barrier
	v_mfma_f32_16x16x32_bf16 v[118:121], v[148:151], v[180:183], v[118:121]
	v_mfma_f32_16x16x32_bf16 v[114:117], v[152:155], v[176:179], v[114:117]
	v_mfma_f32_16x16x32_bf16 v[114:117], v[156:159], v[180:183], v[114:117]
	v_mfma_f32_16x16x32_bf16 v[126:129], v[160:163], v[176:179], v[126:129]
	v_mfma_f32_16x16x32_bf16 v[126:129], v[164:167], v[180:183], v[126:129]
	v_mfma_f32_16x16x32_bf16 v[122:125], v[168:171], v[176:179], v[122:125]
	v_mfma_f32_16x16x32_bf16 v[122:125], v[172:175], v[180:183], v[122:125]
	v_mfma_f32_16x16x32_bf16 v[110:113], v[144:147], v[184:187], v[110:113]
	v_mfma_f32_16x16x32_bf16 v[110:113], v[148:151], v[188:191], v[110:113]
	v_mfma_f32_16x16x32_bf16 v[102:105], v[152:155], v[184:187], v[102:105]
	v_mfma_f32_16x16x32_bf16 v[102:105], v[156:159], v[188:191], v[102:105]
	v_mfma_f32_16x16x32_bf16 v[106:109], v[160:163], v[184:187], v[106:109]
	v_mfma_f32_16x16x32_bf16 v[106:109], v[164:167], v[188:191], v[106:109]
	v_mfma_f32_16x16x32_bf16 v[98:101], v[168:171], v[184:187], v[98:101]
	v_mfma_f32_16x16x32_bf16 v[98:101], v[172:175], v[188:191], v[98:101]
	v_mfma_f32_16x16x32_bf16 v[94:97], v[144:147], v[192:195], v[94:97]
	v_mfma_f32_16x16x32_bf16 v[94:97], v[148:151], v[196:199], v[94:97]
	v_mfma_f32_16x16x32_bf16 v[86:89], v[152:155], v[192:195], v[86:89]
	v_mfma_f32_16x16x32_bf16 v[86:89], v[156:159], v[196:199], v[86:89]
	v_mfma_f32_16x16x32_bf16 v[90:93], v[160:163], v[192:195], v[90:93]
	v_mfma_f32_16x16x32_bf16 v[90:93], v[164:167], v[196:199], v[90:93]
	v_mfma_f32_16x16x32_bf16 v[82:85], v[168:171], v[192:195], v[82:85]
	v_mfma_f32_16x16x32_bf16 v[82:85], v[172:175], v[196:199], v[82:85]
	v_mfma_f32_16x16x32_bf16 v[78:81], v[144:147], v[200:203], v[78:81]
	v_mfma_f32_16x16x32_bf16 v[78:81], v[148:151], v[204:207], v[78:81]
	v_mfma_f32_16x16x32_bf16 v[66:69], v[152:155], v[200:203], v[66:69]
	v_mfma_f32_16x16x32_bf16 v[66:69], v[156:159], v[204:207], v[66:69]
	v_mfma_f32_16x16x32_bf16 v[74:77], v[160:163], v[200:203], v[74:77]
	v_mfma_f32_16x16x32_bf16 v[74:77], v[164:167], v[204:207], v[74:77]
	v_mfma_f32_16x16x32_bf16 v[70:73], v[168:171], v[200:203], v[70:73]
	v_mfma_f32_16x16x32_bf16 v[70:73], v[172:175], v[204:207], v[70:73]
	s_setprio 0
	s_barrier
	s_mov_b32 m0, s53
	s_or_b32 s80, s79, 0x80
	ds_read_b128 v[176:179], v140 offset:49152
	ds_read_b128 v[180:183], v140 offset:50176
	ds_read_b128 v[184:187], v140 offset:51200
	ds_read_b128 v[188:191], v140 offset:52224
	ds_read_b128 v[192:195], v140 offset:53248
	ds_read_b128 v[196:199], v140 offset:54272
	ds_read_b128 v[200:203], v140 offset:55296
	ds_read_b128 v[204:207], v140 offset:56320
	buffer_load_dwordx4 v137, s[12:15], s80 offen lds
	s_add_i32 s80, s79, 0x80080
	s_mov_b32 m0, s54
	s_add_i32 s77, s77, 0x80080
	buffer_load_dwordx4 v137, s[12:15], s80 offen lds
	s_add_i32 s80, s79, 0x100080
	s_mov_b32 m0, s57
	s_add_i32 s79, s79, 0x180080
	buffer_load_dwordx4 v137, s[12:15], s80 offen lds
	s_mov_b32 m0, s58
	s_nop 0
	buffer_load_dwordx4 v137, s[12:15], s79 offen lds
	s_mov_b32 m0, s55
	s_nop 0
	buffer_load_dwordx4 v136, s[16:19], s78 offen lds
	s_mov_b32 m0, s56
	s_nop 0
	buffer_load_dwordx4 v136, s[16:19], s77 offen lds
	s_waitcnt vmcnt(8)
	s_waitcnt lgkmcnt(0)
	s_setprio 1
	v_mfma_f32_16x16x32_bf16 v[62:65], v[144:147], v[176:179], v[62:65]
	s_barrier
	v_mfma_f32_16x16x32_bf16 v[62:65], v[148:151], v[180:183], v[62:65]
	v_mfma_f32_16x16x32_bf16 v[54:57], v[152:155], v[176:179], v[54:57]
	v_mfma_f32_16x16x32_bf16 v[54:57], v[156:159], v[180:183], v[54:57]
	v_mfma_f32_16x16x32_bf16 v[58:61], v[160:163], v[176:179], v[58:61]
	v_mfma_f32_16x16x32_bf16 v[58:61], v[164:167], v[180:183], v[58:61]
	v_mfma_f32_16x16x32_bf16 v[50:53], v[168:171], v[176:179], v[50:53]
	v_mfma_f32_16x16x32_bf16 v[50:53], v[172:175], v[180:183], v[50:53]
	v_mfma_f32_16x16x32_bf16 v[46:49], v[144:147], v[184:187], v[46:49]
	v_mfma_f32_16x16x32_bf16 v[46:49], v[148:151], v[188:191], v[46:49]
	v_mfma_f32_16x16x32_bf16 v[38:41], v[152:155], v[184:187], v[38:41]
	v_mfma_f32_16x16x32_bf16 v[38:41], v[156:159], v[188:191], v[38:41]
	v_mfma_f32_16x16x32_bf16 v[42:45], v[160:163], v[184:187], v[42:45]
	v_mfma_f32_16x16x32_bf16 v[42:45], v[164:167], v[188:191], v[42:45]
	v_mfma_f32_16x16x32_bf16 v[34:37], v[168:171], v[184:187], v[34:37]
	v_mfma_f32_16x16x32_bf16 v[34:37], v[172:175], v[188:191], v[34:37]
	v_mfma_f32_16x16x32_bf16 v[30:33], v[144:147], v[192:195], v[30:33]
	v_mfma_f32_16x16x32_bf16 v[30:33], v[148:151], v[196:199], v[30:33]
	v_mfma_f32_16x16x32_bf16 v[22:25], v[152:155], v[192:195], v[22:25]
	v_mfma_f32_16x16x32_bf16 v[22:25], v[156:159], v[196:199], v[22:25]
	v_mfma_f32_16x16x32_bf16 v[26:29], v[160:163], v[192:195], v[26:29]
	v_mfma_f32_16x16x32_bf16 v[26:29], v[164:167], v[196:199], v[26:29]
	v_mfma_f32_16x16x32_bf16 v[18:21], v[168:171], v[192:195], v[18:21]
	v_mfma_f32_16x16x32_bf16 v[18:21], v[172:175], v[196:199], v[18:21]
	v_mfma_f32_16x16x32_bf16 v[14:17], v[144:147], v[200:203], v[14:17]
	v_mfma_f32_16x16x32_bf16 v[14:17], v[148:151], v[204:207], v[14:17]
	v_mfma_f32_16x16x32_bf16 v[6:9], v[152:155], v[200:203], v[6:9]
	v_mfma_f32_16x16x32_bf16 v[6:9], v[156:159], v[204:207], v[6:9]
	v_mfma_f32_16x16x32_bf16 v[10:13], v[160:163], v[200:203], v[10:13]
	v_mfma_f32_16x16x32_bf16 v[10:13], v[164:167], v[204:207], v[10:13]
	v_mfma_f32_16x16x32_bf16 v[2:5], v[168:171], v[200:203], v[2:5]
	v_mfma_f32_16x16x32_bf16 v[2:5], v[172:175], v[204:207], v[2:5]
	s_setprio 0
	s_barrier
	s_add_i32 s76, s76, 2
	s_addk_i32 s74, 0x100
	s_addk_i32 s75, 0x100
	s_cmp_ge_i32 s76, s27
	s_cbranch_scc0 .LBB0_1382
	s_and_b64 vcc, exec, s[42:43]
	s_cbranch_vccz .LBB0_1385

.LBB0_1402:
	ds_read_b128 v[146:149], v138
	ds_read_b128 v[150:153], v138 offset:1024
	ds_read_b128 v[154:157], v138 offset:2048
	ds_read_b128 v[158:161], v138 offset:3072
	ds_read_b128 v[162:165], v139
	ds_read_b128 v[166:169], v139 offset:1024
	ds_read_b128 v[170:173], v139 offset:2048
	ds_read_b128 v[174:177], v139 offset:3072
	s_add_i32 s22, s75, 0xffe80080
	s_cmp_eq_u32 s62, s77
	s_cselect_b32 s78, s73, s22
	s_cselect_b32 s80, s74, s76
	s_or_b32 s79, s78, 0x80
	s_add_i32 s22, s75, 0xfff80000
	s_mov_b32 m0, s63
	ds_read_b128 v[178:181], v140
	ds_read_b128 v[182:185], v140 offset:1024
	ds_read_b128 v[186:189], v140 offset:2048
	ds_read_b128 v[190:193], v140 offset:3072
	ds_read_b128 v[194:197], v140 offset:4096
	ds_read_b128 v[198:201], v140 offset:5120
	ds_read_b128 v[202:205], v140 offset:6144
	ds_read_b128 v[206:209], v140 offset:7168
	buffer_load_dwordx4 v136, s[16:19], s22 offen lds
	s_mov_b32 m0, s64
	s_nop 0
	buffer_load_dwordx4 v136, s[16:19], s75 offen lds
	s_waitcnt vmcnt(8)
	s_waitcnt lgkmcnt(0)
	s_setprio 1
	v_mfma_f32_16x16x32_bf16 v[118:121], v[146:149], v[178:181], v[118:121]
	s_barrier
	v_mfma_f32_16x16x32_bf16 v[118:121], v[150:153], v[182:185], v[118:121]
	v_mfma_f32_16x16x32_bf16 v[114:117], v[154:157], v[178:181], v[114:117]
	v_mfma_f32_16x16x32_bf16 v[114:117], v[158:161], v[182:185], v[114:117]
	v_mfma_f32_16x16x32_bf16 v[126:129], v[162:165], v[178:181], v[126:129]
	v_mfma_f32_16x16x32_bf16 v[126:129], v[166:169], v[182:185], v[126:129]
	v_mfma_f32_16x16x32_bf16 v[122:125], v[170:173], v[178:181], v[122:125]
	v_mfma_f32_16x16x32_bf16 v[122:125], v[174:177], v[182:185], v[122:125]
	v_mfma_f32_16x16x32_bf16 v[110:113], v[146:149], v[186:189], v[110:113]
	v_mfma_f32_16x16x32_bf16 v[110:113], v[150:153], v[190:193], v[110:113]
	v_mfma_f32_16x16x32_bf16 v[102:105], v[154:157], v[186:189], v[102:105]
	v_mfma_f32_16x16x32_bf16 v[102:105], v[158:161], v[190:193], v[102:105]
	v_mfma_f32_16x16x32_bf16 v[106:109], v[162:165], v[186:189], v[106:109]
	v_mfma_f32_16x16x32_bf16 v[106:109], v[166:169], v[190:193], v[106:109]
	v_mfma_f32_16x16x32_bf16 v[98:101], v[170:173], v[186:189], v[98:101]
	v_mfma_f32_16x16x32_bf16 v[98:101], v[174:177], v[190:193], v[98:101]
	v_mfma_f32_16x16x32_bf16 v[94:97], v[146:149], v[194:197], v[94:97]
	v_mfma_f32_16x16x32_bf16 v[94:97], v[150:153], v[198:201], v[94:97]
	v_mfma_f32_16x16x32_bf16 v[86:89], v[154:157], v[194:197], v[86:89]
	v_mfma_f32_16x16x32_bf16 v[86:89], v[158:161], v[198:201], v[86:89]
	v_mfma_f32_16x16x32_bf16 v[90:93], v[162:165], v[194:197], v[90:93]
	v_mfma_f32_16x16x32_bf16 v[90:93], v[166:169], v[198:201], v[90:93]
	v_mfma_f32_16x16x32_bf16 v[82:85], v[170:173], v[194:197], v[82:85]
	v_mfma_f32_16x16x32_bf16 v[82:85], v[174:177], v[198:201], v[82:85]
	v_mfma_f32_16x16x32_bf16 v[78:81], v[146:149], v[202:205], v[78:81]
	v_mfma_f32_16x16x32_bf16 v[78:81], v[150:153], v[206:209], v[78:81]
	v_mfma_f32_16x16x32_bf16 v[66:69], v[154:157], v[202:205], v[66:69]
	v_mfma_f32_16x16x32_bf16 v[66:69], v[158:161], v[206:209], v[66:69]
	v_mfma_f32_16x16x32_bf16 v[74:77], v[162:165], v[202:205], v[74:77]
	v_mfma_f32_16x16x32_bf16 v[74:77], v[166:169], v[206:209], v[74:77]
	v_mfma_f32_16x16x32_bf16 v[70:73], v[170:173], v[202:205], v[70:73]
	v_mfma_f32_16x16x32_bf16 v[70:73], v[174:177], v[206:209], v[70:73]
	s_setprio 0
	s_barrier
	s_mov_b32 m0, s31
	s_mov_b32 s22, s18
	s_mov_b32 s23, s19
	ds_read_b128 v[178:181], v140 offset:16384
	ds_read_b128 v[182:185], v140 offset:17408
	ds_read_b128 v[186:189], v140 offset:18432
	ds_read_b128 v[190:193], v140 offset:19456
	ds_read_b128 v[194:197], v140 offset:20480
	ds_read_b128 v[198:201], v140 offset:21504
	ds_read_b128 v[202:205], v140 offset:22528
	ds_read_b128 v[206:209], v140 offset:23552
	buffer_load_dwordx4 v137, s[20:23], s80 offen lds
	s_add_i32 s81, s80, 0x80000
	s_mov_b32 m0, s48
	s_nop 0
	buffer_load_dwordx4 v137, s[20:23], s81 offen lds
	s_add_i32 s81, s80, 0x100000
	s_mov_b32 m0, s49
	s_nop 0
	buffer_load_dwordx4 v137, s[20:23], s81 offen lds
	s_add_i32 s81, s80, 0x180000
	s_mov_b32 m0, s50
	s_nop 0
	buffer_load_dwordx4 v137, s[20:23], s81 offen lds
	s_mov_b32 m0, s30
	s_add_i32 s81, s78, 0x80000
	buffer_load_dwordx4 v136, s[16:19], s78 offen lds
	s_mov_b32 m0, s51
	s_nop 0
	buffer_load_dwordx4 v136, s[16:19], s81 offen lds
	s_waitcnt vmcnt(8)
	s_waitcnt lgkmcnt(0)
	s_setprio 1
	v_mfma_f32_16x16x32_bf16 v[62:65], v[146:149], v[178:181], v[62:65]
	s_barrier
	v_mfma_f32_16x16x32_bf16 v[62:65], v[150:153], v[182:185], v[62:65]
	v_mfma_f32_16x16x32_bf16 v[54:57], v[154:157], v[178:181], v[54:57]
	v_mfma_f32_16x16x32_bf16 v[54:57], v[158:161], v[182:185], v[54:57]
	v_mfma_f32_16x16x32_bf16 v[58:61], v[162:165], v[178:181], v[58:61]
	v_mfma_f32_16x16x32_bf16 v[58:61], v[166:169], v[182:185], v[58:61]
	v_mfma_f32_16x16x32_bf16 v[50:53], v[170:173], v[178:181], v[50:53]
	v_mfma_f32_16x16x32_bf16 v[50:53], v[174:177], v[182:185], v[50:53]
	v_mfma_f32_16x16x32_bf16 v[46:49], v[146:149], v[186:189], v[46:49]
	v_mfma_f32_16x16x32_bf16 v[46:49], v[150:153], v[190:193], v[46:49]
	v_mfma_f32_16x16x32_bf16 v[38:41], v[154:157], v[186:189], v[38:41]
	v_mfma_f32_16x16x32_bf16 v[38:41], v[158:161], v[190:193], v[38:41]
	v_mfma_f32_16x16x32_bf16 v[42:45], v[162:165], v[186:189], v[42:45]
	v_mfma_f32_16x16x32_bf16 v[42:45], v[166:169], v[190:193], v[42:45]
	v_mfma_f32_16x16x32_bf16 v[34:37], v[170:173], v[186:189], v[34:37]
	v_mfma_f32_16x16x32_bf16 v[34:37], v[174:177], v[190:193], v[34:37]
	v_mfma_f32_16x16x32_bf16 v[30:33], v[146:149], v[194:197], v[30:33]
	v_mfma_f32_16x16x32_bf16 v[30:33], v[150:153], v[198:201], v[30:33]
	v_mfma_f32_16x16x32_bf16 v[22:25], v[154:157], v[194:197], v[22:25]
	v_mfma_f32_16x16x32_bf16 v[22:25], v[158:161], v[198:201], v[22:25]
	v_mfma_f32_16x16x32_bf16 v[26:29], v[162:165], v[194:197], v[26:29]
	v_mfma_f32_16x16x32_bf16 v[26:29], v[166:169], v[198:201], v[26:29]
	v_mfma_f32_16x16x32_bf16 v[18:21], v[170:173], v[194:197], v[18:21]
	v_mfma_f32_16x16x32_bf16 v[18:21], v[174:177], v[198:201], v[18:21]
	v_mfma_f32_16x16x32_bf16 v[14:17], v[146:149], v[202:205], v[14:17]
	v_mfma_f32_16x16x32_bf16 v[14:17], v[150:153], v[206:209], v[14:17]
	v_mfma_f32_16x16x32_bf16 v[6:9], v[154:157], v[202:205], v[6:9]
	v_mfma_f32_16x16x32_bf16 v[6:9], v[158:161], v[206:209], v[6:9]
	v_mfma_f32_16x16x32_bf16 v[10:13], v[162:165], v[202:205], v[10:13]
	v_mfma_f32_16x16x32_bf16 v[10:13], v[166:169], v[206:209], v[10:13]
	v_mfma_f32_16x16x32_bf16 v[2:5], v[170:173], v[202:205], v[2:5]
	v_mfma_f32_16x16x32_bf16 v[2:5], v[174:177], v[206:209], v[2:5]
	s_setprio 0
	s_barrier
	ds_read_b128 v[146:149], v141
	ds_read_b128 v[150:153], v141 offset:1024
	ds_read_b128 v[154:157], v141 offset:2048
	ds_read_b128 v[158:161], v141 offset:3072
	ds_read_b128 v[162:165], v142
	ds_read_b128 v[166:169], v142 offset:1024
	ds_read_b128 v[170:173], v142 offset:2048
	ds_read_b128 v[174:177], v142 offset:3072
	s_mov_b32 m0, s52
	s_add_i32 s81, s78, 0x100000
	ds_read_b128 v[178:181], v140 offset:32768
	ds_read_b128 v[182:185], v140 offset:33792
	ds_read_b128 v[186:189], v140 offset:34816
	ds_read_b128 v[190:193], v140 offset:35840
	ds_read_b128 v[194:197], v140 offset:36864
	ds_read_b128 v[198:201], v140 offset:37888
	ds_read_b128 v[202:205], v140 offset:38912
	ds_read_b128 v[206:209], v140 offset:39936
	buffer_load_dwordx4 v136, s[16:19], s81 offen lds
	s_add_i32 s81, s78, 0x180000
	s_mov_b32 m0, s53
	s_nop 0
	buffer_load_dwordx4 v136, s[16:19], s81 offen lds
	s_waitcnt vmcnt(8)
	s_waitcnt lgkmcnt(0)
	s_setprio 1
	v_mfma_f32_16x16x32_bf16 v[118:121], v[146:149], v[178:181], v[118:121]
	s_barrier
	v_mfma_f32_16x16x32_bf16 v[118:121], v[150:153], v[182:185], v[118:121]
	v_mfma_f32_16x16x32_bf16 v[114:117], v[154:157], v[178:181], v[114:117]
	v_mfma_f32_16x16x32_bf16 v[114:117], v[158:161], v[182:185], v[114:117]
	v_mfma_f32_16x16x32_bf16 v[126:129], v[162:165], v[178:181], v[126:129]
	v_mfma_f32_16x16x32_bf16 v[126:129], v[166:169], v[182:185], v[126:129]
	v_mfma_f32_16x16x32_bf16 v[122:125], v[170:173], v[178:181], v[122:125]
	v_mfma_f32_16x16x32_bf16 v[122:125], v[174:177], v[182:185], v[122:125]
	v_mfma_f32_16x16x32_bf16 v[110:113], v[146:149], v[186:189], v[110:113]
	v_mfma_f32_16x16x32_bf16 v[110:113], v[150:153], v[190:193], v[110:113]
	v_mfma_f32_16x16x32_bf16 v[102:105], v[154:157], v[186:189], v[102:105]
	v_mfma_f32_16x16x32_bf16 v[102:105], v[158:161], v[190:193], v[102:105]
	v_mfma_f32_16x16x32_bf16 v[106:109], v[162:165], v[186:189], v[106:109]
	v_mfma_f32_16x16x32_bf16 v[106:109], v[166:169], v[190:193], v[106:109]
	v_mfma_f32_16x16x32_bf16 v[98:101], v[170:173], v[186:189], v[98:101]
	v_mfma_f32_16x16x32_bf16 v[98:101], v[174:177], v[190:193], v[98:101]
	v_mfma_f32_16x16x32_bf16 v[94:97], v[146:149], v[194:197], v[94:97]
	v_mfma_f32_16x16x32_bf16 v[94:97], v[150:153], v[198:201], v[94:97]
	v_mfma_f32_16x16x32_bf16 v[86:89], v[154:157], v[194:197], v[86:89]
	v_mfma_f32_16x16x32_bf16 v[86:89], v[158:161], v[198:201], v[86:89]
	v_mfma_f32_16x16x32_bf16 v[90:93], v[162:165], v[194:197], v[90:93]
	v_mfma_f32_16x16x32_bf16 v[90:93], v[166:169], v[198:201], v[90:93]
	v_mfma_f32_16x16x32_bf16 v[82:85], v[170:173], v[194:197], v[82:85]
	v_mfma_f32_16x16x32_bf16 v[82:85], v[174:177], v[198:201], v[82:85]
	v_mfma_f32_16x16x32_bf16 v[78:81], v[146:149], v[202:205], v[78:81]
	v_mfma_f32_16x16x32_bf16 v[78:81], v[150:153], v[206:209], v[78:81]
	v_mfma_f32_16x16x32_bf16 v[66:69], v[154:157], v[202:205], v[66:69]
	v_mfma_f32_16x16x32_bf16 v[66:69], v[158:161], v[206:209], v[66:69]
	v_mfma_f32_16x16x32_bf16 v[74:77], v[162:165], v[202:205], v[74:77]
	v_mfma_f32_16x16x32_bf16 v[74:77], v[166:169], v[206:209], v[74:77]
	v_mfma_f32_16x16x32_bf16 v[70:73], v[170:173], v[202:205], v[70:73]
	v_mfma_f32_16x16x32_bf16 v[70:73], v[174:177], v[206:209], v[70:73]
	s_setprio 0
	s_barrier
	s_mov_b32 m0, s54
	s_or_b32 s81, s80, 0x80
	ds_read_b128 v[178:181], v140 offset:49152
	ds_read_b128 v[182:185], v140 offset:50176
	ds_read_b128 v[186:189], v140 offset:51200
	ds_read_b128 v[190:193], v140 offset:52224
	ds_read_b128 v[194:197], v140 offset:53248
	ds_read_b128 v[198:201], v140 offset:54272
	ds_read_b128 v[202:205], v140 offset:55296
	ds_read_b128 v[206:209], v140 offset:56320
	buffer_load_dwordx4 v137, s[20:23], s81 offen lds
	s_add_i32 s81, s80, 0x80080
	s_mov_b32 m0, s55
	s_add_i32 s78, s78, 0x80080
	buffer_load_dwordx4 v137, s[20:23], s81 offen lds
	s_add_i32 s81, s80, 0x100080
	s_mov_b32 m0, s58
	s_add_i32 s80, s80, 0x180080
	buffer_load_dwordx4 v137, s[20:23], s81 offen lds
	s_mov_b32 m0, s59
	s_nop 0
	buffer_load_dwordx4 v137, s[20:23], s80 offen lds
	s_mov_b32 m0, s56
	s_nop 0
	buffer_load_dwordx4 v136, s[16:19], s79 offen lds
	s_mov_b32 m0, s57
	s_nop 0
	buffer_load_dwordx4 v136, s[16:19], s78 offen lds
	s_waitcnt vmcnt(8)
	s_waitcnt lgkmcnt(0)
	s_setprio 1
	v_mfma_f32_16x16x32_bf16 v[62:65], v[146:149], v[178:181], v[62:65]
	s_barrier
	v_mfma_f32_16x16x32_bf16 v[62:65], v[150:153], v[182:185], v[62:65]
	v_mfma_f32_16x16x32_bf16 v[54:57], v[154:157], v[178:181], v[54:57]
	v_mfma_f32_16x16x32_bf16 v[54:57], v[158:161], v[182:185], v[54:57]
	v_mfma_f32_16x16x32_bf16 v[58:61], v[162:165], v[178:181], v[58:61]
	v_mfma_f32_16x16x32_bf16 v[58:61], v[166:169], v[182:185], v[58:61]
	v_mfma_f32_16x16x32_bf16 v[50:53], v[170:173], v[178:181], v[50:53]
	v_mfma_f32_16x16x32_bf16 v[50:53], v[174:177], v[182:185], v[50:53]
	v_mfma_f32_16x16x32_bf16 v[46:49], v[146:149], v[186:189], v[46:49]
	v_mfma_f32_16x16x32_bf16 v[46:49], v[150:153], v[190:193], v[46:49]
	v_mfma_f32_16x16x32_bf16 v[38:41], v[154:157], v[186:189], v[38:41]
	v_mfma_f32_16x16x32_bf16 v[38:41], v[158:161], v[190:193], v[38:41]
	v_mfma_f32_16x16x32_bf16 v[42:45], v[162:165], v[186:189], v[42:45]
	v_mfma_f32_16x16x32_bf16 v[42:45], v[166:169], v[190:193], v[42:45]
	v_mfma_f32_16x16x32_bf16 v[34:37], v[170:173], v[186:189], v[34:37]
	v_mfma_f32_16x16x32_bf16 v[34:37], v[174:177], v[190:193], v[34:37]
	v_mfma_f32_16x16x32_bf16 v[30:33], v[146:149], v[194:197], v[30:33]
	v_mfma_f32_16x16x32_bf16 v[30:33], v[150:153], v[198:201], v[30:33]
	v_mfma_f32_16x16x32_bf16 v[22:25], v[154:157], v[194:197], v[22:25]
	v_mfma_f32_16x16x32_bf16 v[22:25], v[158:161], v[198:201], v[22:25]
	v_mfma_f32_16x16x32_bf16 v[26:29], v[162:165], v[194:197], v[26:29]
	v_mfma_f32_16x16x32_bf16 v[26:29], v[166:169], v[198:201], v[26:29]
	v_mfma_f32_16x16x32_bf16 v[18:21], v[170:173], v[194:197], v[18:21]
	v_mfma_f32_16x16x32_bf16 v[18:21], v[174:177], v[198:201], v[18:21]
	v_mfma_f32_16x16x32_bf16 v[14:17], v[146:149], v[202:205], v[14:17]
	v_mfma_f32_16x16x32_bf16 v[14:17], v[150:153], v[206:209], v[14:17]
	v_mfma_f32_16x16x32_bf16 v[6:9], v[154:157], v[202:205], v[6:9]
	v_mfma_f32_16x16x32_bf16 v[6:9], v[158:161], v[206:209], v[6:9]
	v_mfma_f32_16x16x32_bf16 v[10:13], v[162:165], v[202:205], v[10:13]
	v_mfma_f32_16x16x32_bf16 v[10:13], v[166:169], v[206:209], v[10:13]
	v_mfma_f32_16x16x32_bf16 v[2:5], v[170:173], v[202:205], v[2:5]
	v_mfma_f32_16x16x32_bf16 v[2:5], v[174:177], v[206:209], v[2:5]
	s_setprio 0
	s_barrier
	s_add_i32 s77, s77, 2
	s_addk_i32 s75, 0x100
	s_addk_i32 s76, 0x100
	s_cmp_ge_i32 s77, s13
	s_cbranch_scc0 .LBB0_1402
	s_and_b64 vcc, exec, s[46:47]
	s_cbranch_vccz .LBB0_1405

.LBB0_1519:
	ds_read_b128 v[134:137], v208
	ds_read_b128 v[138:141], v208 offset:1024
	ds_read_b128 v[142:145], v208 offset:2048
	ds_read_b128 v[146:149], v208 offset:3072
	ds_read_b128 v[150:153], v209
	ds_read_b128 v[154:157], v209 offset:1024
	ds_read_b128 v[158:161], v209 offset:2048
	ds_read_b128 v[162:165], v209 offset:3072
	s_add_i32 s18, s80, 0xffbf8080
	s_cmp_eq_u32 s65, s82
	s_cselect_b32 s83, s6, s18
	s_cselect_b32 s85, s7, s81
	s_or_b32 s84, s83, 0x80
	s_add_i32 s18, s80, 0xffea8000
	s_mov_b32 m0, s66
	ds_read_b128 v[166:169], v210
	ds_read_b128 v[170:173], v210 offset:1024
	ds_read_b128 v[174:177], v210 offset:2048
	ds_read_b128 v[178:181], v210 offset:3072
	ds_read_b128 v[182:185], v210 offset:4096
	ds_read_b128 v[186:189], v210 offset:5120
	ds_read_b128 v[190:193], v210 offset:6144
	ds_read_b128 v[194:197], v210 offset:7168
	buffer_load_dwordx4 v206, s[12:15], s18 offen lds
	s_mov_b32 m0, s69
	s_nop 0
	buffer_load_dwordx4 v206, s[12:15], s80 offen lds
	s_waitcnt vmcnt(8)
	s_waitcnt lgkmcnt(0)
	s_setprio 1
	v_mfma_f32_16x16x32_bf16 v[126:129], v[134:137], v[166:169], v[126:129]
	s_barrier
	v_mfma_f32_16x16x32_bf16 v[126:129], v[138:141], v[170:173], v[126:129]
	v_mfma_f32_16x16x32_bf16 v[122:125], v[142:145], v[166:169], v[122:125]
	v_mfma_f32_16x16x32_bf16 v[122:125], v[146:149], v[170:173], v[122:125]
	v_mfma_f32_16x16x32_bf16 v[110:113], v[150:153], v[166:169], v[110:113]
	v_mfma_f32_16x16x32_bf16 v[110:113], v[154:157], v[170:173], v[110:113]
	v_mfma_f32_16x16x32_bf16 v[102:105], v[158:161], v[166:169], v[102:105]
	v_mfma_f32_16x16x32_bf16 v[102:105], v[162:165], v[170:173], v[102:105]
	v_mfma_f32_16x16x32_bf16 v[118:121], v[134:137], v[174:177], v[118:121]
	v_mfma_f32_16x16x32_bf16 v[118:121], v[138:141], v[178:181], v[118:121]
	v_mfma_f32_16x16x32_bf16 v[114:117], v[142:145], v[174:177], v[114:117]
	v_mfma_f32_16x16x32_bf16 v[114:117], v[146:149], v[178:181], v[114:117]
	v_mfma_f32_16x16x32_bf16 v[94:97], v[150:153], v[174:177], v[94:97]
	v_mfma_f32_16x16x32_bf16 v[94:97], v[154:157], v[178:181], v[94:97]
	v_mfma_f32_16x16x32_bf16 v[86:89], v[158:161], v[174:177], v[86:89]
	v_mfma_f32_16x16x32_bf16 v[86:89], v[162:165], v[178:181], v[86:89]
	v_mfma_f32_16x16x32_bf16 v[106:109], v[134:137], v[182:185], v[106:109]
	v_mfma_f32_16x16x32_bf16 v[106:109], v[138:141], v[186:189], v[106:109]
	v_mfma_f32_16x16x32_bf16 v[98:101], v[142:145], v[182:185], v[98:101]
	v_mfma_f32_16x16x32_bf16 v[98:101], v[146:149], v[186:189], v[98:101]
	v_mfma_f32_16x16x32_bf16 v[78:81], v[150:153], v[182:185], v[78:81]
	v_mfma_f32_16x16x32_bf16 v[78:81], v[154:157], v[186:189], v[78:81]
	v_mfma_f32_16x16x32_bf16 v[74:77], v[158:161], v[182:185], v[74:77]
	v_mfma_f32_16x16x32_bf16 v[74:77], v[162:165], v[186:189], v[74:77]
	v_mfma_f32_16x16x32_bf16 v[90:93], v[134:137], v[190:193], v[90:93]
	v_mfma_f32_16x16x32_bf16 v[90:93], v[138:141], v[194:197], v[90:93]
	v_mfma_f32_16x16x32_bf16 v[82:85], v[142:145], v[190:193], v[82:85]
	v_mfma_f32_16x16x32_bf16 v[82:85], v[146:149], v[194:197], v[82:85]
	v_mfma_f32_16x16x32_bf16 v[70:73], v[150:153], v[190:193], v[70:73]
	v_mfma_f32_16x16x32_bf16 v[70:73], v[154:157], v[194:197], v[70:73]
	v_mfma_f32_16x16x32_bf16 v[66:69], v[158:161], v[190:193], v[66:69]
	v_mfma_f32_16x16x32_bf16 v[66:69], v[162:165], v[194:197], v[66:69]
	s_setprio 0
	s_barrier
	s_mov_b32 m0, s27
	s_mov_b32 s18, s14
	s_mov_b32 s19, s15
	ds_read_b128 v[166:169], v210 offset:16384
	ds_read_b128 v[170:173], v210 offset:17408
	ds_read_b128 v[174:177], v210 offset:18432
	ds_read_b128 v[178:181], v210 offset:19456
	ds_read_b128 v[182:185], v210 offset:20480
	ds_read_b128 v[186:189], v210 offset:21504
	ds_read_b128 v[190:193], v210 offset:22528
	ds_read_b128 v[194:197], v210 offset:23552
	buffer_load_dwordx4 v207, s[16:19], s85 offen lds
	s_add_i32 s86, s85, 0x158000
	s_mov_b32 m0, s30
	s_nop 0
	buffer_load_dwordx4 v207, s[16:19], s86 offen lds
	s_add_i32 s86, s85, 0x2b0000
	s_mov_b32 m0, s31
	s_nop 0
	buffer_load_dwordx4 v207, s[16:19], s86 offen lds
	s_add_i32 s86, s85, 0x408000
	s_mov_b32 m0, s50
	s_nop 0
	buffer_load_dwordx4 v207, s[16:19], s86 offen lds
	s_mov_b32 m0, s25
	s_add_i32 s86, s83, 0x158000
	buffer_load_dwordx4 v206, s[12:15], s83 offen lds
	s_mov_b32 m0, s51
	s_nop 0
	buffer_load_dwordx4 v206, s[12:15], s86 offen lds
	s_waitcnt vmcnt(8)
	s_waitcnt lgkmcnt(0)
	s_setprio 1
	v_mfma_f32_16x16x32_bf16 v[62:65], v[134:137], v[166:169], v[62:65]
	s_barrier
	v_mfma_f32_16x16x32_bf16 v[62:65], v[138:141], v[170:173], v[62:65]
	v_mfma_f32_16x16x32_bf16 v[58:61], v[142:145], v[166:169], v[58:61]
	v_mfma_f32_16x16x32_bf16 v[58:61], v[146:149], v[170:173], v[58:61]
	v_mfma_f32_16x16x32_bf16 v[46:49], v[150:153], v[166:169], v[46:49]
	v_mfma_f32_16x16x32_bf16 v[46:49], v[154:157], v[170:173], v[46:49]
	v_mfma_f32_16x16x32_bf16 v[38:41], v[158:161], v[166:169], v[38:41]
	v_mfma_f32_16x16x32_bf16 v[38:41], v[162:165], v[170:173], v[38:41]
	v_mfma_f32_16x16x32_bf16 v[54:57], v[134:137], v[174:177], v[54:57]
	v_mfma_f32_16x16x32_bf16 v[54:57], v[138:141], v[178:181], v[54:57]
	v_mfma_f32_16x16x32_bf16 v[50:53], v[142:145], v[174:177], v[50:53]
	v_mfma_f32_16x16x32_bf16 v[50:53], v[146:149], v[178:181], v[50:53]
	v_mfma_f32_16x16x32_bf16 v[30:33], v[150:153], v[174:177], v[30:33]
	v_mfma_f32_16x16x32_bf16 v[30:33], v[154:157], v[178:181], v[30:33]
	v_mfma_f32_16x16x32_bf16 v[22:25], v[158:161], v[174:177], v[22:25]
	v_mfma_f32_16x16x32_bf16 v[22:25], v[162:165], v[178:181], v[22:25]
	v_mfma_f32_16x16x32_bf16 v[42:45], v[134:137], v[182:185], v[42:45]
	v_mfma_f32_16x16x32_bf16 v[42:45], v[138:141], v[186:189], v[42:45]
	v_mfma_f32_16x16x32_bf16 v[34:37], v[142:145], v[182:185], v[34:37]
	v_mfma_f32_16x16x32_bf16 v[34:37], v[146:149], v[186:189], v[34:37]
	v_mfma_f32_16x16x32_bf16 v[14:17], v[150:153], v[182:185], v[14:17]
	v_mfma_f32_16x16x32_bf16 v[14:17], v[154:157], v[186:189], v[14:17]
	v_mfma_f32_16x16x32_bf16 v[10:13], v[158:161], v[182:185], v[10:13]
	v_mfma_f32_16x16x32_bf16 v[10:13], v[162:165], v[186:189], v[10:13]
	v_mfma_f32_16x16x32_bf16 v[26:29], v[134:137], v[190:193], v[26:29]
	v_mfma_f32_16x16x32_bf16 v[26:29], v[138:141], v[194:197], v[26:29]
	v_mfma_f32_16x16x32_bf16 v[18:21], v[142:145], v[190:193], v[18:21]
	v_mfma_f32_16x16x32_bf16 v[18:21], v[146:149], v[194:197], v[18:21]
	v_mfma_f32_16x16x32_bf16 v[6:9], v[150:153], v[190:193], v[6:9]
	v_mfma_f32_16x16x32_bf16 v[6:9], v[154:157], v[194:197], v[6:9]
	v_mfma_f32_16x16x32_bf16 v[2:5], v[158:161], v[190:193], v[2:5]
	v_mfma_f32_16x16x32_bf16 v[2:5], v[162:165], v[194:197], v[2:5]
	s_setprio 0
	s_barrier
	ds_read_b128 v[134:137], v211
	ds_read_b128 v[138:141], v211 offset:1024
	ds_read_b128 v[142:145], v211 offset:2048
	ds_read_b128 v[146:149], v211 offset:3072
	ds_read_b128 v[150:153], v212
	ds_read_b128 v[154:157], v212 offset:1024
	ds_read_b128 v[158:161], v212 offset:2048
	ds_read_b128 v[162:165], v212 offset:3072
	s_mov_b32 m0, s52
	s_add_i32 s86, s83, 0x2b0000
	ds_read_b128 v[166:169], v210 offset:32768
	ds_read_b128 v[170:173], v210 offset:33792
	ds_read_b128 v[174:177], v210 offset:34816
	ds_read_b128 v[178:181], v210 offset:35840
	ds_read_b128 v[182:185], v210 offset:36864
	ds_read_b128 v[186:189], v210 offset:37888
	ds_read_b128 v[190:193], v210 offset:38912
	ds_read_b128 v[194:197], v210 offset:39936
	buffer_load_dwordx4 v206, s[12:15], s86 offen lds
	s_add_i32 s86, s83, 0x408000
	s_mov_b32 m0, s53
	s_nop 0
	buffer_load_dwordx4 v206, s[12:15], s86 offen lds
	s_waitcnt vmcnt(8)
	s_waitcnt lgkmcnt(0)
	s_setprio 1
	v_mfma_f32_16x16x32_bf16 v[126:129], v[134:137], v[166:169], v[126:129]
	s_barrier
	v_mfma_f32_16x16x32_bf16 v[126:129], v[138:141], v[170:173], v[126:129]
	v_mfma_f32_16x16x32_bf16 v[122:125], v[142:145], v[166:169], v[122:125]
	v_mfma_f32_16x16x32_bf16 v[122:125], v[146:149], v[170:173], v[122:125]
	v_mfma_f32_16x16x32_bf16 v[110:113], v[150:153], v[166:169], v[110:113]
	v_mfma_f32_16x16x32_bf16 v[110:113], v[154:157], v[170:173], v[110:113]
	v_mfma_f32_16x16x32_bf16 v[102:105], v[158:161], v[166:169], v[102:105]
	v_mfma_f32_16x16x32_bf16 v[102:105], v[162:165], v[170:173], v[102:105]
	v_mfma_f32_16x16x32_bf16 v[118:121], v[134:137], v[174:177], v[118:121]
	v_mfma_f32_16x16x32_bf16 v[118:121], v[138:141], v[178:181], v[118:121]
	v_mfma_f32_16x16x32_bf16 v[114:117], v[142:145], v[174:177], v[114:117]
	v_mfma_f32_16x16x32_bf16 v[114:117], v[146:149], v[178:181], v[114:117]
	v_mfma_f32_16x16x32_bf16 v[94:97], v[150:153], v[174:177], v[94:97]
	v_mfma_f32_16x16x32_bf16 v[94:97], v[154:157], v[178:181], v[94:97]
	v_mfma_f32_16x16x32_bf16 v[86:89], v[158:161], v[174:177], v[86:89]
	v_mfma_f32_16x16x32_bf16 v[86:89], v[162:165], v[178:181], v[86:89]
	v_mfma_f32_16x16x32_bf16 v[106:109], v[134:137], v[182:185], v[106:109]
	v_mfma_f32_16x16x32_bf16 v[106:109], v[138:141], v[186:189], v[106:109]
	v_mfma_f32_16x16x32_bf16 v[98:101], v[142:145], v[182:185], v[98:101]
	v_mfma_f32_16x16x32_bf16 v[98:101], v[146:149], v[186:189], v[98:101]
	v_mfma_f32_16x16x32_bf16 v[78:81], v[150:153], v[182:185], v[78:81]
	v_mfma_f32_16x16x32_bf16 v[78:81], v[154:157], v[186:189], v[78:81]
	v_mfma_f32_16x16x32_bf16 v[74:77], v[158:161], v[182:185], v[74:77]
	v_mfma_f32_16x16x32_bf16 v[74:77], v[162:165], v[186:189], v[74:77]
	v_mfma_f32_16x16x32_bf16 v[90:93], v[134:137], v[190:193], v[90:93]
	v_mfma_f32_16x16x32_bf16 v[90:93], v[138:141], v[194:197], v[90:93]
	v_mfma_f32_16x16x32_bf16 v[82:85], v[142:145], v[190:193], v[82:85]
	v_mfma_f32_16x16x32_bf16 v[82:85], v[146:149], v[194:197], v[82:85]
	v_mfma_f32_16x16x32_bf16 v[70:73], v[150:153], v[190:193], v[70:73]
	v_mfma_f32_16x16x32_bf16 v[70:73], v[154:157], v[194:197], v[70:73]
	v_mfma_f32_16x16x32_bf16 v[66:69], v[158:161], v[190:193], v[66:69]
	v_mfma_f32_16x16x32_bf16 v[66:69], v[162:165], v[194:197], v[66:69]
	s_setprio 0
	s_barrier
	s_mov_b32 m0, s57
	s_or_b32 s86, s85, 0x80
	ds_read_b128 v[166:169], v210 offset:49152
	ds_read_b128 v[170:173], v210 offset:50176
	ds_read_b128 v[174:177], v210 offset:51200
	ds_read_b128 v[178:181], v210 offset:52224
	ds_read_b128 v[182:185], v210 offset:53248
	ds_read_b128 v[186:189], v210 offset:54272
	ds_read_b128 v[190:193], v210 offset:55296
	ds_read_b128 v[194:197], v210 offset:56320
	buffer_load_dwordx4 v207, s[16:19], s86 offen lds
	s_add_i32 s86, s85, 0x158080
	s_mov_b32 m0, s58
	s_add_i32 s83, s83, 0x158080
	buffer_load_dwordx4 v207, s[16:19], s86 offen lds
	s_add_i32 s86, s85, 0x2b0080
	s_mov_b32 m0, s61
	s_add_i32 s85, s85, 0x408080
	buffer_load_dwordx4 v207, s[16:19], s86 offen lds
	s_mov_b32 m0, s62
	s_nop 0
	buffer_load_dwordx4 v207, s[16:19], s85 offen lds
	s_mov_b32 m0, s59
	s_nop 0
	buffer_load_dwordx4 v206, s[12:15], s84 offen lds
	s_mov_b32 m0, s60
	s_nop 0
	buffer_load_dwordx4 v206, s[12:15], s83 offen lds
	s_waitcnt vmcnt(8)
	s_waitcnt lgkmcnt(0)
	s_setprio 1
	v_mfma_f32_16x16x32_bf16 v[62:65], v[134:137], v[166:169], v[62:65]
	s_barrier
	v_mfma_f32_16x16x32_bf16 v[62:65], v[138:141], v[170:173], v[62:65]
	v_mfma_f32_16x16x32_bf16 v[58:61], v[142:145], v[166:169], v[58:61]
	v_mfma_f32_16x16x32_bf16 v[58:61], v[146:149], v[170:173], v[58:61]
	v_mfma_f32_16x16x32_bf16 v[46:49], v[150:153], v[166:169], v[46:49]
	v_mfma_f32_16x16x32_bf16 v[46:49], v[154:157], v[170:173], v[46:49]
	v_mfma_f32_16x16x32_bf16 v[38:41], v[158:161], v[166:169], v[38:41]
	v_mfma_f32_16x16x32_bf16 v[38:41], v[162:165], v[170:173], v[38:41]
	v_mfma_f32_16x16x32_bf16 v[54:57], v[134:137], v[174:177], v[54:57]
	v_mfma_f32_16x16x32_bf16 v[54:57], v[138:141], v[178:181], v[54:57]
	v_mfma_f32_16x16x32_bf16 v[50:53], v[142:145], v[174:177], v[50:53]
	v_mfma_f32_16x16x32_bf16 v[50:53], v[146:149], v[178:181], v[50:53]
	v_mfma_f32_16x16x32_bf16 v[30:33], v[150:153], v[174:177], v[30:33]
	v_mfma_f32_16x16x32_bf16 v[30:33], v[154:157], v[178:181], v[30:33]
	v_mfma_f32_16x16x32_bf16 v[22:25], v[158:161], v[174:177], v[22:25]
	v_mfma_f32_16x16x32_bf16 v[22:25], v[162:165], v[178:181], v[22:25]
	v_mfma_f32_16x16x32_bf16 v[42:45], v[134:137], v[182:185], v[42:45]
	v_mfma_f32_16x16x32_bf16 v[42:45], v[138:141], v[186:189], v[42:45]
	v_mfma_f32_16x16x32_bf16 v[34:37], v[142:145], v[182:185], v[34:37]
	v_mfma_f32_16x16x32_bf16 v[34:37], v[146:149], v[186:189], v[34:37]
	v_mfma_f32_16x16x32_bf16 v[14:17], v[150:153], v[182:185], v[14:17]
	v_mfma_f32_16x16x32_bf16 v[14:17], v[154:157], v[186:189], v[14:17]
	v_mfma_f32_16x16x32_bf16 v[10:13], v[158:161], v[182:185], v[10:13]
	v_mfma_f32_16x16x32_bf16 v[10:13], v[162:165], v[186:189], v[10:13]
	v_mfma_f32_16x16x32_bf16 v[26:29], v[134:137], v[190:193], v[26:29]
	v_mfma_f32_16x16x32_bf16 v[26:29], v[138:141], v[194:197], v[26:29]
	v_mfma_f32_16x16x32_bf16 v[18:21], v[142:145], v[190:193], v[18:21]
	v_mfma_f32_16x16x32_bf16 v[18:21], v[146:149], v[194:197], v[18:21]
	v_mfma_f32_16x16x32_bf16 v[6:9], v[150:153], v[190:193], v[6:9]
	v_mfma_f32_16x16x32_bf16 v[6:9], v[154:157], v[194:197], v[6:9]
	v_mfma_f32_16x16x32_bf16 v[2:5], v[158:161], v[190:193], v[2:5]
	v_mfma_f32_16x16x32_bf16 v[2:5], v[162:165], v[194:197], v[2:5]
	s_setprio 0
	s_barrier
	s_add_i32 s82, s82, 2
	s_addk_i32 s80, 0x100
	s_addk_i32 s81, 0x100
	s_cmp_ge_i32 s82, s3
	s_cbranch_scc0 .LBB0_1519
	v_pk_mul_f32 v[182:183], v[128:129], 0.5 op_sel_hi:[1,0]
	v_pk_mul_f32 v[184:185], v[126:127], 0.5 op_sel_hi:[1,0]
	v_pk_mul_f32 v[186:187], v[124:125], 0.5 op_sel_hi:[1,0]
	v_pk_mul_f32 v[188:189], v[122:123], 0.5 op_sel_hi:[1,0]
	v_pk_mul_f32 v[196:197], v[112:113], 0.5 op_sel_hi:[1,0]
	v_pk_mul_f32 v[194:195], v[110:111], 0.5 op_sel_hi:[1,0]
	v_pk_mul_f32 v[192:193], v[104:105], 0.5 op_sel_hi:[1,0]
	v_pk_mul_f32 v[190:191], v[102:103], 0.5 op_sel_hi:[1,0]
	v_pk_mul_f32 v[180:181], v[120:121], 0.5 op_sel_hi:[1,0]
	v_pk_mul_f32 v[178:179], v[118:119], 0.5 op_sel_hi:[1,0]
	v_pk_mul_f32 v[176:177], v[116:117], 0.5 op_sel_hi:[1,0]
	v_pk_mul_f32 v[174:175], v[114:115], 0.5 op_sel_hi:[1,0]
	v_pk_mul_f32 v[170:171], v[96:97], 0.5 op_sel_hi:[1,0]
	v_pk_mul_f32 v[168:169], v[94:95], 0.5 op_sel_hi:[1,0]
	v_pk_mul_f32 v[166:167], v[88:89], 0.5 op_sel_hi:[1,0]
	v_pk_mul_f32 v[164:165], v[86:87], 0.5 op_sel_hi:[1,0]
	v_pk_mul_f32 v[162:163], v[108:109], 0.5 op_sel_hi:[1,0]
	v_pk_mul_f32 v[160:161], v[106:107], 0.5 op_sel_hi:[1,0]
	v_pk_mul_f32 v[158:159], v[100:101], 0.5 op_sel_hi:[1,0]
	v_pk_mul_f32 v[156:157], v[98:99], 0.5 op_sel_hi:[1,0]
	v_pk_mul_f32 v[154:155], v[80:81], 0.5 op_sel_hi:[1,0]
	v_pk_mul_f32 v[152:153], v[78:79], 0.5 op_sel_hi:[1,0]
	v_pk_mul_f32 v[150:151], v[76:77], 0.5 op_sel_hi:[1,0]
	v_pk_mul_f32 v[148:149], v[74:75], 0.5 op_sel_hi:[1,0]
	v_pk_mul_f32 v[144:145], v[92:93], 0.5 op_sel_hi:[1,0]
	v_pk_mul_f32 v[142:143], v[90:91], 0.5 op_sel_hi:[1,0]
	v_pk_mul_f32 v[140:141], v[84:85], 0.5 op_sel_hi:[1,0]
	v_pk_mul_f32 v[138:139], v[82:83], 0.5 op_sel_hi:[1,0]
	v_pk_mul_f32 v[136:137], v[72:73], 0.5 op_sel_hi:[1,0]
	v_pk_mul_f32 v[134:135], v[70:71], 0.5 op_sel_hi:[1,0]
	v_pk_mul_f32 v[128:129], v[68:69], 0.5 op_sel_hi:[1,0]
	v_pk_mul_f32 v[126:127], v[66:67], 0.5 op_sel_hi:[1,0]
	v_pk_mul_f32 v[122:123], v[64:65], 0.5 op_sel_hi:[1,0]
	v_pk_mul_f32 v[120:121], v[62:63], 0.5 op_sel_hi:[1,0]
	v_pk_mul_f32 v[118:119], v[60:61], 0.5 op_sel_hi:[1,0]
	v_pk_mul_f32 v[116:117], v[58:59], 0.5 op_sel_hi:[1,0]
	v_pk_mul_f32 v[112:113], v[48:49], 0.5 op_sel_hi:[1,0]
	v_pk_mul_f32 v[110:111], v[46:47], 0.5 op_sel_hi:[1,0]
	v_pk_mul_f32 v[108:109], v[40:41], 0.5 op_sel_hi:[1,0]
	v_pk_mul_f32 v[106:107], v[38:39], 0.5 op_sel_hi:[1,0]
	v_pk_mul_f32 v[104:105], v[56:57], 0.5 op_sel_hi:[1,0]
	v_pk_mul_f32 v[102:103], v[54:55], 0.5 op_sel_hi:[1,0]
	v_pk_mul_f32 v[100:101], v[52:53], 0.5 op_sel_hi:[1,0]
	v_pk_mul_f32 v[98:99], v[50:51], 0.5 op_sel_hi:[1,0]
	v_pk_mul_f32 v[96:97], v[32:33], 0.5 op_sel_hi:[1,0]
	v_pk_mul_f32 v[94:95], v[30:31], 0.5 op_sel_hi:[1,0]
	v_pk_mul_f32 v[92:93], v[24:25], 0.5 op_sel_hi:[1,0]
	v_pk_mul_f32 v[90:91], v[22:23], 0.5 op_sel_hi:[1,0]
	v_pk_mul_f32 v[88:89], v[44:45], 0.5 op_sel_hi:[1,0]
	v_pk_mul_f32 v[86:87], v[42:43], 0.5 op_sel_hi:[1,0]
	v_pk_mul_f32 v[84:85], v[36:37], 0.5 op_sel_hi:[1,0]
	v_pk_mul_f32 v[82:83], v[34:35], 0.5 op_sel_hi:[1,0]
	v_pk_mul_f32 v[80:81], v[16:17], 0.5 op_sel_hi:[1,0]
	v_pk_mul_f32 v[78:79], v[14:15], 0.5 op_sel_hi:[1,0]
	v_pk_mul_f32 v[76:77], v[12:13], 0.5 op_sel_hi:[1,0]
	v_pk_mul_f32 v[74:75], v[10:11], 0.5 op_sel_hi:[1,0]
	v_pk_mul_f32 v[72:73], v[28:29], 0.5 op_sel_hi:[1,0]
	v_pk_mul_f32 v[70:71], v[26:27], 0.5 op_sel_hi:[1,0]
	v_pk_mul_f32 v[68:69], v[20:21], 0.5 op_sel_hi:[1,0]
	v_pk_mul_f32 v[66:67], v[18:19], 0.5 op_sel_hi:[1,0]
	v_pk_mul_f32 v[64:65], v[8:9], 0.5 op_sel_hi:[1,0]
	v_pk_mul_f32 v[62:63], v[6:7], 0.5 op_sel_hi:[1,0]
	v_pk_mul_f32 v[60:61], v[4:5], 0.5 op_sel_hi:[1,0]
	v_pk_mul_f32 v[58:59], v[2:3], 0.5 op_sel_hi:[1,0]
	s_and_b64 vcc, exec, s[40:41]
	s_cbranch_vccz .LBB0_1522
